# RG-LRU activations: fold log2e into per-channel constants (sigmoid arg = fmamk(acc,-log2e,-log2e*b), decay exponent r*(log2e*K)); 48 VALU ops fewer per sub-block, f32 reassociation only
# baseline (speedup 1.0000x reference)
.LBB0_264:
	s_and_b32 s65, s96, 63
	s_ashr_i32 s64, s20, 6
	s_lshl_b32 s4, s65, 8
	s_lshl_b32 s5, s64, 5
	v_and_b32_e32 v93, 31, v90
	s_add_i32 s12, s5, s4
	v_or_b32_e32 v9, s12, v93
	v_add_u32_e32 v0, -2, v9
	v_cmp_gt_u32_e32 vcc, s84, v0
	v_bfe_u32 v92, v90, 5, 1
	s_lshl_b32 s20, s73, 1
	v_cndmask_b32_e32 v2, v9, v0, vcc
	v_mov_b64_e32 v[0:1], s[52:53]
	v_mad_i64_i32 v[2:3], s[4:5], v2, s85, v[0:1]
	v_lshl_add_u64 v[2:3], v[2:3], 0, s[20:21]
	v_lshlrev_b32_e32 v88, 4, v92
	v_lshl_add_u64 v[4:5], v[2:3], 0, v[88:89]
	v_add_co_u32_e64 v2, s[4:5], s86, v4
	s_waitcnt lgkmcnt(0)
	s_nop 0
	v_addc_co_u32_e64 v3, s[4:5], 0, v5, s[4:5]
	s_barrier
	global_load_dwordx4 v[10:13], v[2:3], off offset:1024
	global_load_dwordx4 v[178:181], v[2:3], off offset:1056
	global_load_dwordx4 v[194:197], v[2:3], off offset:1088
	global_load_dwordx4 v[210:213], v[2:3], off offset:1120
	global_load_dwordx4 v[226:229], v[2:3], off offset:1152
	global_load_dwordx4 v[242:245], v[2:3], off offset:1184
	v_add_u32_e32 v2, -1, v9
	v_cmp_gt_u32_e64 s[4:5], s84, v2
	v_add_u32_e32 v18, 1, v9
	s_cmpk_lt_u32 s12, 0x4000
	v_cndmask_b32_e64 v2, v9, v2, s[4:5]
	v_mad_i64_i32 v[2:3], s[6:7], v2, s85, v[0:1]
	v_lshl_add_u64 v[2:3], v[2:3], 0, s[20:21]
	v_lshl_add_u64 v[2:3], v[2:3], 0, v[88:89]
	v_add_co_u32_e64 v6, s[6:7], s86, v2
	v_lshlrev_b32_e32 v91, 8, v93
	s_nop 0
	v_addc_co_u32_e64 v7, s[6:7], 0, v3, s[6:7]
	global_load_dwordx4 v[14:17], v[6:7], off offset:1024
	global_load_dwordx4 v[182:185], v[6:7], off offset:1056
	global_load_dwordx4 v[198:201], v[6:7], off offset:1088
	global_load_dwordx4 v[214:217], v[6:7], off offset:1120
	global_load_dwordx4 v[230:233], v[6:7], off offset:1152
	global_load_dwordx4 v[246:249], v[6:7], off offset:1184
	v_mad_i64_i32 v[6:7], s[6:7], v9, s85, v[0:1]
	v_cmp_gt_u32_e64 s[6:7], s84, v18
	v_lshl_add_u64 v[6:7], v[6:7], 0, s[20:21]
	v_lshl_add_u64 v[52:53], v[6:7], 0, v[88:89]
	v_cndmask_b32_e64 v9, v9, v18, s[6:7]
	v_mad_i64_i32 v[0:1], s[8:9], v9, s85, v[0:1]
	v_add_co_u32_e64 v6, s[8:9], s86, v52
	v_lshl_add_u64 v[0:1], v[0:1], 0, s[20:21]
	s_nop 0
	v_addc_co_u32_e64 v7, s[8:9], 0, v53, s[8:9]
	global_load_dwordx4 v[18:21], v[6:7], off offset:1024
	global_load_dwordx4 v[186:189], v[6:7], off offset:1056
	global_load_dwordx4 v[202:205], v[6:7], off offset:1088
	global_load_dwordx4 v[218:221], v[6:7], off offset:1120
	global_load_dwordx4 v[234:237], v[6:7], off offset:1152
	global_load_dwordx4 v[252:255], v[6:7], off offset:1184
	v_lshl_add_u64 v[6:7], v[0:1], 0, v[88:89]
	v_add_co_u32_e64 v0, s[8:9], s86, v6
	v_lshl_add_u32 v9, v92, 5, 16
	s_nop 0
	v_addc_co_u32_e64 v1, s[8:9], 0, v7, s[8:9]
	global_load_dwordx4 v[22:25], v[0:1], off offset:1024
	global_load_dwordx4 v[190:193], v[0:1], off offset:1056
	global_load_dwordx4 v[206:209], v[0:1], off offset:1088
	global_load_dwordx4 v[222:225], v[0:1], off offset:1120
	global_load_dwordx4 v[238:241], v[0:1], off offset:1152
	global_load_dwordx4 v[168:171], v[0:1], off offset:1184
	ds_read_b128 v[26:29], v9 offset:8192
	s_waitcnt vmcnt(26)
	ds_read_b128 v[30:33], v9 offset:8704
	ds_read_b128 v[34:37], v9 offset:10240
	ds_read_b128 v[38:41], v9 offset:10256
	ds_read_b128 v[42:45], v9 offset:8208
	ds_read_b128 v[46:49], v9 offset:8720
	s_waitcnt lgkmcnt(4)
	v_mov_b32_e32 v51, v30
	v_mov_b32_e32 v30, v27
	v_mov_b32_e32 v27, v32
	v_mov_b32_e32 v50, v26
	v_lshl_add_u64 v[0:1], v[4:5], 0, s[38:39]
	v_mov_b32_e32 v26, v28
	s_cselect_b64 s[8:9], -1, 0
	v_lshl_add_u64 v[6:7], v[6:7], 0, s[38:39]
	v_or_b32_e32 v138, s73, v93
	v_and_b32_e32 v8, 0x70, v8
	v_add_u32_e32 v94, 16, v91
	s_waitcnt vmcnt(23)
	v_cndmask_b32_e32 v32, 0, v11, vcc
	v_cndmask_b32_e32 v10, 0, v10, vcc
	v_lshlrev_b32_e32 v4, 16, v10
	v_and_b32_e32 v10, 0xffff0000, v10
	v_cndmask_b32_e32 v54, 0, v12, vcc
	v_lshlrev_b32_e32 v12, 16, v32
	v_cndmask_b32_e32 v28, 0, v13, vcc
	s_waitcnt vmcnt(17)
	v_cndmask_b32_e64 v11, 0, v14, s[4:5]
	v_lshlrev_b32_e32 v5, 16, v11
	v_pk_mul_f32 v[4:5], v[50:51], v[4:5]
	v_cndmask_b32_e64 v15, 0, v15, s[4:5]
	v_and_b32_e32 v11, 0xffff0000, v11
	s_waitcnt lgkmcnt(3)
	v_add_f32_e32 v4, v34, v4
	v_pk_mul_f32 v[10:11], v[30:31], v[10:11]
	v_add_f32_e32 v30, v4, v5
	v_and_b32_e32 v5, 0xffff0000, v15
	v_and_b32_e32 v4, 0xffff0000, v32
	v_mov_b32_e32 v32, v29
	v_pk_mul_f32 v[4:5], v[32:33], v[4:5]
	v_cndmask_b32_e64 v16, 0, v16, s[4:5]
	v_add_f32_e32 v10, v35, v10
	v_add_f32_e32 v4, v37, v4
	v_add_f32_e32 v31, v10, v11
	v_add_f32_e32 v29, v4, v5
	v_lshlrev_b32_e32 v5, 16, v16
	v_lshlrev_b32_e32 v4, 16, v54
	s_waitcnt lgkmcnt(1)
	v_mov_b32_e32 v10, v42
	s_waitcnt lgkmcnt(0)
	v_mov_b32_e32 v11, v46
	v_pk_mul_f32 v[4:5], v[10:11], v[4:5]
	v_mov_b32_e32 v46, v43
	v_add_f32_e32 v4, v38, v4
	v_add_f32_e32 v32, v4, v5
	v_and_b32_e32 v5, 0xffff0000, v16
	v_and_b32_e32 v4, 0xffff0000, v54
	v_pk_mul_f32 v[4:5], v[46:47], v[4:5]
	v_cndmask_b32_e64 v17, 0, v17, s[4:5]
	v_add_f32_e32 v4, v39, v4
	v_add_f32_e32 v33, v4, v5
	v_lshlrev_b32_e32 v5, 16, v17
	v_lshlrev_b32_e32 v4, 16, v28
	v_mov_b32_e32 v10, v44
	v_mov_b32_e32 v11, v48
	v_pk_mul_f32 v[4:5], v[10:11], v[4:5]
	v_lshlrev_b32_e32 v13, 16, v15
	v_add_f32_e32 v4, v40, v4
	v_pk_mul_f32 v[12:13], v[26:27], v[12:13]
	v_add_f32_e32 v35, v4, v5
	v_and_b32_e32 v5, 0xffff0000, v17
	v_and_b32_e32 v4, 0xffff0000, v28
	v_mov_b32_e32 v48, v45
	v_add_f32_e32 v12, v36, v12
	v_pk_mul_f32 v[4:5], v[48:49], v[4:5]
	v_add_f32_e32 v34, v12, v13
	v_add_f32_e32 v4, v41, v4
	s_waitcnt vmcnt(11)
	v_cndmask_b32_e64 v36, 0, v21, s[8:9]
	v_cndmask_b32_e64 v37, 0, v20, s[8:9]
	v_cndmask_b32_e64 v38, 0, v19, s[8:9]
	v_cndmask_b32_e64 v39, 0, v18, s[8:9]
	ds_read_b128 v[10:13], v9 offset:9216
	ds_read_b128 v[14:17], v9 offset:9232
	s_waitcnt vmcnt(5)
	v_cndmask_b32_e64 v40, 0, v25, s[6:7]
	v_cndmask_b32_e64 v41, 0, v24, s[6:7]
	v_cndmask_b32_e64 v42, 0, v23, s[6:7]
	v_cndmask_b32_e64 v43, 0, v22, s[6:7]
	ds_read_b128 v[18:21], v9 offset:9728
	ds_read_b128 v[22:25], v9 offset:9744
	v_add_f32_e32 v28, v4, v5
	v_lshlrev_b32_e32 v5, 16, v43
	v_lshlrev_b32_e32 v4, 16, v39
	s_waitcnt lgkmcnt(3)
	v_mov_b32_e32 v26, v10
	s_waitcnt lgkmcnt(1)
	v_mov_b32_e32 v27, v18
	v_pk_mul_f32 v[4:5], v[26:27], v[4:5]
	v_mov_b32_e32 v18, v11
	v_add_f32_e32 v4, v30, v4
	v_add_f32_e32 v26, v4, v5
	v_and_b32_e32 v5, 0xffff0000, v43
	v_and_b32_e32 v4, 0xffff0000, v39
	v_pk_mul_f32 v[4:5], v[18:19], v[4:5]
	v_mov_b32_e32 v10, v12
	v_add_f32_e32 v4, v31, v4
	v_add_f32_e32 v18, v4, v5
	v_lshlrev_b32_e32 v5, 16, v42
	v_lshlrev_b32_e32 v4, 16, v38
	v_mov_b32_e32 v11, v20
	v_pk_mul_f32 v[4:5], v[10:11], v[4:5]
	v_mov_b32_e32 v20, v13
	v_add_f32_e32 v4, v34, v4
	v_add_f32_e32 v12, v4, v5
	v_and_b32_e32 v5, 0xffff0000, v42
	v_and_b32_e32 v4, 0xffff0000, v38
	v_pk_mul_f32 v[4:5], v[20:21], v[4:5]
	v_mov_b32_e32 v10, v14
	v_add_f32_e32 v4, v29, v4
	v_add_f32_e32 v13, v4, v5
	v_lshlrev_b32_e32 v5, 16, v41
	v_lshlrev_b32_e32 v4, 16, v37
	s_waitcnt lgkmcnt(0)
	v_mov_b32_e32 v11, v22
	v_pk_mul_f32 v[4:5], v[10:11], v[4:5]
	v_mov_b32_e32 v22, v15
	v_add_f32_e32 v4, v32, v4
	v_add_f32_e32 v14, v4, v5
	v_and_b32_e32 v5, 0xffff0000, v41
	v_and_b32_e32 v4, 0xffff0000, v37
	v_pk_mul_f32 v[4:5], v[22:23], v[4:5]
	v_mov_b32_e32 v10, v16
	v_add_f32_e32 v4, v33, v4
	v_add_f32_e32 v15, v4, v5
	v_lshlrev_b32_e32 v5, 16, v40
	v_lshlrev_b32_e32 v4, 16, v36
	v_mov_b32_e32 v11, v24
	v_pk_mul_f32 v[4:5], v[10:11], v[4:5]
	v_mov_b32_e32 v24, v17
	v_add_f32_e32 v4, v35, v4
	v_add_f32_e32 v10, v4, v5
	v_and_b32_e32 v5, 0xffff0000, v40
	v_and_b32_e32 v4, 0xffff0000, v36
	v_pk_mul_f32 v[4:5], v[24:25], v[4:5]
	v_cvt_pk_bf16_f32 v48, v26, v18
	v_cvt_pk_bf16_f32 v49, v12, v13
	v_cvt_pk_bf16_f32 v50, v14, v15
	s_nop 0
	v_add_f32_e32 v4, v28, v4
	v_add_f32_e32 v4, v4, v5
	v_cvt_pk_bf16_f32 v51, v10, v4
	v_lshl_add_u64 v[4:5], v[2:3], 0, s[38:39]
	v_lshl_add_u64 v[2:3], v[52:53], 0, s[38:39]
	ds_read_b128 v[26:29], v9 offset:10304
	ds_read_b128 v[30:33], v9 offset:10320
	s_waitcnt vmcnt(4)
	v_cndmask_b32_e32 v46, 0, v181, vcc
	v_cndmask_b32_e32 v47, 0, v180, vcc
	v_cndmask_b32_e32 v52, 0, v179, vcc
	v_cndmask_b32_e32 v53, 0, v178, vcc
	ds_read_b128 v[10:13], v9 offset:8256
	ds_read_b128 v[34:37], v9 offset:8272
	s_waitcnt vmcnt(4)
	v_cndmask_b32_e64 v54, 0, v185, s[4:5]
	v_cndmask_b32_e64 v55, 0, v184, s[4:5]
	v_cndmask_b32_e64 v56, 0, v183, s[4:5]
	v_cndmask_b32_e64 v57, 0, v182, s[4:5]
	ds_read_b128 v[14:17], v9 offset:8768
	ds_read_b128 v[38:41], v9 offset:8784
	v_lshlrev_b32_e32 v43, 16, v57
	v_lshlrev_b32_e32 v42, 16, v53
	s_waitcnt lgkmcnt(3)
	v_mov_b32_e32 v44, v10
	s_waitcnt lgkmcnt(1)
	v_mov_b32_e32 v45, v14
	v_pk_mul_f32 v[42:43], v[44:45], v[42:43]
	v_mov_b32_e32 v14, v11
	v_add_f32_e32 v10, v26, v42
	v_add_f32_e32 v44, v10, v43
	v_and_b32_e32 v43, 0xffff0000, v57
	v_and_b32_e32 v42, 0xffff0000, v53
	v_pk_mul_f32 v[10:11], v[14:15], v[42:43]
	v_mov_b32_e32 v14, v12
	v_add_f32_e32 v10, v27, v10
	v_add_f32_e32 v42, v10, v11
	v_lshlrev_b32_e32 v11, 16, v56
	v_lshlrev_b32_e32 v10, 16, v52
	v_mov_b32_e32 v15, v16
	v_pk_mul_f32 v[10:11], v[14:15], v[10:11]
	v_mov_b32_e32 v16, v13
	v_add_f32_e32 v10, v28, v10
	v_add_f32_e32 v43, v10, v11
	v_and_b32_e32 v11, 0xffff0000, v56
	v_and_b32_e32 v10, 0xffff0000, v52
	v_pk_mul_f32 v[10:11], v[16:17], v[10:11]
	v_mov_b32_e32 v12, v34
	v_add_f32_e32 v10, v29, v10
	v_add_f32_e32 v45, v10, v11
	v_lshlrev_b32_e32 v11, 16, v55
	v_lshlrev_b32_e32 v10, 16, v47
	s_waitcnt lgkmcnt(0)
	v_mov_b32_e32 v13, v38
	v_pk_mul_f32 v[10:11], v[12:13], v[10:11]
	v_mov_b32_e32 v38, v35
	v_add_f32_e32 v10, v30, v10
	v_add_f32_e32 v30, v10, v11
	v_and_b32_e32 v11, 0xffff0000, v55
	v_and_b32_e32 v10, 0xffff0000, v47
	v_pk_mul_f32 v[10:11], v[38:39], v[10:11]
	v_mov_b32_e32 v12, v36
	v_add_f32_e32 v10, v31, v10
	v_add_f32_e32 v31, v10, v11
	v_lshlrev_b32_e32 v11, 16, v54
	v_lshlrev_b32_e32 v10, 16, v46
	v_mov_b32_e32 v13, v40
	v_pk_mul_f32 v[10:11], v[12:13], v[10:11]
	v_mov_b32_e32 v40, v37
	v_add_f32_e32 v10, v32, v10
	v_add_f32_e32 v32, v10, v11
	v_and_b32_e32 v11, 0xffff0000, v54
	v_and_b32_e32 v10, 0xffff0000, v46
	v_pk_mul_f32 v[10:11], v[40:41], v[10:11]
	s_waitcnt vmcnt(4)
	v_cndmask_b32_e64 v34, 0, v189, s[8:9]
	v_add_f32_e32 v10, v33, v10
	v_add_f32_e32 v33, v10, v11
	v_cndmask_b32_e64 v35, 0, v188, s[8:9]
	v_cndmask_b32_e64 v36, 0, v187, s[8:9]
	v_cndmask_b32_e64 v37, 0, v186, s[8:9]
	ds_read_b128 v[10:13], v9 offset:9280
	ds_read_b128 v[14:17], v9 offset:9296
	v_cndmask_b32_e64 v38, 0, v193, s[6:7]
	v_cndmask_b32_e64 v39, 0, v192, s[6:7]
	v_cndmask_b32_e64 v40, 0, v191, s[6:7]
	v_cndmask_b32_e64 v41, 0, v190, s[6:7]
	ds_read_b128 v[18:21], v9 offset:9792
	ds_read_b128 v[22:25], v9 offset:9808
	v_lshlrev_b32_e32 v27, 16, v41
	v_lshlrev_b32_e32 v26, 16, v37
	s_waitcnt lgkmcnt(3)
	v_mov_b32_e32 v28, v10
	s_waitcnt lgkmcnt(1)
	v_mov_b32_e32 v29, v18
	v_pk_mul_f32 v[26:27], v[28:29], v[26:27]
	v_mov_b32_e32 v18, v11
	v_add_f32_e32 v10, v44, v26
	v_add_f32_e32 v28, v10, v27
	v_and_b32_e32 v27, 0xffff0000, v41
	v_and_b32_e32 v26, 0xffff0000, v37
	v_pk_mul_f32 v[10:11], v[18:19], v[26:27]
	v_mov_b32_e32 v18, v12
	v_add_f32_e32 v10, v42, v10
	v_add_f32_e32 v26, v10, v11
	v_lshlrev_b32_e32 v11, 16, v40
	v_lshlrev_b32_e32 v10, 16, v36
	v_mov_b32_e32 v19, v20
	v_pk_mul_f32 v[10:11], v[18:19], v[10:11]
	v_mov_b32_e32 v20, v13
	v_add_f32_e32 v10, v43, v10
	v_add_f32_e32 v18, v10, v11
	v_and_b32_e32 v11, 0xffff0000, v40
	v_and_b32_e32 v10, 0xffff0000, v36
	v_pk_mul_f32 v[10:11], v[20:21], v[10:11]
	v_mov_b32_e32 v12, v14
	v_add_f32_e32 v10, v45, v10
	v_add_f32_e32 v19, v10, v11
	v_lshlrev_b32_e32 v11, 16, v39
	v_lshlrev_b32_e32 v10, 16, v35
	s_waitcnt lgkmcnt(0)
	v_mov_b32_e32 v13, v22
	v_pk_mul_f32 v[10:11], v[12:13], v[10:11]
	v_mov_b32_e32 v22, v15
	v_add_f32_e32 v10, v30, v10
	v_add_f32_e32 v14, v10, v11
	v_and_b32_e32 v11, 0xffff0000, v39
	v_and_b32_e32 v10, 0xffff0000, v35
	v_pk_mul_f32 v[10:11], v[22:23], v[10:11]
	v_mov_b32_e32 v12, v16
	v_add_f32_e32 v10, v31, v10
	v_add_f32_e32 v15, v10, v11
	v_lshlrev_b32_e32 v11, 16, v38
	v_lshlrev_b32_e32 v10, 16, v34
	v_mov_b32_e32 v13, v24
	v_pk_mul_f32 v[10:11], v[12:13], v[10:11]
	v_mov_b32_e32 v24, v17
	v_add_f32_e32 v10, v32, v10
	v_add_f32_e32 v12, v10, v11
	v_and_b32_e32 v11, 0xffff0000, v38
	v_and_b32_e32 v10, 0xffff0000, v34
	v_pk_mul_f32 v[10:11], v[24:25], v[10:11]
	v_cvt_pk_bf16_f32 v52, v28, v26
	v_cvt_pk_bf16_f32 v53, v18, v19
	v_cvt_pk_bf16_f32 v54, v14, v15
	s_nop 0
	v_add_f32_e32 v10, v33, v10
	v_add_f32_e32 v10, v10, v11
	v_cvt_pk_bf16_f32 v55, v12, v10
	global_load_dwordx4 v[178:181], v[0:1], off offset:192
	global_load_dwordx4 v[182:185], v[4:5], off offset:192
	global_load_dwordx4 v[186:189], v[2:3], off offset:192
	global_load_dwordx4 v[190:193], v[6:7], off offset:192
	ds_read_b128 v[26:29], v9 offset:10368
	ds_read_b128 v[30:33], v9 offset:10384
	s_waitcnt vmcnt(7)
	v_cndmask_b32_e32 v46, 0, v197, vcc
	v_cndmask_b32_e32 v47, 0, v196, vcc
	v_cndmask_b32_e32 v56, 0, v195, vcc
	v_cndmask_b32_e32 v57, 0, v194, vcc
	ds_read_b128 v[10:13], v9 offset:8320
	ds_read_b128 v[34:37], v9 offset:8336
	s_waitcnt vmcnt(7)
	v_cndmask_b32_e64 v58, 0, v201, s[4:5]
	v_cndmask_b32_e64 v59, 0, v200, s[4:5]
	v_cndmask_b32_e64 v60, 0, v199, s[4:5]
	v_cndmask_b32_e64 v61, 0, v198, s[4:5]
	ds_read_b128 v[14:17], v9 offset:8832
	ds_read_b128 v[38:41], v9 offset:8848
	v_lshlrev_b32_e32 v43, 16, v61
	v_lshlrev_b32_e32 v42, 16, v57
	s_waitcnt lgkmcnt(3)
	v_mov_b32_e32 v44, v10
	s_waitcnt lgkmcnt(1)
	v_mov_b32_e32 v45, v14
	v_pk_mul_f32 v[42:43], v[44:45], v[42:43]
	v_mov_b32_e32 v14, v11
	v_add_f32_e32 v10, v26, v42
	v_add_f32_e32 v44, v10, v43
	v_and_b32_e32 v43, 0xffff0000, v61
	v_and_b32_e32 v42, 0xffff0000, v57
	v_pk_mul_f32 v[10:11], v[14:15], v[42:43]
	v_mov_b32_e32 v14, v12
	v_add_f32_e32 v10, v27, v10
	v_add_f32_e32 v42, v10, v11
	v_lshlrev_b32_e32 v11, 16, v60
	v_lshlrev_b32_e32 v10, 16, v56
	v_mov_b32_e32 v15, v16
	v_pk_mul_f32 v[10:11], v[14:15], v[10:11]
	v_mov_b32_e32 v16, v13
	v_add_f32_e32 v10, v28, v10
	v_add_f32_e32 v43, v10, v11
	v_and_b32_e32 v11, 0xffff0000, v60
	v_and_b32_e32 v10, 0xffff0000, v56
	v_pk_mul_f32 v[10:11], v[16:17], v[10:11]
	v_mov_b32_e32 v12, v34
	v_add_f32_e32 v10, v29, v10
	v_add_f32_e32 v45, v10, v11
	v_lshlrev_b32_e32 v11, 16, v59
	v_lshlrev_b32_e32 v10, 16, v47
	s_waitcnt lgkmcnt(0)
	v_mov_b32_e32 v13, v38
	v_pk_mul_f32 v[10:11], v[12:13], v[10:11]
	v_mov_b32_e32 v38, v35
	v_add_f32_e32 v10, v30, v10
	v_add_f32_e32 v30, v10, v11
	v_and_b32_e32 v11, 0xffff0000, v59
	v_and_b32_e32 v10, 0xffff0000, v47
	v_pk_mul_f32 v[10:11], v[38:39], v[10:11]
	v_mov_b32_e32 v12, v36
	v_add_f32_e32 v10, v31, v10
	v_add_f32_e32 v31, v10, v11
	v_lshlrev_b32_e32 v11, 16, v58
	v_lshlrev_b32_e32 v10, 16, v46
	v_mov_b32_e32 v13, v40
	v_pk_mul_f32 v[10:11], v[12:13], v[10:11]
	v_mov_b32_e32 v40, v37
	v_add_f32_e32 v10, v32, v10
	v_add_f32_e32 v32, v10, v11
	v_and_b32_e32 v11, 0xffff0000, v58
	v_and_b32_e32 v10, 0xffff0000, v46
	v_pk_mul_f32 v[10:11], v[40:41], v[10:11]
	s_waitcnt vmcnt(7)
	v_cndmask_b32_e64 v34, 0, v205, s[8:9]
	v_add_f32_e32 v10, v33, v10
	v_add_f32_e32 v33, v10, v11
	v_cndmask_b32_e64 v35, 0, v204, s[8:9]
	v_cndmask_b32_e64 v36, 0, v203, s[8:9]
	v_cndmask_b32_e64 v37, 0, v202, s[8:9]
	ds_read_b128 v[10:13], v9 offset:9344
	ds_read_b128 v[14:17], v9 offset:9360
	s_waitcnt vmcnt(7)
	v_cndmask_b32_e64 v38, 0, v209, s[6:7]
	v_cndmask_b32_e64 v39, 0, v208, s[6:7]
	v_cndmask_b32_e64 v40, 0, v207, s[6:7]
	v_cndmask_b32_e64 v41, 0, v206, s[6:7]
	ds_read_b128 v[18:21], v9 offset:9856
	ds_read_b128 v[22:25], v9 offset:9872
	v_lshlrev_b32_e32 v27, 16, v41
	v_lshlrev_b32_e32 v26, 16, v37
	s_waitcnt lgkmcnt(3)
	v_mov_b32_e32 v28, v10
	s_waitcnt lgkmcnt(1)
	v_mov_b32_e32 v29, v18
	v_pk_mul_f32 v[26:27], v[28:29], v[26:27]
	v_mov_b32_e32 v18, v11
	v_add_f32_e32 v10, v44, v26
	v_add_f32_e32 v28, v10, v27
	v_and_b32_e32 v27, 0xffff0000, v41
	v_and_b32_e32 v26, 0xffff0000, v37
	v_pk_mul_f32 v[10:11], v[18:19], v[26:27]
	v_mov_b32_e32 v18, v12
	v_add_f32_e32 v10, v42, v10
	v_add_f32_e32 v26, v10, v11
	v_lshlrev_b32_e32 v11, 16, v40
	v_lshlrev_b32_e32 v10, 16, v36
	v_mov_b32_e32 v19, v20
	v_pk_mul_f32 v[10:11], v[18:19], v[10:11]
	v_mov_b32_e32 v20, v13
	v_add_f32_e32 v10, v43, v10
	v_add_f32_e32 v18, v10, v11
	v_and_b32_e32 v11, 0xffff0000, v40
	v_and_b32_e32 v10, 0xffff0000, v36
	v_pk_mul_f32 v[10:11], v[20:21], v[10:11]
	v_mov_b32_e32 v12, v14
	v_add_f32_e32 v10, v45, v10
	v_add_f32_e32 v19, v10, v11
	v_lshlrev_b32_e32 v11, 16, v39
	v_lshlrev_b32_e32 v10, 16, v35
	s_waitcnt lgkmcnt(0)
	v_mov_b32_e32 v13, v22
	v_pk_mul_f32 v[10:11], v[12:13], v[10:11]
	v_mov_b32_e32 v22, v15
	v_add_f32_e32 v10, v30, v10
	v_add_f32_e32 v14, v10, v11
	v_and_b32_e32 v11, 0xffff0000, v39
	v_and_b32_e32 v10, 0xffff0000, v35
	v_pk_mul_f32 v[10:11], v[22:23], v[10:11]
	v_mov_b32_e32 v12, v16
	v_add_f32_e32 v10, v31, v10
	v_add_f32_e32 v15, v10, v11
	v_lshlrev_b32_e32 v11, 16, v38
	v_lshlrev_b32_e32 v10, 16, v34
	v_mov_b32_e32 v13, v24
	v_pk_mul_f32 v[10:11], v[12:13], v[10:11]
	v_mov_b32_e32 v24, v17
	v_add_f32_e32 v10, v32, v10
	v_add_f32_e32 v12, v10, v11
	v_and_b32_e32 v11, 0xffff0000, v38
	v_and_b32_e32 v10, 0xffff0000, v34
	v_pk_mul_f32 v[10:11], v[24:25], v[10:11]
	v_cvt_pk_bf16_f32 v56, v28, v26
	v_cvt_pk_bf16_f32 v57, v18, v19
	v_cvt_pk_bf16_f32 v58, v14, v15
	s_nop 0
	v_add_f32_e32 v10, v33, v10
	v_add_f32_e32 v10, v10, v11
	v_cvt_pk_bf16_f32 v59, v12, v10
	global_load_dwordx4 v[194:197], v[0:1], off offset:224
	global_load_dwordx4 v[198:201], v[4:5], off offset:224
	global_load_dwordx4 v[202:205], v[2:3], off offset:224
	global_load_dwordx4 v[206:209], v[6:7], off offset:224
	ds_read_b128 v[26:29], v9 offset:10432
	ds_read_b128 v[30:33], v9 offset:10448
	s_waitcnt vmcnt(10)
	v_cndmask_b32_e32 v46, 0, v213, vcc
	v_cndmask_b32_e32 v47, 0, v212, vcc
	v_cndmask_b32_e32 v60, 0, v211, vcc
	v_cndmask_b32_e32 v61, 0, v210, vcc
	ds_read_b128 v[10:13], v9 offset:8384
	ds_read_b128 v[34:37], v9 offset:8400
	s_waitcnt vmcnt(10)
	v_cndmask_b32_e64 v62, 0, v217, s[4:5]
	v_cndmask_b32_e64 v63, 0, v216, s[4:5]
	v_cndmask_b32_e64 v64, 0, v215, s[4:5]
	v_cndmask_b32_e64 v65, 0, v214, s[4:5]
	ds_read_b128 v[14:17], v9 offset:8896
	ds_read_b128 v[38:41], v9 offset:8912
	v_lshlrev_b32_e32 v43, 16, v65
	v_lshlrev_b32_e32 v42, 16, v61
	s_waitcnt lgkmcnt(3)
	v_mov_b32_e32 v44, v10
	s_waitcnt lgkmcnt(1)
	v_mov_b32_e32 v45, v14
	v_pk_mul_f32 v[42:43], v[44:45], v[42:43]
	v_mov_b32_e32 v14, v11
	v_add_f32_e32 v10, v26, v42
	v_add_f32_e32 v44, v10, v43
	v_and_b32_e32 v43, 0xffff0000, v65
	v_and_b32_e32 v42, 0xffff0000, v61
	v_pk_mul_f32 v[10:11], v[14:15], v[42:43]
	v_mov_b32_e32 v14, v12
	v_add_f32_e32 v10, v27, v10
	v_add_f32_e32 v42, v10, v11
	v_lshlrev_b32_e32 v11, 16, v64
	v_lshlrev_b32_e32 v10, 16, v60
	v_mov_b32_e32 v15, v16
	v_pk_mul_f32 v[10:11], v[14:15], v[10:11]
	v_mov_b32_e32 v16, v13
	v_add_f32_e32 v10, v28, v10
	v_add_f32_e32 v43, v10, v11
	v_and_b32_e32 v11, 0xffff0000, v64
	v_and_b32_e32 v10, 0xffff0000, v60
	v_pk_mul_f32 v[10:11], v[16:17], v[10:11]
	v_mov_b32_e32 v12, v34
	v_add_f32_e32 v10, v29, v10
	v_add_f32_e32 v45, v10, v11
	v_lshlrev_b32_e32 v11, 16, v63
	v_lshlrev_b32_e32 v10, 16, v47
	s_waitcnt lgkmcnt(0)
	v_mov_b32_e32 v13, v38
	v_pk_mul_f32 v[10:11], v[12:13], v[10:11]
	v_mov_b32_e32 v38, v35
	v_add_f32_e32 v10, v30, v10
	v_add_f32_e32 v30, v10, v11
	v_and_b32_e32 v11, 0xffff0000, v63
	v_and_b32_e32 v10, 0xffff0000, v47
	v_pk_mul_f32 v[10:11], v[38:39], v[10:11]
	v_mov_b32_e32 v12, v36
	v_add_f32_e32 v10, v31, v10
	v_add_f32_e32 v31, v10, v11
	v_lshlrev_b32_e32 v11, 16, v62
	v_lshlrev_b32_e32 v10, 16, v46
	v_mov_b32_e32 v13, v40
	v_pk_mul_f32 v[10:11], v[12:13], v[10:11]
	v_mov_b32_e32 v40, v37
	v_add_f32_e32 v10, v32, v10
	v_add_f32_e32 v32, v10, v11
	v_and_b32_e32 v11, 0xffff0000, v62
	v_and_b32_e32 v10, 0xffff0000, v46
	v_pk_mul_f32 v[10:11], v[40:41], v[10:11]
	s_waitcnt vmcnt(10)
	v_cndmask_b32_e64 v34, 0, v221, s[8:9]
	v_add_f32_e32 v10, v33, v10
	v_add_f32_e32 v33, v10, v11
	v_cndmask_b32_e64 v35, 0, v220, s[8:9]
	v_cndmask_b32_e64 v36, 0, v219, s[8:9]
	v_cndmask_b32_e64 v37, 0, v218, s[8:9]
	ds_read_b128 v[10:13], v9 offset:9408
	ds_read_b128 v[14:17], v9 offset:9424
	s_waitcnt vmcnt(10)
	v_cndmask_b32_e64 v38, 0, v225, s[6:7]
	v_cndmask_b32_e64 v39, 0, v224, s[6:7]
	v_cndmask_b32_e64 v40, 0, v223, s[6:7]
	v_cndmask_b32_e64 v41, 0, v222, s[6:7]
	ds_read_b128 v[18:21], v9 offset:9920
	ds_read_b128 v[22:25], v9 offset:9936
	v_lshlrev_b32_e32 v27, 16, v41
	v_lshlrev_b32_e32 v26, 16, v37
	s_waitcnt lgkmcnt(3)
	v_mov_b32_e32 v28, v10
	s_waitcnt lgkmcnt(1)
	v_mov_b32_e32 v29, v18
	v_pk_mul_f32 v[26:27], v[28:29], v[26:27]
	v_mov_b32_e32 v18, v11
	v_add_f32_e32 v10, v44, v26
	v_add_f32_e32 v28, v10, v27
	v_and_b32_e32 v27, 0xffff0000, v41
	v_and_b32_e32 v26, 0xffff0000, v37
	v_pk_mul_f32 v[10:11], v[18:19], v[26:27]
	v_mov_b32_e32 v18, v12
	v_add_f32_e32 v10, v42, v10
	v_add_f32_e32 v26, v10, v11
	v_lshlrev_b32_e32 v11, 16, v40
	v_lshlrev_b32_e32 v10, 16, v36
	v_mov_b32_e32 v19, v20
	v_pk_mul_f32 v[10:11], v[18:19], v[10:11]
	v_mov_b32_e32 v20, v13
	v_add_f32_e32 v10, v43, v10
	v_add_f32_e32 v18, v10, v11
	v_and_b32_e32 v11, 0xffff0000, v40
	v_and_b32_e32 v10, 0xffff0000, v36
	v_pk_mul_f32 v[10:11], v[20:21], v[10:11]
	v_mov_b32_e32 v12, v14
	v_add_f32_e32 v10, v45, v10
	v_add_f32_e32 v19, v10, v11
	v_lshlrev_b32_e32 v11, 16, v39
	v_lshlrev_b32_e32 v10, 16, v35
	s_waitcnt lgkmcnt(0)
	v_mov_b32_e32 v13, v22
	v_pk_mul_f32 v[10:11], v[12:13], v[10:11]
	v_mov_b32_e32 v22, v15
	v_add_f32_e32 v10, v30, v10
	v_add_f32_e32 v14, v10, v11
	v_and_b32_e32 v11, 0xffff0000, v39
	v_and_b32_e32 v10, 0xffff0000, v35
	v_pk_mul_f32 v[10:11], v[22:23], v[10:11]
	v_mov_b32_e32 v12, v16
	v_add_f32_e32 v10, v31, v10
	v_add_f32_e32 v15, v10, v11
	v_lshlrev_b32_e32 v11, 16, v38
	v_lshlrev_b32_e32 v10, 16, v34
	v_mov_b32_e32 v13, v24
	v_pk_mul_f32 v[10:11], v[12:13], v[10:11]
	v_mov_b32_e32 v24, v17
	v_add_f32_e32 v10, v32, v10
	v_add_f32_e32 v12, v10, v11
	v_and_b32_e32 v11, 0xffff0000, v38
	v_and_b32_e32 v10, 0xffff0000, v34
	v_pk_mul_f32 v[10:11], v[24:25], v[10:11]
	v_cvt_pk_bf16_f32 v60, v28, v26
	v_cvt_pk_bf16_f32 v61, v18, v19
	v_cvt_pk_bf16_f32 v62, v14, v15
	s_nop 0
	v_add_f32_e32 v10, v33, v10
	v_add_f32_e32 v10, v10, v11
	v_cvt_pk_bf16_f32 v63, v12, v10
	ds_read_b128 v[26:29], v9 offset:10496
	ds_read_b128 v[30:33], v9 offset:10512
	s_waitcnt vmcnt(9)
	v_cndmask_b32_e32 v46, 0, v229, vcc
	v_cndmask_b32_e32 v47, 0, v228, vcc
	v_cndmask_b32_e32 v64, 0, v227, vcc
	v_cndmask_b32_e32 v65, 0, v226, vcc
	ds_read_b128 v[10:13], v9 offset:8448
	ds_read_b128 v[34:37], v9 offset:8464
	s_waitcnt vmcnt(9)
	v_cndmask_b32_e64 v66, 0, v233, s[4:5]
	v_cndmask_b32_e64 v67, 0, v232, s[4:5]
	v_cndmask_b32_e64 v68, 0, v231, s[4:5]
	v_cndmask_b32_e64 v69, 0, v230, s[4:5]
	ds_read_b128 v[14:17], v9 offset:8960
	ds_read_b128 v[38:41], v9 offset:8976
	v_lshlrev_b32_e32 v43, 16, v69
	v_lshlrev_b32_e32 v42, 16, v65
	s_waitcnt lgkmcnt(3)
	v_mov_b32_e32 v44, v10
	s_waitcnt lgkmcnt(1)
	v_mov_b32_e32 v45, v14
	v_pk_mul_f32 v[42:43], v[44:45], v[42:43]
	v_mov_b32_e32 v14, v11
	v_add_f32_e32 v10, v26, v42
	v_add_f32_e32 v44, v10, v43
	v_and_b32_e32 v43, 0xffff0000, v69
	v_and_b32_e32 v42, 0xffff0000, v65
	v_pk_mul_f32 v[10:11], v[14:15], v[42:43]
	v_mov_b32_e32 v14, v12
	v_add_f32_e32 v10, v27, v10
	v_add_f32_e32 v42, v10, v11
	v_lshlrev_b32_e32 v11, 16, v68
	v_lshlrev_b32_e32 v10, 16, v64
	v_mov_b32_e32 v15, v16
	v_pk_mul_f32 v[10:11], v[14:15], v[10:11]
	v_mov_b32_e32 v16, v13
	v_add_f32_e32 v10, v28, v10
	v_add_f32_e32 v43, v10, v11
	v_and_b32_e32 v11, 0xffff0000, v68
	v_and_b32_e32 v10, 0xffff0000, v64
	v_pk_mul_f32 v[10:11], v[16:17], v[10:11]
	v_mov_b32_e32 v12, v34
	v_add_f32_e32 v10, v29, v10
	v_add_f32_e32 v45, v10, v11
	v_lshlrev_b32_e32 v11, 16, v67
	v_lshlrev_b32_e32 v10, 16, v47
	s_waitcnt lgkmcnt(0)
	v_mov_b32_e32 v13, v38
	v_pk_mul_f32 v[10:11], v[12:13], v[10:11]
	v_mov_b32_e32 v38, v35
	v_add_f32_e32 v10, v30, v10
	v_add_f32_e32 v30, v10, v11
	v_and_b32_e32 v11, 0xffff0000, v67
	v_and_b32_e32 v10, 0xffff0000, v47
	v_pk_mul_f32 v[10:11], v[38:39], v[10:11]
	v_mov_b32_e32 v12, v36
	v_add_f32_e32 v10, v31, v10
	v_add_f32_e32 v31, v10, v11
	v_lshlrev_b32_e32 v11, 16, v66
	v_lshlrev_b32_e32 v10, 16, v46
	v_mov_b32_e32 v13, v40
	v_pk_mul_f32 v[10:11], v[12:13], v[10:11]
	v_mov_b32_e32 v40, v37
	v_add_f32_e32 v10, v32, v10
	v_add_f32_e32 v32, v10, v11
	v_and_b32_e32 v11, 0xffff0000, v66
	v_and_b32_e32 v10, 0xffff0000, v46
	v_pk_mul_f32 v[10:11], v[40:41], v[10:11]
	s_waitcnt vmcnt(9)
	v_cndmask_b32_e64 v34, 0, v237, s[8:9]
	v_add_f32_e32 v10, v33, v10
	v_add_f32_e32 v33, v10, v11
	v_cndmask_b32_e64 v35, 0, v236, s[8:9]
	v_cndmask_b32_e64 v36, 0, v235, s[8:9]
	v_cndmask_b32_e64 v37, 0, v234, s[8:9]
	ds_read_b128 v[10:13], v9 offset:9472
	ds_read_b128 v[14:17], v9 offset:9488
	s_waitcnt vmcnt(9)
	v_cndmask_b32_e64 v38, 0, v241, s[6:7]
	v_cndmask_b32_e64 v39, 0, v240, s[6:7]
	v_cndmask_b32_e64 v40, 0, v239, s[6:7]
	v_cndmask_b32_e64 v41, 0, v238, s[6:7]
	ds_read_b128 v[18:21], v9 offset:9984
	ds_read_b128 v[22:25], v9 offset:10000
	v_lshlrev_b32_e32 v27, 16, v41
	v_lshlrev_b32_e32 v26, 16, v37
	s_waitcnt lgkmcnt(3)
	v_mov_b32_e32 v28, v10
	s_waitcnt lgkmcnt(1)
	v_mov_b32_e32 v29, v18
	v_pk_mul_f32 v[26:27], v[28:29], v[26:27]
	v_mov_b32_e32 v18, v11
	v_add_f32_e32 v10, v44, v26
	v_add_f32_e32 v28, v10, v27
	v_and_b32_e32 v27, 0xffff0000, v41
	v_and_b32_e32 v26, 0xffff0000, v37
	v_pk_mul_f32 v[10:11], v[18:19], v[26:27]
	v_mov_b32_e32 v18, v12
	v_add_f32_e32 v10, v42, v10
	v_add_f32_e32 v26, v10, v11
	v_lshlrev_b32_e32 v11, 16, v40
	v_lshlrev_b32_e32 v10, 16, v36
	v_mov_b32_e32 v19, v20
	v_pk_mul_f32 v[10:11], v[18:19], v[10:11]
	v_mov_b32_e32 v20, v13
	v_add_f32_e32 v10, v43, v10
	v_add_f32_e32 v18, v10, v11
	v_and_b32_e32 v11, 0xffff0000, v40
	v_and_b32_e32 v10, 0xffff0000, v36
	v_pk_mul_f32 v[10:11], v[20:21], v[10:11]
	v_mov_b32_e32 v12, v14
	v_add_f32_e32 v10, v45, v10
	v_add_f32_e32 v19, v10, v11
	v_lshlrev_b32_e32 v11, 16, v39
	v_lshlrev_b32_e32 v10, 16, v35
	s_waitcnt lgkmcnt(0)
	v_mov_b32_e32 v13, v22
	v_pk_mul_f32 v[10:11], v[12:13], v[10:11]
	v_mov_b32_e32 v22, v15
	v_add_f32_e32 v10, v30, v10
	v_add_f32_e32 v14, v10, v11
	v_and_b32_e32 v11, 0xffff0000, v39
	v_and_b32_e32 v10, 0xffff0000, v35
	v_pk_mul_f32 v[10:11], v[22:23], v[10:11]
	v_mov_b32_e32 v12, v16
	v_add_f32_e32 v10, v31, v10
	v_add_f32_e32 v15, v10, v11
	v_lshlrev_b32_e32 v11, 16, v38
	v_lshlrev_b32_e32 v10, 16, v34
	v_mov_b32_e32 v13, v24
	v_pk_mul_f32 v[10:11], v[12:13], v[10:11]
	v_mov_b32_e32 v24, v17
	v_add_f32_e32 v10, v32, v10
	v_add_f32_e32 v12, v10, v11
	v_and_b32_e32 v11, 0xffff0000, v38
	v_and_b32_e32 v10, 0xffff0000, v34
	v_pk_mul_f32 v[10:11], v[24:25], v[10:11]
	v_cvt_pk_bf16_f32 v64, v28, v26
	v_cvt_pk_bf16_f32 v65, v18, v19
	v_cvt_pk_bf16_f32 v66, v14, v15
	s_nop 0
	v_add_f32_e32 v10, v33, v10
	v_add_f32_e32 v10, v10, v11
	v_cvt_pk_bf16_f32 v67, v12, v10
	ds_read_b128 v[26:29], v9 offset:10560
	ds_read_b128 v[30:33], v9 offset:10576
	s_waitcnt vmcnt(8)
	v_cndmask_b32_e32 v46, 0, v245, vcc
	v_cndmask_b32_e32 v47, 0, v244, vcc
	v_cndmask_b32_e32 v68, 0, v243, vcc
	v_cndmask_b32_e32 v69, 0, v242, vcc
	ds_read_b128 v[10:13], v9 offset:8512
	ds_read_b128 v[34:37], v9 offset:8528
	s_waitcnt vmcnt(8)
	v_cndmask_b32_e64 v70, 0, v249, s[4:5]
	v_cndmask_b32_e64 v71, 0, v248, s[4:5]
	v_cndmask_b32_e64 v72, 0, v247, s[4:5]
	v_cndmask_b32_e64 v73, 0, v246, s[4:5]
	ds_read_b128 v[14:17], v9 offset:9024
	ds_read_b128 v[38:41], v9 offset:9040
	v_lshlrev_b32_e32 v43, 16, v73
	v_lshlrev_b32_e32 v42, 16, v69
	s_waitcnt lgkmcnt(3)
	v_mov_b32_e32 v44, v10
	s_waitcnt lgkmcnt(1)
	v_mov_b32_e32 v45, v14
	v_pk_mul_f32 v[42:43], v[44:45], v[42:43]
	v_mov_b32_e32 v14, v11
	v_add_f32_e32 v10, v26, v42
	v_add_f32_e32 v44, v10, v43
	v_and_b32_e32 v43, 0xffff0000, v73
	v_and_b32_e32 v42, 0xffff0000, v69
	v_pk_mul_f32 v[10:11], v[14:15], v[42:43]
	v_mov_b32_e32 v14, v12
	v_add_f32_e32 v10, v27, v10
	v_add_f32_e32 v42, v10, v11
	v_lshlrev_b32_e32 v11, 16, v72
	v_lshlrev_b32_e32 v10, 16, v68
	v_mov_b32_e32 v15, v16
	v_pk_mul_f32 v[10:11], v[14:15], v[10:11]
	v_mov_b32_e32 v16, v13
	v_add_f32_e32 v10, v28, v10
	v_add_f32_e32 v43, v10, v11
	v_and_b32_e32 v11, 0xffff0000, v72
	v_and_b32_e32 v10, 0xffff0000, v68
	v_pk_mul_f32 v[10:11], v[16:17], v[10:11]
	v_mov_b32_e32 v12, v34
	v_add_f32_e32 v10, v29, v10
	v_add_f32_e32 v45, v10, v11
	v_lshlrev_b32_e32 v11, 16, v71
	v_lshlrev_b32_e32 v10, 16, v47
	s_waitcnt lgkmcnt(0)
	v_mov_b32_e32 v13, v38
	v_pk_mul_f32 v[10:11], v[12:13], v[10:11]
	v_mov_b32_e32 v38, v35
	v_add_f32_e32 v10, v30, v10
	v_add_f32_e32 v30, v10, v11
	v_and_b32_e32 v11, 0xffff0000, v71
	v_and_b32_e32 v10, 0xffff0000, v47
	v_pk_mul_f32 v[10:11], v[38:39], v[10:11]
	v_mov_b32_e32 v12, v36
	v_add_f32_e32 v10, v31, v10
	v_add_f32_e32 v31, v10, v11
	v_lshlrev_b32_e32 v11, 16, v70
	v_lshlrev_b32_e32 v10, 16, v46
	v_mov_b32_e32 v13, v40
	v_pk_mul_f32 v[10:11], v[12:13], v[10:11]
	v_mov_b32_e32 v40, v37
	v_add_f32_e32 v10, v32, v10
	v_add_f32_e32 v32, v10, v11
	v_and_b32_e32 v11, 0xffff0000, v70
	v_and_b32_e32 v10, 0xffff0000, v46
	v_pk_mul_f32 v[10:11], v[40:41], v[10:11]
	s_waitcnt vmcnt(8)
	v_cndmask_b32_e64 v34, 0, v255, s[8:9]
	v_add_f32_e32 v10, v33, v10
	v_add_f32_e32 v33, v10, v11
	v_cndmask_b32_e64 v35, 0, v254, s[8:9]
	v_cndmask_b32_e64 v36, 0, v253, s[8:9]
	v_cndmask_b32_e64 v37, 0, v252, s[8:9]
	ds_read_b128 v[10:13], v9 offset:9536
	ds_read_b128 v[14:17], v9 offset:9552
	s_waitcnt vmcnt(8)
	v_cndmask_b32_e64 v38, 0, v171, s[6:7]
	v_cndmask_b32_e64 v39, 0, v170, s[6:7]
	v_cndmask_b32_e64 v40, 0, v169, s[6:7]
	v_cndmask_b32_e64 v41, 0, v168, s[6:7]
	ds_read_b128 v[18:21], v9 offset:10048
	ds_read_b128 v[22:25], v9 offset:10064
	v_lshlrev_b32_e32 v27, 16, v41
	v_lshlrev_b32_e32 v26, 16, v37
	s_waitcnt lgkmcnt(3)
	v_mov_b32_e32 v28, v10
	s_waitcnt lgkmcnt(1)
	v_mov_b32_e32 v29, v18
	v_pk_mul_f32 v[26:27], v[28:29], v[26:27]
	v_mov_b32_e32 v18, v11
	v_add_f32_e32 v10, v44, v26
	v_add_f32_e32 v28, v10, v27
	v_and_b32_e32 v27, 0xffff0000, v41
	v_and_b32_e32 v26, 0xffff0000, v37
	v_pk_mul_f32 v[10:11], v[18:19], v[26:27]
	v_mov_b32_e32 v18, v12
	v_add_f32_e32 v10, v42, v10
	v_add_f32_e32 v26, v10, v11
	v_lshlrev_b32_e32 v11, 16, v40
	v_lshlrev_b32_e32 v10, 16, v36
	v_mov_b32_e32 v19, v20
	v_pk_mul_f32 v[10:11], v[18:19], v[10:11]
	v_mov_b32_e32 v20, v13
	v_add_f32_e32 v10, v43, v10
	v_add_f32_e32 v18, v10, v11
	v_and_b32_e32 v11, 0xffff0000, v40
	v_and_b32_e32 v10, 0xffff0000, v36
	v_pk_mul_f32 v[10:11], v[20:21], v[10:11]
	v_mov_b32_e32 v12, v14
	v_add_f32_e32 v10, v45, v10
	v_add_f32_e32 v19, v10, v11
	v_lshlrev_b32_e32 v11, 16, v39
	v_lshlrev_b32_e32 v10, 16, v35
	s_waitcnt lgkmcnt(0)
	v_mov_b32_e32 v13, v22
	v_pk_mul_f32 v[10:11], v[12:13], v[10:11]
	v_mov_b32_e32 v22, v15
	v_add_f32_e32 v10, v30, v10
	v_add_f32_e32 v14, v10, v11
	v_and_b32_e32 v11, 0xffff0000, v39
	v_and_b32_e32 v10, 0xffff0000, v35
	v_pk_mul_f32 v[10:11], v[22:23], v[10:11]
	v_mov_b32_e32 v12, v16
	v_add_f32_e32 v10, v31, v10
	v_add_f32_e32 v15, v10, v11
	v_lshlrev_b32_e32 v11, 16, v38
	v_lshlrev_b32_e32 v10, 16, v34
	v_mov_b32_e32 v13, v24
	v_pk_mul_f32 v[10:11], v[12:13], v[10:11]
	v_mov_b32_e32 v24, v17
	v_add_f32_e32 v10, v32, v10
	v_add_f32_e32 v12, v10, v11
	v_and_b32_e32 v11, 0xffff0000, v38
	v_and_b32_e32 v10, 0xffff0000, v34
	v_pk_mul_f32 v[10:11], v[24:25], v[10:11]
	v_cvt_pk_bf16_f32 v68, v28, v26
	v_cvt_pk_bf16_f32 v69, v18, v19
	v_cvt_pk_bf16_f32 v70, v14, v15
	s_nop 0
	v_add_f32_e32 v10, v33, v10
	v_add_f32_e32 v10, v10, v11
	v_cvt_pk_bf16_f32 v71, v12, v10
	ds_read_b128 v[26:29], v9 offset:10624
	ds_read_b128 v[30:33], v9 offset:10640
	s_waitcnt vmcnt(4)
	v_cndmask_b32_e32 v46, 0, v181, vcc
	v_cndmask_b32_e32 v47, 0, v180, vcc
	v_cndmask_b32_e32 v72, 0, v179, vcc
	v_cndmask_b32_e32 v73, 0, v178, vcc
	ds_read_b128 v[10:13], v9 offset:8576
	ds_read_b128 v[34:37], v9 offset:8592
	s_waitcnt vmcnt(4)
	v_cndmask_b32_e64 v74, 0, v185, s[4:5]
	v_cndmask_b32_e64 v75, 0, v184, s[4:5]
	v_cndmask_b32_e64 v76, 0, v183, s[4:5]
	v_cndmask_b32_e64 v77, 0, v182, s[4:5]
	ds_read_b128 v[14:17], v9 offset:9088
	ds_read_b128 v[38:41], v9 offset:9104
	v_lshlrev_b32_e32 v43, 16, v77
	v_lshlrev_b32_e32 v42, 16, v73
	s_waitcnt lgkmcnt(3)
	v_mov_b32_e32 v44, v10
	s_waitcnt lgkmcnt(1)
	v_mov_b32_e32 v45, v14
	v_pk_mul_f32 v[42:43], v[44:45], v[42:43]
	v_mov_b32_e32 v14, v11
	v_add_f32_e32 v10, v26, v42
	v_add_f32_e32 v44, v10, v43
	v_and_b32_e32 v43, 0xffff0000, v77
	v_and_b32_e32 v42, 0xffff0000, v73
	v_pk_mul_f32 v[10:11], v[14:15], v[42:43]
	v_mov_b32_e32 v14, v12
	v_add_f32_e32 v10, v27, v10
	v_add_f32_e32 v42, v10, v11
	v_lshlrev_b32_e32 v11, 16, v76
	v_lshlrev_b32_e32 v10, 16, v72
	v_mov_b32_e32 v15, v16
	v_pk_mul_f32 v[10:11], v[14:15], v[10:11]
	v_mov_b32_e32 v16, v13
	v_add_f32_e32 v10, v28, v10
	v_add_f32_e32 v43, v10, v11
	v_and_b32_e32 v11, 0xffff0000, v76
	v_and_b32_e32 v10, 0xffff0000, v72
	v_pk_mul_f32 v[10:11], v[16:17], v[10:11]
	v_mov_b32_e32 v12, v34
	v_add_f32_e32 v10, v29, v10
	v_add_f32_e32 v45, v10, v11
	v_lshlrev_b32_e32 v11, 16, v75
	v_lshlrev_b32_e32 v10, 16, v47
	s_waitcnt lgkmcnt(0)
	v_mov_b32_e32 v13, v38
	v_pk_mul_f32 v[10:11], v[12:13], v[10:11]
	v_mov_b32_e32 v38, v35
	v_add_f32_e32 v10, v30, v10
	v_add_f32_e32 v30, v10, v11
	v_and_b32_e32 v11, 0xffff0000, v75
	v_and_b32_e32 v10, 0xffff0000, v47
	v_pk_mul_f32 v[10:11], v[38:39], v[10:11]
	v_mov_b32_e32 v12, v36
	v_add_f32_e32 v10, v31, v10
	v_add_f32_e32 v31, v10, v11
	v_lshlrev_b32_e32 v11, 16, v74
	v_lshlrev_b32_e32 v10, 16, v46
	v_mov_b32_e32 v13, v40
	v_pk_mul_f32 v[10:11], v[12:13], v[10:11]
	v_mov_b32_e32 v40, v37
	v_add_f32_e32 v10, v32, v10
	v_add_f32_e32 v32, v10, v11
	v_and_b32_e32 v11, 0xffff0000, v74
	v_and_b32_e32 v10, 0xffff0000, v46
	v_pk_mul_f32 v[10:11], v[40:41], v[10:11]
	s_waitcnt vmcnt(4)
	v_cndmask_b32_e64 v34, 0, v189, s[8:9]
	v_add_f32_e32 v10, v33, v10
	v_add_f32_e32 v33, v10, v11
	v_cndmask_b32_e64 v35, 0, v188, s[8:9]
	v_cndmask_b32_e64 v36, 0, v187, s[8:9]
	v_cndmask_b32_e64 v37, 0, v186, s[8:9]
	ds_read_b128 v[10:13], v9 offset:9600
	ds_read_b128 v[14:17], v9 offset:9616
	s_waitcnt vmcnt(4)
	v_cndmask_b32_e64 v38, 0, v193, s[6:7]
	v_cndmask_b32_e64 v39, 0, v192, s[6:7]
	v_cndmask_b32_e64 v40, 0, v191, s[6:7]
	v_cndmask_b32_e64 v41, 0, v190, s[6:7]
	ds_read_b128 v[18:21], v9 offset:10112
	ds_read_b128 v[22:25], v9 offset:10128
	v_lshlrev_b32_e32 v27, 16, v41
	v_lshlrev_b32_e32 v26, 16, v37
	s_waitcnt lgkmcnt(3)
	v_mov_b32_e32 v28, v10
	s_waitcnt lgkmcnt(1)
	v_mov_b32_e32 v29, v18
	v_pk_mul_f32 v[26:27], v[28:29], v[26:27]
	v_mov_b32_e32 v18, v11
	v_add_f32_e32 v10, v44, v26
	v_add_f32_e32 v28, v10, v27
	v_and_b32_e32 v27, 0xffff0000, v41
	v_and_b32_e32 v26, 0xffff0000, v37
	v_pk_mul_f32 v[10:11], v[18:19], v[26:27]
	v_mov_b32_e32 v18, v12
	v_add_f32_e32 v10, v42, v10
	v_add_f32_e32 v26, v10, v11
	v_lshlrev_b32_e32 v11, 16, v40
	v_lshlrev_b32_e32 v10, 16, v36
	v_mov_b32_e32 v19, v20
	v_pk_mul_f32 v[10:11], v[18:19], v[10:11]
	v_mov_b32_e32 v20, v13
	v_add_f32_e32 v10, v43, v10
	v_add_f32_e32 v18, v10, v11
	v_and_b32_e32 v11, 0xffff0000, v40
	v_and_b32_e32 v10, 0xffff0000, v36
	v_pk_mul_f32 v[10:11], v[20:21], v[10:11]
	v_mov_b32_e32 v12, v14
	v_add_f32_e32 v10, v45, v10
	v_add_f32_e32 v19, v10, v11
	v_lshlrev_b32_e32 v11, 16, v39
	v_lshlrev_b32_e32 v10, 16, v35
	s_waitcnt lgkmcnt(0)
	v_mov_b32_e32 v13, v22
	v_pk_mul_f32 v[10:11], v[12:13], v[10:11]
	v_mov_b32_e32 v22, v15
	v_add_f32_e32 v10, v30, v10
	v_add_f32_e32 v14, v10, v11
	v_and_b32_e32 v11, 0xffff0000, v39
	v_and_b32_e32 v10, 0xffff0000, v35
	v_pk_mul_f32 v[10:11], v[22:23], v[10:11]
	v_mov_b32_e32 v12, v16
	v_add_f32_e32 v10, v31, v10
	v_add_f32_e32 v15, v10, v11
	v_lshlrev_b32_e32 v11, 16, v38
	v_lshlrev_b32_e32 v10, 16, v34
	v_mov_b32_e32 v13, v24
	v_pk_mul_f32 v[10:11], v[12:13], v[10:11]
	v_mov_b32_e32 v24, v17
	v_add_f32_e32 v10, v32, v10
	v_add_f32_e32 v12, v10, v11
	v_and_b32_e32 v11, 0xffff0000, v38
	v_and_b32_e32 v10, 0xffff0000, v34
	v_pk_mul_f32 v[10:11], v[24:25], v[10:11]
	v_cvt_pk_bf16_f32 v72, v28, v26
	v_cvt_pk_bf16_f32 v73, v18, v19
	v_cvt_pk_bf16_f32 v74, v14, v15
	v_lshlrev_b32_e32 v38, 3, v92
	v_add_f32_e32 v10, v33, v10
	v_add_f32_e32 v10, v10, v11
	v_cvt_pk_bf16_f32 v75, v12, v10
	s_nop 0
	s_nop 0
	ds_read_b128 v[18:21], v9 offset:10688
	ds_read_b128 v[22:25], v9 offset:10704
	v_or_b32_e32 v39, 16, v38
	s_waitcnt vmcnt(0)
	v_cndmask_b32_e32 v40, 0, v197, vcc
	v_cndmask_b32_e32 v41, 0, v196, vcc
	v_cndmask_b32_e32 v42, 0, v195, vcc
	v_cndmask_b32_e32 v43, 0, v194, vcc
	ds_read_b128 v[10:13], v9 offset:8640
	ds_read_b128 v[26:29], v9 offset:8656
	s_waitcnt vmcnt(0)
	v_cndmask_b32_e64 v44, 0, v201, s[4:5]
	v_cndmask_b32_e64 v45, 0, v200, s[4:5]
	v_cndmask_b32_e64 v46, 0, v199, s[4:5]
	v_cndmask_b32_e64 v47, 0, v198, s[4:5]
	ds_read_b128 v[14:17], v9 offset:9152
	ds_read_b128 v[30:33], v9 offset:9168
	v_lshlrev_b32_e32 v35, 16, v47
	v_lshlrev_b32_e32 v34, 16, v43
	s_waitcnt lgkmcnt(3)
	v_mov_b32_e32 v36, v10
	s_waitcnt lgkmcnt(1)
	v_mov_b32_e32 v37, v14
	v_pk_mul_f32 v[34:35], v[36:37], v[34:35]
	v_mov_b32_e32 v14, v11
	v_add_f32_e32 v10, v18, v34
	v_add_f32_e32 v36, v10, v35
	v_and_b32_e32 v35, 0xffff0000, v47
	v_and_b32_e32 v34, 0xffff0000, v43
	v_pk_mul_f32 v[10:11], v[14:15], v[34:35]
	v_mov_b32_e32 v14, v12
	v_add_f32_e32 v10, v19, v10
	v_add_f32_e32 v34, v10, v11
	v_lshlrev_b32_e32 v11, 16, v46
	v_lshlrev_b32_e32 v10, 16, v42
	v_mov_b32_e32 v15, v16
	v_pk_mul_f32 v[10:11], v[14:15], v[10:11]
	v_mov_b32_e32 v16, v13
	v_add_f32_e32 v10, v20, v10
	v_add_f32_e32 v35, v10, v11
	v_and_b32_e32 v11, 0xffff0000, v46
	v_and_b32_e32 v10, 0xffff0000, v42
	v_pk_mul_f32 v[10:11], v[16:17], v[10:11]
	v_mov_b32_e32 v12, v26
	v_add_f32_e32 v10, v21, v10
	v_add_f32_e32 v37, v10, v11
	v_lshlrev_b32_e32 v11, 16, v45
	v_lshlrev_b32_e32 v10, 16, v41
	s_waitcnt lgkmcnt(0)
	v_mov_b32_e32 v13, v30
	v_pk_mul_f32 v[10:11], v[12:13], v[10:11]
	v_mov_b32_e32 v30, v27
	v_add_f32_e32 v10, v22, v10
	v_add_f32_e32 v22, v10, v11
	v_and_b32_e32 v11, 0xffff0000, v45
	v_and_b32_e32 v10, 0xffff0000, v41
	v_pk_mul_f32 v[10:11], v[30:31], v[10:11]
	v_mov_b32_e32 v12, v28
	v_add_f32_e32 v10, v23, v10
	v_add_f32_e32 v23, v10, v11
	v_lshlrev_b32_e32 v11, 16, v44
	v_lshlrev_b32_e32 v10, 16, v40
	v_mov_b32_e32 v13, v32
	v_pk_mul_f32 v[10:11], v[12:13], v[10:11]
	v_mov_b32_e32 v32, v29
	v_add_f32_e32 v10, v24, v10
	v_add_f32_e32 v24, v10, v11
	v_and_b32_e32 v11, 0xffff0000, v44
	v_and_b32_e32 v10, 0xffff0000, v40
	v_pk_mul_f32 v[10:11], v[32:33], v[10:11]
	s_waitcnt vmcnt(0)
	v_cndmask_b32_e64 v26, 0, v205, s[8:9]
	v_add_f32_e32 v10, v25, v10
	v_add_f32_e32 v25, v10, v11
	v_cndmask_b32_e64 v27, 0, v204, s[8:9]
	v_cndmask_b32_e64 v28, 0, v203, s[8:9]
	v_cndmask_b32_e64 v29, 0, v202, s[8:9]
	ds_read_b128 v[0:3], v9 offset:9664
	ds_read_b128 v[10:13], v9 offset:9680
	s_waitcnt vmcnt(0)
	v_cndmask_b32_e64 v30, 0, v209, s[6:7]
	v_cndmask_b32_e64 v31, 0, v208, s[6:7]
	v_cndmask_b32_e64 v32, 0, v207, s[6:7]
	v_cndmask_b32_e64 v33, 0, v206, s[6:7]
	ds_read_b128 v[4:7], v9 offset:10176
	ds_read_b128 v[14:17], v9 offset:10192
	v_lshlrev_b32_e32 v19, 16, v33
	v_lshlrev_b32_e32 v18, 16, v29
	s_waitcnt lgkmcnt(3)
	v_mov_b32_e32 v20, v0
	s_waitcnt lgkmcnt(1)
	v_mov_b32_e32 v21, v4
	v_pk_mul_f32 v[18:19], v[20:21], v[18:19]
	v_mov_b32_e32 v4, v1
	v_add_f32_e32 v0, v36, v18
	v_add_f32_e32 v9, v0, v19
	v_and_b32_e32 v19, 0xffff0000, v33
	v_and_b32_e32 v18, 0xffff0000, v29
	v_pk_mul_f32 v[0:1], v[4:5], v[18:19]
	v_mov_b32_e32 v4, v2
	v_add_f32_e32 v0, v34, v0
	v_add_f32_e32 v18, v0, v1
	v_lshlrev_b32_e32 v1, 16, v32
	v_lshlrev_b32_e32 v0, 16, v28
	v_mov_b32_e32 v5, v6
	v_pk_mul_f32 v[0:1], v[4:5], v[0:1]
	v_mov_b32_e32 v6, v3
	v_add_f32_e32 v0, v35, v0
	v_add_f32_e32 v4, v0, v1
	v_and_b32_e32 v1, 0xffff0000, v32
	v_and_b32_e32 v0, 0xffff0000, v28
	v_pk_mul_f32 v[0:1], v[6:7], v[0:1]
	v_mov_b32_e32 v2, v10
	v_add_f32_e32 v0, v37, v0
	v_add_f32_e32 v5, v0, v1
	v_lshlrev_b32_e32 v1, 16, v31
	v_lshlrev_b32_e32 v0, 16, v27
	s_waitcnt lgkmcnt(0)
	v_mov_b32_e32 v3, v14
	v_pk_mul_f32 v[0:1], v[2:3], v[0:1]
	v_mov_b32_e32 v14, v11
	v_add_f32_e32 v0, v22, v0
	v_add_f32_e32 v6, v0, v1
	v_and_b32_e32 v1, 0xffff0000, v31
	v_and_b32_e32 v0, 0xffff0000, v27
	v_pk_mul_f32 v[0:1], v[14:15], v[0:1]
	v_mov_b32_e32 v2, v12
	v_add_f32_e32 v0, v23, v0
	v_add_f32_e32 v7, v0, v1
	v_lshlrev_b32_e32 v1, 16, v30
	v_lshlrev_b32_e32 v0, 16, v26
	v_mov_b32_e32 v3, v16
	v_pk_mul_f32 v[0:1], v[2:3], v[0:1]
	v_mov_b32_e32 v16, v13
	v_add_f32_e32 v0, v24, v0
	v_add_f32_e32 v2, v0, v1
	v_and_b32_e32 v1, 0xffff0000, v30
	v_and_b32_e32 v0, 0xffff0000, v26
	v_pk_mul_f32 v[0:1], v[16:17], v[0:1]
	v_cvt_pk_bf16_f32 v76, v9, v18
	v_cvt_pk_bf16_f32 v77, v4, v5
	v_cvt_pk_bf16_f32 v78, v6, v7
	v_cmp_eq_u32_e32 vcc, v38, v93
	v_add_f32_e32 v0, v25, v0
	v_add_f32_e32 v0, v0, v1
	v_cvt_pk_bf16_f32 v79, v2, v0
	v_or_b32_e32 v2, 1, v38
	v_cndmask_b32_e32 v0, 0, v128, vcc
	v_or_b32_e32 v1, 2, v38
	v_cmp_eq_u32_e32 vcc, v2, v93
	v_or_b32_e32 v4, 3, v38
	v_or_b32_e32 v3, 4, v38
	v_cndmask_b32_e32 v2, 0, v128, vcc
	v_cmp_eq_u32_e32 vcc, v1, v93
	v_or_b32_e32 v5, 6, v38
	v_or_b32_e32 v6, 5, v38
	v_cndmask_b32_e32 v1, 0, v128, vcc
	v_cmp_eq_u32_e32 vcc, v4, v93
	v_or_b32_e32 v7, 7, v38
	v_or_b32_e32 v11, 17, v38
	v_cndmask_b32_e32 v4, 0, v128, vcc
	v_cmp_eq_u32_e32 vcc, v3, v93
	v_or_b32_e32 v10, 18, v38
	v_or_b32_e32 v13, 19, v38
	v_cndmask_b32_e32 v3, 0, v128, vcc
	v_cmp_eq_u32_e32 vcc, v5, v93
	v_or_b32_e32 v12, 20, v38
	v_or_b32_e32 v14, 22, v38
	v_cndmask_b32_e32 v5, 0, v128, vcc
	v_cmp_eq_u32_e32 vcc, v6, v93
	v_or_b32_e32 v15, 21, v38
	v_or_b32_e32 v16, 23, v38
	v_cndmask_b32_e32 v6, 0, v128, vcc
	v_cmp_eq_u32_e32 vcc, v7, v93
	v_and_b32_e32 v18, 64, v126
	v_xor_b32_e32 v17, 32, v126
	v_cndmask_b32_e32 v7, 0, v128, vcc
	v_cmp_eq_u32_e32 vcc, v39, v93
	v_add_u32_e32 v18, 64, v18
	s_lshl_b32 s6, s64, 8
	v_cndmask_b32_e32 v9, 0, v128, vcc
	v_cmp_eq_u32_e32 vcc, v11, v93
	s_add_i32 s6, s6, 16
	v_cmp_eq_u32_e64 s[4:5], 0, v92
	v_cndmask_b32_e32 v11, 0, v128, vcc
	v_cmp_eq_u32_e32 vcc, v10, v93
	v_lshl_add_u32 v136, v93, 3, s6
	v_perm_b32 v82, v6, v3, s87
	v_cndmask_b32_e32 v10, 0, v128, vcc
	v_cmp_eq_u32_e32 vcc, v13, v93
	v_perm_b32 v81, v4, v1, s87
	v_perm_b32 v83, v7, v5, s87
	v_cndmask_b32_e32 v13, 0, v128, vcc
	v_cmp_eq_u32_e32 vcc, v12, v93
	v_perm_b32 v80, v2, v0, s87
	v_perm_b32 v85, v13, v10, s87
	v_cndmask_b32_e32 v12, 0, v128, vcc
	v_cmp_eq_u32_e32 vcc, v14, v93
	v_perm_b32 v84, v11, v9, s87
	s_nop 0
	v_cndmask_b32_e32 v14, 0, v128, vcc
	v_cmp_eq_u32_e32 vcc, v15, v93
	s_nop 1
	v_cndmask_b32_e32 v15, 0, v128, vcc
	v_cmp_eq_u32_e32 vcc, v16, v93
	v_perm_b32 v86, v15, v12, s87
	s_nop 0
	v_cndmask_b32_e32 v16, 0, v128, vcc
	v_cmp_lt_i32_e32 vcc, v17, v18
	v_perm_b32 v87, v16, v14, s87
	s_nop 0
	v_cndmask_b32_e32 v17, v126, v17, vcc
	v_lshlrev_b32_e32 v137, 2, v17
	v_lshl_or_b32 v175, v138, 2, v129
	global_load_dword v172, v175, s[42:43]
	global_load_dword v173, v175, s[36:37]
	global_load_dword v174, v175, s[40:41]
	s_setprio 1
	v_xad_u32 v145, v88, v8, v94
	ds_read_b128 v[0:3], v145 offset:16384
	ds_read_b128 v[4:7], v145 offset:49152
	s_waitcnt lgkmcnt(1)
	v_mfma_f32_32x32x16_bf16 v[32:47], v[48:51], v[0:3], 0
	v_or_b32_e32 v0, 32, v88
	v_xad_u32 v147, v0, v8, v94
	s_waitcnt lgkmcnt(0)
	v_mfma_f32_32x32x16_bf16 v[16:31], v[48:51], v[4:7], 0
	ds_read_b128 v[0:3], v147 offset:16384
	ds_read_b128 v[4:7], v147 offset:49152
	s_waitcnt lgkmcnt(1)
	v_mfma_f32_32x32x16_bf16 v[32:47], v[52:55], v[0:3], v[32:47]
	v_or_b32_e32 v0, 64, v88
	v_xad_u32 v142, v0, v8, v94
	s_waitcnt lgkmcnt(0)
	v_mfma_f32_32x32x16_bf16 v[16:31], v[52:55], v[4:7], v[16:31]
	ds_read_b128 v[0:3], v142 offset:16384
	ds_read_b128 v[4:7], v142 offset:49152
	s_waitcnt lgkmcnt(1)
	v_mfma_f32_32x32x16_bf16 v[32:47], v[56:59], v[0:3], v[32:47]
	v_or_b32_e32 v0, 0x60, v88
	v_xad_u32 v146, v0, v8, v94
	s_waitcnt lgkmcnt(0)
	v_mfma_f32_32x32x16_bf16 v[16:31], v[56:59], v[4:7], v[16:31]
	ds_read_b128 v[0:3], v146 offset:16384
	ds_read_b128 v[4:7], v146 offset:49152
	s_waitcnt lgkmcnt(1)
	v_mfma_f32_32x32x16_bf16 v[32:47], v[60:63], v[0:3], v[32:47]
	v_or_b32_e32 v0, 0x80, v88
	v_xad_u32 v141, v0, v8, v94
	s_waitcnt lgkmcnt(0)
	v_mfma_f32_32x32x16_bf16 v[16:31], v[60:63], v[4:7], v[16:31]
	ds_read_b128 v[0:3], v141 offset:16384
	ds_read_b128 v[4:7], v141 offset:49152
	s_waitcnt lgkmcnt(1)
	v_mfma_f32_32x32x16_bf16 v[32:47], v[64:67], v[0:3], v[32:47]
	v_or_b32_e32 v0, 0xa0, v88
	v_xad_u32 v144, v0, v8, v94
	s_waitcnt lgkmcnt(0)
	v_mfma_f32_32x32x16_bf16 v[16:31], v[64:67], v[4:7], v[16:31]
	ds_read_b128 v[0:3], v144 offset:16384
	ds_read_b128 v[4:7], v144 offset:49152
	s_waitcnt lgkmcnt(1)
	v_mfma_f32_32x32x16_bf16 v[32:47], v[68:71], v[0:3], v[32:47]
	v_or_b32_e32 v0, 0xc0, v88
	v_xad_u32 v139, v0, v8, v94
	s_waitcnt lgkmcnt(0)
	v_mfma_f32_32x32x16_bf16 v[16:31], v[68:71], v[4:7], v[16:31]
	ds_read_b128 v[0:3], v139 offset:16384
	ds_read_b128 v[4:7], v139 offset:49152
	s_waitcnt lgkmcnt(1)
	v_mfma_f32_32x32x16_bf16 v[32:47], v[72:75], v[0:3], v[32:47]
	v_or_b32_e32 v0, 0xe0, v88
	v_xad_u32 v143, v0, v8, v94
	s_waitcnt lgkmcnt(0)
	v_mfma_f32_32x32x16_bf16 v[16:31], v[72:75], v[4:7], v[16:31]
	ds_read_b128 v[0:3], v143 offset:16384
	ds_read_b128 v[4:7], v143 offset:49152
	s_waitcnt lgkmcnt(1)
	v_mfma_f32_32x32x16_bf16 v[32:47], v[76:79], v[0:3], v[32:47]
	s_waitcnt lgkmcnt(0)
	v_mfma_f32_32x32x16_bf16 v[16:31], v[76:79], v[4:7], v[16:31]
	v_mfma_f32_32x32x16_bf16 v[0:15], v[48:51], v[80:83], 0
	v_mfma_f32_32x32x16_bf16 v[0:15], v[52:55], v[84:87], v[0:15]
	s_setprio 0
	v_lshl_or_b32 v88, v138, 2, v129
	s_waitcnt vmcnt(0)
	ds_read_b32 v251, v167
	v_mul_f32_e32 v94, 0xbfb8aa3b, v173
	v_mul_f32_e32 v88, 0xbfb8aa3b, v174
	v_fmamk_f32 v32, v32, 0xbfb8aa3b, v94
	v_fmamk_f32 v16, v16, 0xbfb8aa3b, v88
	v_exp_f32_e32 v32, v32
	v_exp_f32_e32 v96, v16
	v_fmamk_f32 v17, v17, 0xbfb8aa3b, v88
	v_exp_f32_e32 v97, v17
	v_add_f32_e32 v32, 1.0, v32
	v_add_f32_e32 v96, 1.0, v96
	v_rcp_f32_e32 v17, v32
	v_rcp_f32_e32 v32, v96
	v_fmamk_f32 v33, v33, 0xbfb8aa3b, v94
	v_fmamk_f32 v34, v34, 0xbfb8aa3b, v94
	v_exp_f32_e32 v33, v33
	v_exp_f32_e32 v34, v34
	v_add_f32_e32 v33, 1.0, v33
	v_add_f32_e32 v34, 1.0, v34
	v_rcp_f32_e32 v33, v33
	v_rcp_f32_e32 v34, v34
	v_fmamk_f32 v18, v18, 0xbfb8aa3b, v88
	v_fmamk_f32 v19, v19, 0xbfb8aa3b, v88
	v_exp_f32_e32 v18, v18
	s_waitcnt lgkmcnt(0)
	v_mul_f32_e32 v95, 0x3fb8aa3b, v251
	v_mul_f32_e32 v16, v17, v95
	v_mul_f32_e32 v17, v33, v95
	v_exp_f32_e32 v33, v16
	v_mul_f32_e32 v16, v34, v95
	v_exp_f32_e32 v98, v16
	v_fmamk_f32 v16, v35, 0xbfb8aa3b, v94
	v_exp_f32_e32 v16, v16
	v_exp_f32_e32 v96, v17
	v_add_f32_e32 v16, 1.0, v16
	v_rcp_f32_e32 v16, v16
	v_exp_f32_e32 v19, v19
	v_add_f32_e32 v97, 1.0, v97
	v_add_f32_e32 v18, 1.0, v18
	v_mul_f32_e32 v16, v16, v95
	v_exp_f32_e32 v16, v16
	v_fma_f32 v35, -v98, v98, 1.0
	v_rcp_f32_e32 v17, v97
	v_fma_f32 v34, -v33, v33, 1.0
	v_fma_f32 v97, -v96, v96, 1.0
	v_rcp_f32_e32 v18, v18
	v_sqrt_f32_e32 v35, v35
	v_add_f32_e32 v19, 1.0, v19
	v_fma_f32 v99, -v16, v16, 1.0
	v_sqrt_f32_e32 v34, v34
	v_sqrt_f32_e32 v97, v97
	v_rcp_f32_e32 v19, v19
	v_sqrt_f32_e32 v99, v99
	v_mul_f32_e32 v35, v18, v35
	v_fmamk_f32 v18, v36, 0xbfb8aa3b, v94
	v_mul_f32_e32 v32, v32, v34
	v_mul_f32_e32 v34, v17, v97
	v_mul_f32_e32 v17, v19, v99
	v_fmamk_f32 v19, v20, 0xbfb8aa3b, v88
	v_exp_f32_e32 v18, v18
	v_exp_f32_e32 v19, v19
	v_mul_f32_e32 v3, v3, v17
	v_add_f32_e32 v17, 1.0, v18
	v_rcp_f32_e32 v17, v17
	v_add_f32_e32 v18, 1.0, v19
	v_fmamk_f32 v19, v37, 0xbfb8aa3b, v94
	v_exp_f32_e32 v19, v19
	v_mul_f32_e32 v17, v17, v95
	v_exp_f32_e32 v36, v17
	v_add_f32_e32 v17, 1.0, v19
	v_rcp_f32_e32 v17, v17
	v_fmamk_f32 v19, v21, 0xbfb8aa3b, v88
	v_exp_f32_e32 v19, v19
	v_mul_f32_e32 v17, v17, v95
	v_exp_f32_e32 v37, v17
	v_fmamk_f32 v17, v38, 0xbfb8aa3b, v94
	v_exp_f32_e32 v17, v17
	v_fmamk_f32 v23, v23, 0xbfb8aa3b, v88
	v_add_f32_e32 v19, 1.0, v19
	v_fma_f32 v21, -v37, v37, 1.0
	v_add_f32_e32 v17, 1.0, v17
	v_rcp_f32_e32 v17, v17
	v_rcp_f32_e32 v19, v19
	v_sqrt_f32_e32 v21, v21
	v_mul_f32_e32 v17, v17, v95
	v_exp_f32_e32 v38, v17
	v_fmamk_f32 v17, v39, 0xbfb8aa3b, v94
	v_exp_f32_e32 v17, v17
	v_exp_f32_e32 v23, v23
	v_fma_f32 v20, -v36, v36, 1.0
	v_mul_f32_e32 v100, v19, v21
	v_add_f32_e32 v17, 1.0, v17
	v_rcp_f32_e32 v17, v17
	v_add_f32_e32 v23, 1.0, v23
	v_fmamk_f32 v19, v40, 0xbfb8aa3b, v94
	v_rcp_f32_e32 v18, v18
	v_mul_f32_e32 v17, v17, v95
	v_exp_f32_e32 v17, v17
	v_sqrt_f32_e32 v20, v20
	v_rcp_f32_e32 v23, v23
	v_fma_f32 v97, -v17, v17, 1.0
	v_sqrt_f32_e32 v97, v97
	v_fmamk_f32 v21, v24, 0xbfb8aa3b, v88
	v_fmamk_f32 v22, v22, 0xbfb8aa3b, v88
	v_exp_f32_e32 v19, v19
	v_exp_f32_e32 v21, v21
	v_exp_f32_e32 v22, v22
	v_mul_f32_e32 v99, v18, v20
	v_mul_f32_e32 v18, v23, v97
	v_mul_f32_e32 v7, v7, v18
	v_add_f32_e32 v18, 1.0, v19
	v_rcp_f32_e32 v18, v18
	v_add_f32_e32 v19, 1.0, v21
	v_fmamk_f32 v21, v41, 0xbfb8aa3b, v94
	v_add_f32_e32 v22, 1.0, v22
	v_fma_f32 v39, -v38, v38, 1.0
	v_rcp_f32_e32 v22, v22
	v_sqrt_f32_e32 v39, v39
	v_exp_f32_e32 v21, v21
	v_mul_f32_e32 v18, v18, v95
	v_mul_f32_e32 v20, v22, v39
	v_exp_f32_e32 v39, v18
	v_add_f32_e32 v18, 1.0, v21
	v_rcp_f32_e32 v18, v18
	v_fmamk_f32 v21, v25, 0xbfb8aa3b, v88
	v_exp_f32_e32 v21, v21
	v_mul_f32_e32 v18, v18, v95
	v_exp_f32_e32 v40, v18
	v_fmamk_f32 v18, v42, 0xbfb8aa3b, v94
	v_exp_f32_e32 v18, v18
	v_fmamk_f32 v24, v26, 0xbfb8aa3b, v88
	v_fmamk_f32 v26, v27, 0xbfb8aa3b, v88
	v_add_f32_e32 v21, 1.0, v21
	v_add_f32_e32 v18, 1.0, v18
	v_rcp_f32_e32 v18, v18
	v_fma_f32 v23, -v40, v40, 1.0
	v_fma_f32 v22, -v39, v39, 1.0
	v_mul_f32_e32 v18, v18, v95
	v_exp_f32_e32 v41, v18
	v_fmamk_f32 v18, v43, 0xbfb8aa3b, v94
	v_exp_f32_e32 v18, v18
	v_rcp_f32_e32 v21, v21
	v_sqrt_f32_e32 v23, v23
	v_exp_f32_e32 v26, v26
	v_add_f32_e32 v18, 1.0, v18
	v_rcp_f32_e32 v18, v18
	v_rcp_f32_e32 v19, v19
	v_sqrt_f32_e32 v22, v22
	v_add_f32_e32 v26, 1.0, v26
	v_mul_f32_e32 v18, v18, v95
	v_exp_f32_e32 v18, v18
	v_mul_f32_e32 v43, v21, v23
	v_fmamk_f32 v21, v44, 0xbfb8aa3b, v94
	v_rcp_f32_e32 v26, v26
	v_fma_f32 v27, -v18, v18, 1.0
	v_sqrt_f32_e32 v27, v27
	v_mul_f32_e32 v42, v19, v22
	v_fmamk_f32 v22, v28, 0xbfb8aa3b, v88
	v_exp_f32_e32 v21, v21
	v_exp_f32_e32 v22, v22
	v_mul_f32_e32 v19, v26, v27
	v_mul_f32_e32 v11, v11, v19
	v_add_f32_e32 v19, 1.0, v21
	v_rcp_f32_e32 v19, v19
	v_add_f32_e32 v21, 1.0, v22
	v_fmamk_f32 v22, v45, 0xbfb8aa3b, v94
	v_exp_f32_e32 v22, v22
	v_mul_f32_e32 v19, v19, v95
	v_exp_f32_e32 v44, v19
	v_add_f32_e32 v19, 1.0, v22
	v_rcp_f32_e32 v19, v19
	v_exp_f32_e32 v24, v24
	v_fma_f32 v25, -v41, v41, 1.0
	v_mul_f32_e32 v19, v19, v95
	v_exp_f32_e32 v45, v19
	v_fmamk_f32 v19, v46, 0xbfb8aa3b, v94
	v_exp_f32_e32 v19, v19
	v_add_f32_e32 v24, 1.0, v24
	v_rcp_f32_e32 v24, v24
	v_sqrt_f32_e32 v25, v25
	v_add_f32_e32 v19, 1.0, v19
	v_rcp_f32_e32 v19, v19
	v_fmamk_f32 v22, v29, 0xbfb8aa3b, v88
	v_mul_f32_e32 v97, v24, v25
	v_fma_f32 v24, -v45, v45, 1.0
	v_mul_f32_e32 v19, v19, v95
	v_exp_f32_e32 v46, v19
	v_fmamk_f32 v19, v47, 0xbfb8aa3b, v94
	v_exp_f32_e32 v19, v19
	v_sqrt_f32_e32 v25, v24
	v_fmamk_f32 v24, v30, 0xbfb8aa3b, v88
	v_exp_f32_e32 v24, v24
	v_add_f32_e32 v19, 1.0, v19
	v_rcp_f32_e32 v19, v19
	v_fma_f32 v27, -v46, v46, 1.0
	v_add_f32_e32 v24, 1.0, v24
	v_rcp_f32_e32 v26, v24
	v_fmamk_f32 v24, v31, 0xbfb8aa3b, v88
	v_mul_f32_e32 v19, v19, v95
	v_exp_f32_e32 v28, v24
	v_exp_f32_e32 v24, v19
	v_sqrt_f32_e32 v19, v27
	v_add_f32_e32 v27, 1.0, v28
	v_fma_f32 v28, -v24, v24, 1.0
	v_exp_f32_e32 v22, v22
	v_rcp_f32_e32 v27, v27
	v_sqrt_f32_e32 v28, v28
	v_fma_f32 v23, -v44, v44, 1.0
	v_rcp_f32_e32 v21, v21
	v_sqrt_f32_e32 v23, v23
	v_add_f32_e32 v22, 1.0, v22
	v_mul_f32_e32 v94, v26, v19
	v_mul_f32_e32 v19, v27, v28
	v_fmac_f32_e32 v7, 0, v17
	v_rcp_f32_e32 v22, v22
	v_mul_f32_e32 v15, v15, v19
	v_mul_f32_e32 v19, v38, v7
	v_fmac_f32_e32 v3, 0, v16
	v_fmac_f32_e32 v19, v6, v20
	v_mul_f32_e32 v47, v21, v23
	v_mul_f32_e32 v21, v98, v3
	v_mul_f32_e32 v20, v37, v19
	v_fmac_f32_e32 v15, 0, v24
	v_fmac_f32_e32 v21, v2, v35
	v_fmac_f32_e32 v20, v5, v100
	v_mul_f32_e32 v2, v46, v15
	v_mul_f32_e32 v88, v22, v25
	v_mul_f32_e32 v22, v36, v20
	v_fmac_f32_e32 v2, v14, v94
	v_fmac_f32_e32 v22, v4, v99
	v_mul_f32_e32 v4, v45, v2
	v_mul_f32_e32 v23, v96, v21
	v_fmac_f32_e32 v4, v13, v88
	v_fmac_f32_e32 v23, v1, v34
	v_fmac_f32_e32 v11, 0, v18
	v_mul_f32_e32 v14, v24, v46
	v_mul_f32_e32 v6, v44, v4
	v_mul_f32_e32 v25, v33, v23
	v_mul_f32_e32 v5, v41, v11
	v_mul_f32_e32 v13, v45, v14
	v_fmac_f32_e32 v6, v12, v47
	v_fmac_f32_e32 v25, v0, v32
	v_fmac_f32_e32 v5, v10, v97
	v_mul_f32_e32 v12, v44, v13
	ds_bpermute_b32 v0, v137, v6
	v_mul_f32_e32 v10, v40, v5
	ds_bpermute_b32 v35, v137, v12
	v_mul_f32_e32 v28, v18, v41
	v_fmac_f32_e32 v10, v9, v43
	v_mul_f32_e32 v26, v16, v98
	v_mul_f32_e32 v27, v17, v38
	v_mul_f32_e32 v31, v40, v28
	v_mul_f32_e32 v9, v39, v10
	v_mul_f32_e32 v29, v96, v26
	v_mul_f32_e32 v30, v37, v27
	v_fmac_f32_e32 v9, v8, v42
	v_mul_f32_e32 v34, v39, v31
	v_mul_f32_e32 v32, v33, v29
	v_mul_f32_e32 v33, v36, v30
	s_waitcnt lgkmcnt(1)
	v_cndmask_b32_e64 v36, v0, v6, s[4:5]
	v_cndmask_b32_e64 v37, v6, v0, s[4:5]
	ds_bpermute_b32 v0, v137, v34
	ds_bpermute_b32 v40, v137, v9
	s_waitcnt lgkmcnt(2)
	v_cndmask_b32_e64 v8, v12, v35, s[4:5]
	v_fmac_f32_e32 v37, 0, v8
	ds_bpermute_b32 v8, v137, v33
	v_cndmask_b32_e64 v1, v35, v12, s[4:5]
	v_mul_f32_e32 v38, v12, v35
	v_fmac_f32_e32 v36, v1, v37
	s_waitcnt lgkmcnt(2)
	v_cndmask_b32_e64 v1, v0, v34, s[4:5]
	s_waitcnt lgkmcnt(1)
	v_cndmask_b32_e64 v39, v40, v9, s[4:5]
	v_cndmask_b32_e64 v0, v34, v0, s[4:5]
	v_cndmask_b32_e64 v40, v9, v40, s[4:5]
	ds_bpermute_b32 v44, v137, v22
	v_mul_f32_e32 v41, v38, v0
	v_fmac_f32_e32 v40, v0, v36
	v_mul_f32_e32 v42, v1, v41
	v_fmac_f32_e32 v39, v1, v40
	s_waitcnt lgkmcnt(1)
	v_cndmask_b32_e64 v0, v8, v33, s[4:5]
	v_cndmask_b32_e64 v1, v33, v8, s[4:5]
	ds_bpermute_b32 v8, v137, v32
	ds_bpermute_b32 v47, v137, v25
	s_waitcnt lgkmcnt(2)
	v_cndmask_b32_e64 v43, v44, v22, s[4:5]
	v_cndmask_b32_e64 v44, v22, v44, s[4:5]
	v_mul_f32_e32 v45, v1, v42
	v_fmac_f32_e32 v44, v1, v39
	v_mul_f32_e32 v46, v0, v45
	v_fmac_f32_e32 v43, v0, v44
	s_waitcnt lgkmcnt(1)
	v_cndmask_b32_e64 v0, v32, v8, s[4:5]
	s_waitcnt lgkmcnt(0)
	v_cndmask_b32_e64 v47, v25, v47, s[4:5]
	v_mul_f32_e32 v88, v0, v46
	v_fmac_f32_e32 v47, v0, v43
	s_and_saveexec_b64 s[6:7], s[4:5]
	v_mul_f32_e32 v0, v32, v88
	v_fma_f32 v1, v32, v47, v25
	ds_write_b64 v136, v[0:1]
	s_or_b64 exec, exec, s[6:7]
	s_cmp_lt_i32 s64, 7
	s_cselect_b64 s[14:15], -1, 0
	s_cmp_gt_i32 s64, 6
	v_mul_i32_i24_e32 v140, 0xffffff08, v93
	s_waitcnt lgkmcnt(0)
	s_barrier
	s_cbranch_scc1 .LBB0_269
	v_add3_u32 v94, v140, v91, s92
	v_mov_b32_e32 v8, 1.0
	v_mov_b32_e32 v1, 0
	s_mov_b32 s6, 7

.LBB0_272:
	s_or_b64 exec, exec, s[8:9]
	s_setprio 1
	ds_read_b128 v[0:3], v145 offset:24576
	ds_read_b128 v[4:7], v145 offset:57344
	s_waitcnt lgkmcnt(1)
	v_mfma_f32_32x32x16_bf16 v[32:47], v[48:51], v[0:3], 0
	s_waitcnt lgkmcnt(0)
	v_mfma_f32_32x32x16_bf16 v[16:31], v[48:51], v[4:7], 0
	ds_read_b128 v[0:3], v147 offset:24576
	ds_read_b128 v[4:7], v147 offset:57344
	s_waitcnt lgkmcnt(1)
	v_mfma_f32_32x32x16_bf16 v[32:47], v[52:55], v[0:3], v[32:47]
	s_waitcnt lgkmcnt(0)
	v_mfma_f32_32x32x16_bf16 v[16:31], v[52:55], v[4:7], v[16:31]
	ds_read_b128 v[0:3], v142 offset:24576
	ds_read_b128 v[4:7], v142 offset:57344
	s_waitcnt lgkmcnt(1)
	v_mfma_f32_32x32x16_bf16 v[32:47], v[56:59], v[0:3], v[32:47]
	s_waitcnt lgkmcnt(0)
	v_mfma_f32_32x32x16_bf16 v[16:31], v[56:59], v[4:7], v[16:31]
	ds_read_b128 v[0:3], v146 offset:24576
	ds_read_b128 v[4:7], v146 offset:57344
	s_waitcnt lgkmcnt(1)
	v_mfma_f32_32x32x16_bf16 v[32:47], v[60:63], v[0:3], v[32:47]
	s_waitcnt lgkmcnt(0)
	v_mfma_f32_32x32x16_bf16 v[16:31], v[60:63], v[4:7], v[16:31]
	ds_read_b128 v[0:3], v141 offset:24576
	ds_read_b128 v[4:7], v141 offset:57344
	s_waitcnt lgkmcnt(1)
	v_mfma_f32_32x32x16_bf16 v[32:47], v[64:67], v[0:3], v[32:47]
	s_waitcnt lgkmcnt(0)
	v_mfma_f32_32x32x16_bf16 v[16:31], v[64:67], v[4:7], v[16:31]
	ds_read_b128 v[0:3], v144 offset:24576
	ds_read_b128 v[4:7], v144 offset:57344
	s_waitcnt lgkmcnt(1)
	v_mfma_f32_32x32x16_bf16 v[32:47], v[68:71], v[0:3], v[32:47]
	s_waitcnt lgkmcnt(0)
	v_mfma_f32_32x32x16_bf16 v[16:31], v[68:71], v[4:7], v[16:31]
	ds_read_b128 v[0:3], v139 offset:24576
	ds_read_b128 v[4:7], v139 offset:57344
	s_waitcnt lgkmcnt(1)
	v_mfma_f32_32x32x16_bf16 v[32:47], v[72:75], v[0:3], v[32:47]
	s_waitcnt lgkmcnt(0)
	v_mfma_f32_32x32x16_bf16 v[16:31], v[72:75], v[4:7], v[16:31]
	ds_read_b128 v[0:3], v143 offset:24576
	ds_read_b128 v[4:7], v143 offset:57344
	s_waitcnt lgkmcnt(1)
	v_mfma_f32_32x32x16_bf16 v[32:47], v[76:79], v[0:3], v[32:47]
	s_waitcnt lgkmcnt(0)
	v_mfma_f32_32x32x16_bf16 v[16:31], v[76:79], v[4:7], v[16:31]
	v_mfma_f32_32x32x16_bf16 v[0:15], v[56:59], v[80:83], 0
	v_mfma_f32_32x32x16_bf16 v[0:15], v[60:63], v[84:87], v[0:15]
	s_setprio 0
	v_lshl_or_b32 v93, v138, 2, v133
	s_waitcnt vmcnt(16)
	ds_read_b32 v251, v167 offset:128
	v_mul_f32_e32 v148, 0xbfb8aa3b, v173
	v_mul_f32_e32 v93, 0xbfb8aa3b, v174
	v_fmamk_f32 v32, v32, 0xbfb8aa3b, v148
	v_fmamk_f32 v16, v16, 0xbfb8aa3b, v93
	v_exp_f32_e32 v32, v32
	v_exp_f32_e32 v150, v16
	v_fmamk_f32 v17, v17, 0xbfb8aa3b, v93
	v_exp_f32_e32 v151, v17
	v_add_f32_e32 v32, 1.0, v32
	v_add_f32_e32 v150, 1.0, v150
	v_rcp_f32_e32 v17, v32
	v_rcp_f32_e32 v32, v150
	v_fmamk_f32 v33, v33, 0xbfb8aa3b, v148
	v_fmamk_f32 v34, v34, 0xbfb8aa3b, v148
	v_exp_f32_e32 v33, v33
	v_exp_f32_e32 v34, v34
	v_add_f32_e32 v33, 1.0, v33
	v_add_f32_e32 v34, 1.0, v34
	v_rcp_f32_e32 v33, v33
	v_rcp_f32_e32 v34, v34
	v_fmamk_f32 v18, v18, 0xbfb8aa3b, v93
	v_fmamk_f32 v19, v19, 0xbfb8aa3b, v93
	v_exp_f32_e32 v18, v18
	s_waitcnt lgkmcnt(0)
	v_mul_f32_e32 v149, 0x3fb8aa3b, v251
	v_mul_f32_e32 v16, v17, v149
	v_mul_f32_e32 v17, v33, v149
	v_exp_f32_e32 v33, v16
	v_mul_f32_e32 v16, v34, v149
	v_exp_f32_e32 v152, v16
	v_fmamk_f32 v16, v35, 0xbfb8aa3b, v148
	v_exp_f32_e32 v16, v16
	v_exp_f32_e32 v150, v17
	v_add_f32_e32 v16, 1.0, v16
	v_rcp_f32_e32 v16, v16
	v_exp_f32_e32 v19, v19
	v_add_f32_e32 v151, 1.0, v151
	v_add_f32_e32 v18, 1.0, v18
	v_mul_f32_e32 v16, v16, v149
	v_exp_f32_e32 v16, v16
	v_fma_f32 v35, -v152, v152, 1.0
	v_rcp_f32_e32 v17, v151
	v_fma_f32 v34, -v33, v33, 1.0
	v_fma_f32 v151, -v150, v150, 1.0
	v_rcp_f32_e32 v18, v18
	v_sqrt_f32_e32 v35, v35
	v_add_f32_e32 v19, 1.0, v19
	v_fma_f32 v153, -v16, v16, 1.0
	v_sqrt_f32_e32 v34, v34
	v_sqrt_f32_e32 v151, v151
	v_rcp_f32_e32 v19, v19
	v_sqrt_f32_e32 v153, v153
	v_mul_f32_e32 v35, v18, v35
	v_fmamk_f32 v18, v36, 0xbfb8aa3b, v148
	v_mul_f32_e32 v32, v32, v34
	v_mul_f32_e32 v34, v17, v151
	v_mul_f32_e32 v17, v19, v153
	v_fmamk_f32 v19, v20, 0xbfb8aa3b, v93
	v_exp_f32_e32 v18, v18
	v_exp_f32_e32 v19, v19
	v_mul_f32_e32 v3, v3, v17
	v_add_f32_e32 v17, 1.0, v18
	v_rcp_f32_e32 v17, v17
	v_add_f32_e32 v18, 1.0, v19
	v_fmamk_f32 v19, v37, 0xbfb8aa3b, v148
	v_exp_f32_e32 v19, v19
	v_mul_f32_e32 v17, v17, v149
	v_exp_f32_e32 v36, v17
	v_add_f32_e32 v17, 1.0, v19
	v_rcp_f32_e32 v17, v17
	v_fmamk_f32 v19, v21, 0xbfb8aa3b, v93
	v_exp_f32_e32 v19, v19
	v_mul_f32_e32 v17, v17, v149
	v_exp_f32_e32 v37, v17
	v_fmamk_f32 v17, v38, 0xbfb8aa3b, v148
	v_exp_f32_e32 v17, v17
	v_fmamk_f32 v23, v23, 0xbfb8aa3b, v93
	v_add_f32_e32 v19, 1.0, v19
	v_fma_f32 v21, -v37, v37, 1.0
	v_add_f32_e32 v17, 1.0, v17
	v_rcp_f32_e32 v17, v17
	v_fma_f32 v20, -v36, v36, 1.0
	v_rcp_f32_e32 v19, v19
	v_mul_f32_e32 v17, v17, v149
	v_exp_f32_e32 v38, v17
	v_fmamk_f32 v17, v39, 0xbfb8aa3b, v148
	v_exp_f32_e32 v17, v17
	v_sqrt_f32_e32 v21, v21
	v_exp_f32_e32 v23, v23
	v_rcp_f32_e32 v18, v18
	v_add_f32_e32 v17, 1.0, v17
	v_rcp_f32_e32 v17, v17
	v_sqrt_f32_e32 v20, v20
	v_add_f32_e32 v23, 1.0, v23
	v_mul_f32_e32 v154, v19, v21
	v_mul_f32_e32 v17, v17, v149
	v_exp_f32_e32 v17, v17
	v_fmamk_f32 v19, v40, 0xbfb8aa3b, v148
	v_rcp_f32_e32 v23, v23
	v_mul_f32_e32 v153, v18, v20
	v_fma_f32 v151, -v17, v17, 1.0
	v_sqrt_f32_e32 v151, v151
	v_fmamk_f32 v20, v24, 0xbfb8aa3b, v93
	v_fmamk_f32 v22, v22, 0xbfb8aa3b, v93
	v_exp_f32_e32 v19, v19
	v_exp_f32_e32 v20, v20
	v_exp_f32_e32 v22, v22
	v_mul_f32_e32 v18, v23, v151
	v_mul_f32_e32 v7, v7, v18
	v_add_f32_e32 v18, 1.0, v19
	v_rcp_f32_e32 v18, v18
	v_add_f32_e32 v19, 1.0, v20
	v_fmamk_f32 v20, v41, 0xbfb8aa3b, v148
	v_add_f32_e32 v22, 1.0, v22
	v_fma_f32 v39, -v38, v38, 1.0
	v_rcp_f32_e32 v22, v22
	v_sqrt_f32_e32 v39, v39
	v_exp_f32_e32 v20, v20
	v_mul_f32_e32 v18, v18, v149
	v_mul_f32_e32 v21, v22, v39
	v_exp_f32_e32 v39, v18
	v_add_f32_e32 v18, 1.0, v20
	v_rcp_f32_e32 v18, v18
	v_fmamk_f32 v20, v25, 0xbfb8aa3b, v93
	v_exp_f32_e32 v20, v20
	v_mul_f32_e32 v18, v18, v149
	v_exp_f32_e32 v40, v18
	v_fmamk_f32 v18, v42, 0xbfb8aa3b, v148
	v_exp_f32_e32 v18, v18
	v_fmamk_f32 v24, v26, 0xbfb8aa3b, v93
	v_fmamk_f32 v26, v27, 0xbfb8aa3b, v93
	v_add_f32_e32 v20, 1.0, v20
	v_add_f32_e32 v18, 1.0, v18
	v_rcp_f32_e32 v18, v18
	v_fma_f32 v23, -v40, v40, 1.0
	v_fma_f32 v22, -v39, v39, 1.0
	v_mul_f32_e32 v18, v18, v149
	v_exp_f32_e32 v41, v18
	v_fmamk_f32 v18, v43, 0xbfb8aa3b, v148
	v_exp_f32_e32 v18, v18
	v_rcp_f32_e32 v20, v20
	v_sqrt_f32_e32 v23, v23
	v_exp_f32_e32 v26, v26
	v_add_f32_e32 v18, 1.0, v18
	v_rcp_f32_e32 v18, v18
	v_rcp_f32_e32 v19, v19
	v_sqrt_f32_e32 v22, v22
	v_add_f32_e32 v26, 1.0, v26
	v_mul_f32_e32 v18, v18, v149
	v_exp_f32_e32 v18, v18
	v_mul_f32_e32 v43, v20, v23
	v_fmamk_f32 v20, v44, 0xbfb8aa3b, v148
	v_rcp_f32_e32 v26, v26
	v_fma_f32 v27, -v18, v18, 1.0
	v_sqrt_f32_e32 v27, v27
	v_mul_f32_e32 v42, v19, v22
	v_fmamk_f32 v22, v28, 0xbfb8aa3b, v93
	v_exp_f32_e32 v20, v20
	v_exp_f32_e32 v22, v22
	v_mul_f32_e32 v19, v26, v27
	v_mul_f32_e32 v11, v11, v19
	v_add_f32_e32 v19, 1.0, v20
	v_rcp_f32_e32 v19, v19
	v_add_f32_e32 v20, 1.0, v22
	v_fmamk_f32 v22, v45, 0xbfb8aa3b, v148
	v_exp_f32_e32 v22, v22
	v_mul_f32_e32 v19, v19, v149
	v_exp_f32_e32 v44, v19
	v_add_f32_e32 v19, 1.0, v22
	v_rcp_f32_e32 v19, v19
	v_exp_f32_e32 v24, v24
	v_fmamk_f32 v22, v29, 0xbfb8aa3b, v93
	v_mul_f32_e32 v19, v19, v149
	v_exp_f32_e32 v45, v19
	v_fmamk_f32 v19, v46, 0xbfb8aa3b, v148
	v_exp_f32_e32 v19, v19
	v_add_f32_e32 v24, 1.0, v24
	v_fma_f32 v25, -v41, v41, 1.0
	v_add_f32_e32 v19, 1.0, v19
	v_rcp_f32_e32 v19, v19
	v_exp_f32_e32 v22, v22
	v_rcp_f32_e32 v24, v24
	v_sqrt_f32_e32 v25, v25
	v_mul_f32_e32 v19, v19, v149
	v_exp_f32_e32 v46, v19
	v_fmamk_f32 v19, v47, 0xbfb8aa3b, v148
	v_add_f32_e32 v22, 1.0, v22
	v_exp_f32_e32 v19, v19
	v_mul_f32_e32 v151, v24, v25
	v_rcp_f32_e32 v24, v22
	v_fma_f32 v22, -v45, v45, 1.0
	v_sqrt_f32_e32 v25, v22
	v_fmamk_f32 v22, v30, 0xbfb8aa3b, v93
	v_exp_f32_e32 v22, v22
	v_add_f32_e32 v19, 1.0, v19
	v_rcp_f32_e32 v19, v19
	v_fma_f32 v27, -v46, v46, 1.0
	v_add_f32_e32 v22, 1.0, v22
	v_rcp_f32_e32 v26, v22
	v_fmamk_f32 v22, v31, 0xbfb8aa3b, v93
	v_mul_f32_e32 v19, v19, v149
	v_exp_f32_e32 v28, v22
	v_exp_f32_e32 v22, v19
	v_sqrt_f32_e32 v19, v27
	v_fma_f32 v23, -v44, v44, 1.0
	v_add_f32_e32 v27, 1.0, v28
	v_fma_f32 v28, -v22, v22, 1.0
	v_rcp_f32_e32 v27, v27
	v_sqrt_f32_e32 v28, v28
	v_rcp_f32_e32 v20, v20
	v_sqrt_f32_e32 v23, v23
	v_mul_f32_e32 v148, v26, v19
	v_mul_f32_e32 v19, v27, v28
	v_fmac_f32_e32 v7, 0, v17
	v_mul_f32_e32 v15, v15, v19
	v_mul_f32_e32 v19, v38, v7
	v_fmac_f32_e32 v19, v6, v21
	v_fmac_f32_e32 v3, 0, v16
	v_mul_f32_e32 v21, v37, v19
	v_mul_f32_e32 v47, v20, v23
	v_mul_f32_e32 v20, v152, v3
	v_fmac_f32_e32 v21, v5, v154
	v_fmac_f32_e32 v15, 0, v22
	v_mul_f32_e32 v93, v24, v25
	v_fmac_f32_e32 v20, v2, v35
	v_mul_f32_e32 v24, v36, v21
	v_fmac_f32_e32 v11, 0, v18
	v_mul_f32_e32 v2, v46, v15
	v_fmac_f32_e32 v24, v4, v153
	v_mul_f32_e32 v4, v41, v11
	v_fmac_f32_e32 v2, v14, v148
	v_fmac_f32_e32 v4, v10, v151
	v_mul_f32_e32 v5, v45, v2
	v_mul_f32_e32 v23, v150, v20
	v_mul_f32_e32 v6, v40, v4
	v_fmac_f32_e32 v5, v13, v93
	v_fmac_f32_e32 v23, v1, v34
	v_fmac_f32_e32 v6, v9, v43
	v_mul_f32_e32 v14, v22, v46
	v_mul_f32_e32 v9, v44, v5
	v_mul_f32_e32 v25, v33, v23
	v_mul_f32_e32 v13, v45, v14
	v_fmac_f32_e32 v9, v12, v47
	v_fmac_f32_e32 v25, v0, v32
	v_mul_f32_e32 v12, v44, v13
	ds_bpermute_b32 v0, v137, v9
	ds_bpermute_b32 v35, v137, v12
	v_mul_f32_e32 v28, v18, v41
	v_mul_f32_e32 v26, v16, v152
	v_mul_f32_e32 v27, v17, v38
	v_mul_f32_e32 v31, v40, v28
	v_mul_f32_e32 v10, v39, v6
	v_mul_f32_e32 v29, v150, v26
	v_mul_f32_e32 v30, v37, v27
	v_fmac_f32_e32 v10, v8, v42
	v_mul_f32_e32 v34, v39, v31
	v_mul_f32_e32 v32, v33, v29
	v_mul_f32_e32 v33, v36, v30
	s_waitcnt lgkmcnt(1)
	v_cndmask_b32_e64 v36, v0, v9, s[4:5]
	v_cndmask_b32_e64 v37, v9, v0, s[4:5]
	ds_bpermute_b32 v0, v137, v34
	ds_bpermute_b32 v40, v137, v10
	s_waitcnt lgkmcnt(2)
	v_cndmask_b32_e64 v8, v12, v35, s[4:5]
	v_fmac_f32_e32 v37, 0, v8
	ds_bpermute_b32 v8, v137, v33
	v_cndmask_b32_e64 v1, v35, v12, s[4:5]
	v_mul_f32_e32 v38, v12, v35
	v_fmac_f32_e32 v36, v1, v37
	s_waitcnt lgkmcnt(2)
	v_cndmask_b32_e64 v1, v0, v34, s[4:5]
	s_waitcnt lgkmcnt(1)
	v_cndmask_b32_e64 v39, v40, v10, s[4:5]
	v_cndmask_b32_e64 v0, v34, v0, s[4:5]
	v_cndmask_b32_e64 v40, v10, v40, s[4:5]
	ds_bpermute_b32 v44, v137, v24
	v_mul_f32_e32 v41, v38, v0
	v_fmac_f32_e32 v40, v0, v36
	v_mul_f32_e32 v42, v1, v41
	v_fmac_f32_e32 v39, v1, v40
	s_waitcnt lgkmcnt(1)
	v_cndmask_b32_e64 v0, v8, v33, s[4:5]
	v_cndmask_b32_e64 v1, v33, v8, s[4:5]
	ds_bpermute_b32 v8, v137, v32
	ds_bpermute_b32 v47, v137, v25
	s_waitcnt lgkmcnt(2)
	v_cndmask_b32_e64 v43, v44, v24, s[4:5]
	v_cndmask_b32_e64 v44, v24, v44, s[4:5]
	v_mul_f32_e32 v45, v1, v42
	v_fmac_f32_e32 v44, v1, v39
	v_mul_f32_e32 v46, v0, v45
	v_fmac_f32_e32 v43, v0, v44
	s_waitcnt lgkmcnt(1)
	v_cndmask_b32_e64 v0, v32, v8, s[4:5]
	s_waitcnt lgkmcnt(0)
	v_cndmask_b32_e64 v47, v25, v47, s[4:5]
	v_mul_f32_e32 v93, v0, v46
	v_fmac_f32_e32 v47, v0, v43
	s_and_saveexec_b64 s[8:9], s[4:5]
	v_mul_f32_e32 v0, v32, v93
	v_fma_f32 v1, v32, v47, v25
	ds_write_b64 v136, v[0:1] offset:2048
	s_or_b64 exec, exec, s[8:9]
	v_cndmask_b32_e64 v0, 0, 1, s[14:15]
	v_cmp_ne_u32_e64 s[8:9], 1, v0
	s_andn2_b64 vcc, exec, s[14:15]
	s_waitcnt lgkmcnt(0)
	s_barrier
	s_cbranch_vccnz .LBB0_277
	v_add3_u32 v148, v140, v91, s93
	v_mov_b32_e32 v8, 1.0
	v_mov_b32_e32 v1, 0
	s_mov_b32 s12, 7

.LBB0_280:
	s_or_b64 exec, exec, s[12:13]
	s_setprio 1
	ds_read_b128 v[0:3], v145 offset:32768
	ds_read_b128 v[4:7], v147 offset:32768
	v_add_u32_e32 v8, 0x8000, v147
	s_waitcnt lgkmcnt(1)
	v_mfma_f32_32x32x16_bf16 v[32:47], v[48:51], v[0:3], 0
	v_add_u32_e32 v0, 0x8000, v145
	ds_read_b128 v[0:3], v0 offset:32768
	ds_read_b128 v[8:11], v8 offset:32768
	s_waitcnt lgkmcnt(1)
	v_mfma_f32_32x32x16_bf16 v[16:31], v[48:51], v[0:3], 0
	v_mfma_f32_32x32x16_bf16 v[32:47], v[52:55], v[4:7], v[32:47]
	ds_read_b128 v[0:3], v142 offset:32768
	ds_read_b128 v[4:7], v146 offset:32768
	s_waitcnt lgkmcnt(2)
	v_mfma_f32_32x32x16_bf16 v[16:31], v[52:55], v[8:11], v[16:31]
	v_add_u32_e32 v8, 0x8000, v146
	ds_read_b128 v[8:11], v8 offset:32768
	s_waitcnt lgkmcnt(2)
	v_mfma_f32_32x32x16_bf16 v[32:47], v[56:59], v[0:3], v[32:47]
	v_add_u32_e32 v0, 0x8000, v142
	ds_read_b128 v[0:3], v0 offset:32768
	s_waitcnt lgkmcnt(0)
	v_mfma_f32_32x32x16_bf16 v[16:31], v[56:59], v[0:3], v[16:31]
	v_mfma_f32_32x32x16_bf16 v[32:47], v[60:63], v[4:7], v[32:47]
	ds_read_b128 v[0:3], v141 offset:32768
	ds_read_b128 v[4:7], v144 offset:32768
	v_mfma_f32_32x32x16_bf16 v[16:31], v[60:63], v[8:11], v[16:31]
	v_add_u32_e32 v8, 0x8000, v144
	ds_read_b128 v[8:11], v8 offset:32768
	s_waitcnt lgkmcnt(2)
	v_mfma_f32_32x32x16_bf16 v[32:47], v[64:67], v[0:3], v[32:47]
	v_add_u32_e32 v0, 0x8000, v141
	ds_read_b128 v[0:3], v0 offset:32768
	s_waitcnt lgkmcnt(0)
	v_mfma_f32_32x32x16_bf16 v[16:31], v[64:67], v[0:3], v[16:31]
	v_mfma_f32_32x32x16_bf16 v[32:47], v[68:71], v[4:7], v[32:47]
	ds_read_b128 v[0:3], v139 offset:32768
	ds_read_b128 v[4:7], v143 offset:32768
	v_mfma_f32_32x32x16_bf16 v[16:31], v[68:71], v[8:11], v[16:31]
	v_add_u32_e32 v8, 0x8000, v143
	ds_read_b128 v[8:11], v8 offset:32768
	s_waitcnt lgkmcnt(2)
	v_mfma_f32_32x32x16_bf16 v[32:47], v[72:75], v[0:3], v[32:47]
	v_add_u32_e32 v0, 0x8000, v139
	ds_read_b128 v[0:3], v0 offset:32768
	s_waitcnt lgkmcnt(0)
	v_mfma_f32_32x32x16_bf16 v[16:31], v[72:75], v[0:3], v[16:31]
	v_mfma_f32_32x32x16_bf16 v[32:47], v[76:79], v[4:7], v[32:47]
	v_mfma_f32_32x32x16_bf16 v[16:31], v[76:79], v[8:11], v[16:31]
	v_mfma_f32_32x32x16_bf16 v[0:15], v[64:67], v[80:83], 0
	v_mfma_f32_32x32x16_bf16 v[0:15], v[68:71], v[84:87], v[0:15]
	s_setprio 0
	v_lshl_or_b32 v93, v138, 2, v134
	s_waitcnt vmcnt(16)
	ds_read_b32 v251, v167 offset:256
	v_mul_f32_e32 v148, 0xbfb8aa3b, v173
	v_mul_f32_e32 v93, 0xbfb8aa3b, v174
	v_fmamk_f32 v32, v32, 0xbfb8aa3b, v148
	v_fmamk_f32 v16, v16, 0xbfb8aa3b, v93
	v_exp_f32_e32 v32, v32
	v_exp_f32_e32 v150, v16
	v_fmamk_f32 v17, v17, 0xbfb8aa3b, v93
	v_exp_f32_e32 v151, v17
	v_add_f32_e32 v32, 1.0, v32
	v_add_f32_e32 v150, 1.0, v150
	v_rcp_f32_e32 v17, v32
	v_rcp_f32_e32 v32, v150
	v_fmamk_f32 v33, v33, 0xbfb8aa3b, v148
	v_fmamk_f32 v34, v34, 0xbfb8aa3b, v148
	v_exp_f32_e32 v33, v33
	v_exp_f32_e32 v34, v34
	v_add_f32_e32 v33, 1.0, v33
	v_add_f32_e32 v34, 1.0, v34
	v_rcp_f32_e32 v33, v33
	v_rcp_f32_e32 v34, v34
	v_fmamk_f32 v18, v18, 0xbfb8aa3b, v93
	v_fmamk_f32 v19, v19, 0xbfb8aa3b, v93
	v_exp_f32_e32 v18, v18
	s_waitcnt lgkmcnt(0)
	v_mul_f32_e32 v149, 0x3fb8aa3b, v251
	v_mul_f32_e32 v16, v17, v149
	v_mul_f32_e32 v17, v33, v149
	v_exp_f32_e32 v33, v16
	v_mul_f32_e32 v16, v34, v149
	v_exp_f32_e32 v152, v16
	v_fmamk_f32 v16, v35, 0xbfb8aa3b, v148
	v_exp_f32_e32 v16, v16
	v_exp_f32_e32 v150, v17
	v_add_f32_e32 v16, 1.0, v16
	v_rcp_f32_e32 v16, v16
	v_exp_f32_e32 v19, v19
	v_add_f32_e32 v151, 1.0, v151
	v_add_f32_e32 v18, 1.0, v18
	v_mul_f32_e32 v16, v16, v149
	v_exp_f32_e32 v16, v16
	v_fma_f32 v35, -v152, v152, 1.0
	v_rcp_f32_e32 v17, v151
	v_fma_f32 v34, -v33, v33, 1.0
	v_fma_f32 v151, -v150, v150, 1.0
	v_rcp_f32_e32 v18, v18
	v_sqrt_f32_e32 v35, v35
	v_add_f32_e32 v19, 1.0, v19
	v_fma_f32 v153, -v16, v16, 1.0
	v_sqrt_f32_e32 v34, v34
	v_sqrt_f32_e32 v151, v151
	v_rcp_f32_e32 v19, v19
	v_sqrt_f32_e32 v153, v153
	v_mul_f32_e32 v35, v18, v35
	v_fmamk_f32 v18, v36, 0xbfb8aa3b, v148
	v_mul_f32_e32 v32, v32, v34
	v_mul_f32_e32 v34, v17, v151
	v_mul_f32_e32 v17, v19, v153
	v_fmamk_f32 v19, v20, 0xbfb8aa3b, v93
	v_exp_f32_e32 v18, v18
	v_exp_f32_e32 v19, v19
	v_mul_f32_e32 v3, v3, v17
	v_add_f32_e32 v17, 1.0, v18
	v_rcp_f32_e32 v17, v17
	v_add_f32_e32 v18, 1.0, v19
	v_fmamk_f32 v19, v37, 0xbfb8aa3b, v148
	v_exp_f32_e32 v19, v19
	v_mul_f32_e32 v17, v17, v149
	v_exp_f32_e32 v36, v17
	v_add_f32_e32 v17, 1.0, v19
	v_rcp_f32_e32 v17, v17
	v_fmamk_f32 v19, v21, 0xbfb8aa3b, v93
	v_exp_f32_e32 v19, v19
	v_mul_f32_e32 v17, v17, v149
	v_exp_f32_e32 v37, v17
	v_fmamk_f32 v17, v38, 0xbfb8aa3b, v148
	v_exp_f32_e32 v17, v17
	v_fmamk_f32 v23, v23, 0xbfb8aa3b, v93
	v_add_f32_e32 v19, 1.0, v19
	v_fma_f32 v21, -v37, v37, 1.0
	v_add_f32_e32 v17, 1.0, v17
	v_rcp_f32_e32 v17, v17
	v_fma_f32 v20, -v36, v36, 1.0
	v_rcp_f32_e32 v19, v19
	v_mul_f32_e32 v17, v17, v149
	v_exp_f32_e32 v38, v17
	v_fmamk_f32 v17, v39, 0xbfb8aa3b, v148
	v_exp_f32_e32 v17, v17
	v_sqrt_f32_e32 v21, v21
	v_exp_f32_e32 v23, v23
	v_rcp_f32_e32 v18, v18
	v_add_f32_e32 v17, 1.0, v17
	v_rcp_f32_e32 v17, v17
	v_sqrt_f32_e32 v20, v20
	v_add_f32_e32 v23, 1.0, v23
	v_mul_f32_e32 v154, v19, v21
	v_mul_f32_e32 v17, v17, v149
	v_exp_f32_e32 v17, v17
	v_fmamk_f32 v19, v40, 0xbfb8aa3b, v148
	v_rcp_f32_e32 v23, v23
	v_mul_f32_e32 v153, v18, v20
	v_fma_f32 v151, -v17, v17, 1.0
	v_sqrt_f32_e32 v151, v151
	v_fmamk_f32 v20, v24, 0xbfb8aa3b, v93
	v_fmamk_f32 v22, v22, 0xbfb8aa3b, v93
	v_exp_f32_e32 v19, v19
	v_exp_f32_e32 v20, v20
	v_exp_f32_e32 v22, v22
	v_mul_f32_e32 v18, v23, v151
	v_mul_f32_e32 v7, v7, v18
	v_add_f32_e32 v18, 1.0, v19
	v_rcp_f32_e32 v18, v18
	v_add_f32_e32 v19, 1.0, v20
	v_fmamk_f32 v20, v41, 0xbfb8aa3b, v148
	v_add_f32_e32 v22, 1.0, v22
	v_fma_f32 v39, -v38, v38, 1.0
	v_rcp_f32_e32 v22, v22
	v_sqrt_f32_e32 v39, v39
	v_exp_f32_e32 v20, v20
	v_mul_f32_e32 v18, v18, v149
	v_mul_f32_e32 v21, v22, v39
	v_exp_f32_e32 v39, v18
	v_add_f32_e32 v18, 1.0, v20
	v_rcp_f32_e32 v18, v18
	v_fmamk_f32 v20, v25, 0xbfb8aa3b, v93
	v_exp_f32_e32 v20, v20
	v_mul_f32_e32 v18, v18, v149
	v_exp_f32_e32 v40, v18
	v_fmamk_f32 v18, v42, 0xbfb8aa3b, v148
	v_exp_f32_e32 v18, v18
	v_fmamk_f32 v24, v26, 0xbfb8aa3b, v93
	v_fmamk_f32 v26, v27, 0xbfb8aa3b, v93
	v_add_f32_e32 v20, 1.0, v20
	v_add_f32_e32 v18, 1.0, v18
	v_rcp_f32_e32 v18, v18
	v_fma_f32 v23, -v40, v40, 1.0
	v_fma_f32 v22, -v39, v39, 1.0
	v_mul_f32_e32 v18, v18, v149
	v_exp_f32_e32 v41, v18
	v_fmamk_f32 v18, v43, 0xbfb8aa3b, v148
	v_exp_f32_e32 v18, v18
	v_rcp_f32_e32 v20, v20
	v_sqrt_f32_e32 v23, v23
	v_exp_f32_e32 v26, v26
	v_add_f32_e32 v18, 1.0, v18
	v_rcp_f32_e32 v18, v18
	v_rcp_f32_e32 v19, v19
	v_sqrt_f32_e32 v22, v22
	v_add_f32_e32 v26, 1.0, v26
	v_mul_f32_e32 v18, v18, v149
	v_exp_f32_e32 v18, v18
	v_mul_f32_e32 v43, v20, v23
	v_fmamk_f32 v20, v44, 0xbfb8aa3b, v148
	v_rcp_f32_e32 v26, v26
	v_fma_f32 v27, -v18, v18, 1.0
	v_sqrt_f32_e32 v27, v27
	v_mul_f32_e32 v42, v19, v22
	v_fmamk_f32 v22, v28, 0xbfb8aa3b, v93
	v_exp_f32_e32 v20, v20
	v_exp_f32_e32 v22, v22
	v_mul_f32_e32 v19, v26, v27
	v_mul_f32_e32 v11, v11, v19
	v_add_f32_e32 v19, 1.0, v20
	v_rcp_f32_e32 v19, v19
	v_add_f32_e32 v20, 1.0, v22
	v_fmamk_f32 v22, v45, 0xbfb8aa3b, v148
	v_exp_f32_e32 v22, v22
	v_mul_f32_e32 v19, v19, v149
	v_exp_f32_e32 v44, v19
	v_add_f32_e32 v19, 1.0, v22
	v_rcp_f32_e32 v19, v19
	v_exp_f32_e32 v24, v24
	v_fmamk_f32 v22, v29, 0xbfb8aa3b, v93
	v_mul_f32_e32 v19, v19, v149
	v_exp_f32_e32 v45, v19
	v_fmamk_f32 v19, v46, 0xbfb8aa3b, v148
	v_exp_f32_e32 v19, v19
	v_add_f32_e32 v24, 1.0, v24
	v_fma_f32 v25, -v41, v41, 1.0
	v_add_f32_e32 v19, 1.0, v19
	v_rcp_f32_e32 v19, v19
	v_exp_f32_e32 v22, v22
	v_rcp_f32_e32 v24, v24
	v_sqrt_f32_e32 v25, v25
	v_mul_f32_e32 v19, v19, v149
	v_exp_f32_e32 v46, v19
	v_fmamk_f32 v19, v47, 0xbfb8aa3b, v148
	v_add_f32_e32 v22, 1.0, v22
	v_exp_f32_e32 v19, v19
	v_mul_f32_e32 v151, v24, v25
	v_rcp_f32_e32 v24, v22
	v_fma_f32 v22, -v45, v45, 1.0
	v_sqrt_f32_e32 v25, v22
	v_fmamk_f32 v22, v30, 0xbfb8aa3b, v93
	v_exp_f32_e32 v22, v22
	v_add_f32_e32 v19, 1.0, v19
	v_rcp_f32_e32 v19, v19
	v_fma_f32 v27, -v46, v46, 1.0
	v_add_f32_e32 v22, 1.0, v22
	v_rcp_f32_e32 v26, v22
	v_fmamk_f32 v22, v31, 0xbfb8aa3b, v93
	v_mul_f32_e32 v19, v19, v149
	v_exp_f32_e32 v28, v22
	v_exp_f32_e32 v22, v19
	v_sqrt_f32_e32 v19, v27
	v_fma_f32 v23, -v44, v44, 1.0
	v_add_f32_e32 v27, 1.0, v28
	v_fma_f32 v28, -v22, v22, 1.0
	v_rcp_f32_e32 v27, v27
	v_sqrt_f32_e32 v28, v28
	v_rcp_f32_e32 v20, v20
	v_sqrt_f32_e32 v23, v23
	v_mul_f32_e32 v148, v26, v19
	v_mul_f32_e32 v19, v27, v28
	v_fmac_f32_e32 v7, 0, v17
	v_mul_f32_e32 v15, v15, v19
	v_mul_f32_e32 v19, v38, v7
	v_fmac_f32_e32 v19, v6, v21
	v_fmac_f32_e32 v3, 0, v16
	v_mul_f32_e32 v21, v37, v19
	v_mul_f32_e32 v47, v20, v23
	v_mul_f32_e32 v20, v152, v3
	v_fmac_f32_e32 v21, v5, v154
	v_fmac_f32_e32 v15, 0, v22
	v_mul_f32_e32 v93, v24, v25
	v_fmac_f32_e32 v20, v2, v35
	v_mul_f32_e32 v24, v36, v21
	v_fmac_f32_e32 v11, 0, v18
	v_mul_f32_e32 v2, v46, v15
	v_fmac_f32_e32 v24, v4, v153
	v_mul_f32_e32 v4, v41, v11
	v_fmac_f32_e32 v2, v14, v148
	v_fmac_f32_e32 v4, v10, v151
	v_mul_f32_e32 v5, v45, v2
	v_mul_f32_e32 v23, v150, v20
	v_mul_f32_e32 v6, v40, v4
	v_fmac_f32_e32 v5, v13, v93
	v_fmac_f32_e32 v23, v1, v34
	v_fmac_f32_e32 v6, v9, v43
	v_mul_f32_e32 v14, v22, v46
	v_mul_f32_e32 v9, v44, v5
	v_mul_f32_e32 v25, v33, v23
	v_mul_f32_e32 v13, v45, v14
	v_fmac_f32_e32 v9, v12, v47
	v_fmac_f32_e32 v25, v0, v32
	v_mul_f32_e32 v12, v44, v13
	ds_bpermute_b32 v0, v137, v9
	ds_bpermute_b32 v35, v137, v12
	v_mul_f32_e32 v28, v18, v41
	v_mul_f32_e32 v26, v16, v152
	v_mul_f32_e32 v27, v17, v38
	v_mul_f32_e32 v31, v40, v28
	v_mul_f32_e32 v10, v39, v6
	v_mul_f32_e32 v29, v150, v26
	v_mul_f32_e32 v30, v37, v27
	v_fmac_f32_e32 v10, v8, v42
	v_mul_f32_e32 v34, v39, v31
	v_mul_f32_e32 v32, v33, v29
	v_mul_f32_e32 v33, v36, v30
	s_waitcnt lgkmcnt(1)
	v_cndmask_b32_e64 v36, v0, v9, s[4:5]
	v_cndmask_b32_e64 v37, v9, v0, s[4:5]
	ds_bpermute_b32 v0, v137, v34
	ds_bpermute_b32 v40, v137, v10
	s_waitcnt lgkmcnt(2)
	v_cndmask_b32_e64 v8, v12, v35, s[4:5]
	v_fmac_f32_e32 v37, 0, v8
	ds_bpermute_b32 v8, v137, v33
	v_cndmask_b32_e64 v1, v35, v12, s[4:5]
	v_mul_f32_e32 v38, v12, v35
	v_fmac_f32_e32 v36, v1, v37
	s_waitcnt lgkmcnt(2)
	v_cndmask_b32_e64 v1, v0, v34, s[4:5]
	s_waitcnt lgkmcnt(1)
	v_cndmask_b32_e64 v39, v40, v10, s[4:5]
	v_cndmask_b32_e64 v0, v34, v0, s[4:5]
	v_cndmask_b32_e64 v40, v10, v40, s[4:5]
	ds_bpermute_b32 v44, v137, v24
	v_mul_f32_e32 v41, v38, v0
	v_fmac_f32_e32 v40, v0, v36
	v_mul_f32_e32 v42, v1, v41
	v_fmac_f32_e32 v39, v1, v40
	s_waitcnt lgkmcnt(1)
	v_cndmask_b32_e64 v0, v8, v33, s[4:5]
	v_cndmask_b32_e64 v1, v33, v8, s[4:5]
	ds_bpermute_b32 v8, v137, v32
	ds_bpermute_b32 v47, v137, v25
	s_waitcnt lgkmcnt(2)
	v_cndmask_b32_e64 v43, v44, v24, s[4:5]
	v_cndmask_b32_e64 v44, v24, v44, s[4:5]
	v_mul_f32_e32 v45, v1, v42
	v_fmac_f32_e32 v44, v1, v39
	v_mul_f32_e32 v46, v0, v45
	v_fmac_f32_e32 v43, v0, v44
	s_waitcnt lgkmcnt(1)
	v_cndmask_b32_e64 v0, v32, v8, s[4:5]
	s_waitcnt lgkmcnt(0)
	v_cndmask_b32_e64 v47, v25, v47, s[4:5]
	v_mul_f32_e32 v93, v0, v46
	v_fmac_f32_e32 v47, v0, v43
	s_and_saveexec_b64 s[12:13], s[4:5]
	v_mul_f32_e32 v0, v32, v93
	v_fma_f32 v1, v32, v47, v25
	ds_write_b64 v136, v[0:1] offset:4096
	s_or_b64 exec, exec, s[12:13]
	s_and_b64 vcc, exec, s[8:9]
	s_waitcnt lgkmcnt(0)
	s_barrier
	s_cbranch_vccnz .LBB0_285
	v_add3_u32 v148, v140, v91, s94
	v_mov_b32_e32 v8, 1.0
	v_mov_b32_e32 v1, 0
	s_mov_b32 s12, 7

.LBB0_288:
	s_or_b64 exec, exec, s[12:13]
	s_setprio 1
	ds_read_b128 v[0:3], v145 offset:40960
	ds_read_b128 v[4:7], v147 offset:40960
	v_add_u32_e32 v8, 0xa000, v147
	s_waitcnt lgkmcnt(1)
	v_mfma_f32_32x32x16_bf16 v[32:47], v[48:51], v[0:3], 0
	v_add_u32_e32 v0, 0xa000, v145
	ds_read_b128 v[0:3], v0 offset:32768
	ds_read_b128 v[8:11], v8 offset:32768
	s_waitcnt lgkmcnt(1)
	v_mfma_f32_32x32x16_bf16 v[16:31], v[48:51], v[0:3], 0
	v_mfma_f32_32x32x16_bf16 v[32:47], v[52:55], v[4:7], v[32:47]
	ds_read_b128 v[0:3], v142 offset:40960
	ds_read_b128 v[4:7], v146 offset:40960
	s_waitcnt lgkmcnt(2)
	v_mfma_f32_32x32x16_bf16 v[16:31], v[52:55], v[8:11], v[16:31]
	v_add_u32_e32 v8, 0xa000, v146
	ds_read_b128 v[8:11], v8 offset:32768
	s_waitcnt lgkmcnt(2)
	v_mfma_f32_32x32x16_bf16 v[32:47], v[56:59], v[0:3], v[32:47]
	v_add_u32_e32 v0, 0xa000, v142
	ds_read_b128 v[0:3], v0 offset:32768
	s_waitcnt lgkmcnt(0)
	v_mfma_f32_32x32x16_bf16 v[16:31], v[56:59], v[0:3], v[16:31]
	v_mfma_f32_32x32x16_bf16 v[32:47], v[60:63], v[4:7], v[32:47]
	ds_read_b128 v[0:3], v141 offset:40960
	ds_read_b128 v[4:7], v144 offset:40960
	v_mfma_f32_32x32x16_bf16 v[16:31], v[60:63], v[8:11], v[16:31]
	v_add_u32_e32 v8, 0xa000, v144
	ds_read_b128 v[8:11], v8 offset:32768
	s_waitcnt lgkmcnt(2)
	v_mfma_f32_32x32x16_bf16 v[32:47], v[64:67], v[0:3], v[32:47]
	v_add_u32_e32 v0, 0xa000, v141
	ds_read_b128 v[0:3], v0 offset:32768
	s_waitcnt lgkmcnt(0)
	v_mfma_f32_32x32x16_bf16 v[16:31], v[64:67], v[0:3], v[16:31]
	v_mfma_f32_32x32x16_bf16 v[32:47], v[68:71], v[4:7], v[32:47]
	ds_read_b128 v[0:3], v139 offset:40960
	ds_read_b128 v[4:7], v143 offset:40960
	v_mfma_f32_32x32x16_bf16 v[16:31], v[68:71], v[8:11], v[16:31]
	v_add_u32_e32 v8, 0xa000, v143
	ds_read_b128 v[8:11], v8 offset:32768
	s_waitcnt lgkmcnt(2)
	v_mfma_f32_32x32x16_bf16 v[32:47], v[72:75], v[0:3], v[32:47]
	v_add_u32_e32 v0, 0xa000, v139
	ds_read_b128 v[0:3], v0 offset:32768
	s_waitcnt lgkmcnt(0)
	v_mfma_f32_32x32x16_bf16 v[16:31], v[72:75], v[0:3], v[16:31]
	v_mfma_f32_32x32x16_bf16 v[32:47], v[76:79], v[4:7], v[32:47]
	v_mfma_f32_32x32x16_bf16 v[16:31], v[76:79], v[8:11], v[16:31]
	v_mfma_f32_32x32x16_bf16 v[0:15], v[72:75], v[80:83], 0
	v_mfma_f32_32x32x16_bf16 v[0:15], v[76:79], v[84:87], v[0:15]
	s_setprio 0
	v_lshl_or_b32 v48, v138, 2, v135
	s_waitcnt vmcnt(16)
	ds_read_b32 v251, v167 offset:384
	v_mul_f32_e32 v49, 0xbfb8aa3b, v173
	v_mul_f32_e32 v48, 0xbfb8aa3b, v174
	v_fmamk_f32 v32, v32, 0xbfb8aa3b, v49
	v_fmamk_f32 v16, v16, 0xbfb8aa3b, v48
	v_exp_f32_e32 v32, v32
	v_exp_f32_e32 v51, v16
	v_fmamk_f32 v17, v17, 0xbfb8aa3b, v48
	v_exp_f32_e32 v52, v17
	v_add_f32_e32 v32, 1.0, v32
	v_add_f32_e32 v51, 1.0, v51
	v_rcp_f32_e32 v17, v32
	v_rcp_f32_e32 v32, v51
	v_fmamk_f32 v33, v33, 0xbfb8aa3b, v49
	v_fmamk_f32 v34, v34, 0xbfb8aa3b, v49
	v_exp_f32_e32 v33, v33
	v_exp_f32_e32 v34, v34
	v_add_f32_e32 v33, 1.0, v33
	v_add_f32_e32 v34, 1.0, v34
	v_rcp_f32_e32 v33, v33
	v_rcp_f32_e32 v34, v34
	v_fmamk_f32 v18, v18, 0xbfb8aa3b, v48
	v_fmamk_f32 v19, v19, 0xbfb8aa3b, v48
	v_exp_f32_e32 v18, v18
	s_waitcnt lgkmcnt(0)
	v_mul_f32_e32 v50, 0x3fb8aa3b, v251
	v_mul_f32_e32 v16, v17, v50
	v_mul_f32_e32 v17, v33, v50
	v_exp_f32_e32 v33, v16
	v_mul_f32_e32 v16, v34, v50
	v_exp_f32_e32 v53, v16
	v_fmamk_f32 v16, v35, 0xbfb8aa3b, v49
	v_exp_f32_e32 v16, v16
	v_exp_f32_e32 v51, v17
	v_add_f32_e32 v16, 1.0, v16
	v_rcp_f32_e32 v16, v16
	v_exp_f32_e32 v19, v19
	v_add_f32_e32 v52, 1.0, v52
	v_add_f32_e32 v18, 1.0, v18
	v_mul_f32_e32 v16, v16, v50
	v_exp_f32_e32 v16, v16
	v_fma_f32 v35, -v53, v53, 1.0
	v_rcp_f32_e32 v17, v52
	v_fma_f32 v34, -v33, v33, 1.0
	v_fma_f32 v52, -v51, v51, 1.0
	v_rcp_f32_e32 v18, v18
	v_sqrt_f32_e32 v35, v35
	v_add_f32_e32 v19, 1.0, v19
	v_fma_f32 v54, -v16, v16, 1.0
	v_sqrt_f32_e32 v34, v34
	v_sqrt_f32_e32 v52, v52
	v_rcp_f32_e32 v19, v19
	v_sqrt_f32_e32 v54, v54
	v_mul_f32_e32 v35, v18, v35
	v_fmamk_f32 v18, v36, 0xbfb8aa3b, v49
	v_mul_f32_e32 v32, v32, v34
	v_mul_f32_e32 v34, v17, v52
	v_mul_f32_e32 v17, v19, v54
	v_fmamk_f32 v19, v20, 0xbfb8aa3b, v48
	v_exp_f32_e32 v18, v18
	v_exp_f32_e32 v19, v19
	v_mul_f32_e32 v3, v3, v17
	v_add_f32_e32 v17, 1.0, v18
	v_rcp_f32_e32 v17, v17
	v_add_f32_e32 v18, 1.0, v19
	v_fmamk_f32 v19, v37, 0xbfb8aa3b, v49
	v_exp_f32_e32 v19, v19
	v_mul_f32_e32 v17, v17, v50
	v_exp_f32_e32 v36, v17
	v_add_f32_e32 v17, 1.0, v19
	v_rcp_f32_e32 v17, v17
	v_fmamk_f32 v19, v21, 0xbfb8aa3b, v48
	v_exp_f32_e32 v19, v19
	v_mul_f32_e32 v17, v17, v50
	v_exp_f32_e32 v37, v17
	v_fmamk_f32 v17, v38, 0xbfb8aa3b, v49
	v_exp_f32_e32 v17, v17
	v_fmamk_f32 v23, v23, 0xbfb8aa3b, v48
	v_add_f32_e32 v19, 1.0, v19
	v_fma_f32 v21, -v37, v37, 1.0
	v_add_f32_e32 v17, 1.0, v17
	v_rcp_f32_e32 v17, v17
	v_fma_f32 v20, -v36, v36, 1.0
	v_rcp_f32_e32 v19, v19
	v_mul_f32_e32 v17, v17, v50
	v_exp_f32_e32 v38, v17
	v_fmamk_f32 v17, v39, 0xbfb8aa3b, v49
	v_exp_f32_e32 v17, v17
	v_sqrt_f32_e32 v21, v21
	v_exp_f32_e32 v23, v23
	v_rcp_f32_e32 v18, v18
	v_add_f32_e32 v17, 1.0, v17
	v_rcp_f32_e32 v17, v17
	v_sqrt_f32_e32 v20, v20
	v_add_f32_e32 v23, 1.0, v23
	v_mul_f32_e32 v55, v19, v21
	v_mul_f32_e32 v17, v17, v50
	v_exp_f32_e32 v17, v17
	v_fmamk_f32 v19, v40, 0xbfb8aa3b, v49
	v_rcp_f32_e32 v23, v23
	v_mul_f32_e32 v54, v18, v20
	v_fma_f32 v52, -v17, v17, 1.0
	v_sqrt_f32_e32 v52, v52
	v_fmamk_f32 v20, v24, 0xbfb8aa3b, v48
	v_fmamk_f32 v22, v22, 0xbfb8aa3b, v48
	v_exp_f32_e32 v19, v19
	v_exp_f32_e32 v20, v20
	v_exp_f32_e32 v22, v22
	v_mul_f32_e32 v18, v23, v52
	v_mul_f32_e32 v7, v7, v18
	v_add_f32_e32 v18, 1.0, v19
	v_rcp_f32_e32 v18, v18
	v_add_f32_e32 v19, 1.0, v20
	v_fmamk_f32 v20, v41, 0xbfb8aa3b, v49
	v_add_f32_e32 v22, 1.0, v22
	v_fma_f32 v39, -v38, v38, 1.0
	v_rcp_f32_e32 v22, v22
	v_sqrt_f32_e32 v39, v39
	v_exp_f32_e32 v20, v20
	v_mul_f32_e32 v18, v18, v50
	v_mul_f32_e32 v21, v22, v39
	v_exp_f32_e32 v39, v18
	v_add_f32_e32 v18, 1.0, v20
	v_rcp_f32_e32 v18, v18
	v_fmamk_f32 v20, v25, 0xbfb8aa3b, v48
	v_exp_f32_e32 v20, v20
	v_mul_f32_e32 v18, v18, v50
	v_exp_f32_e32 v40, v18
	v_fmamk_f32 v18, v42, 0xbfb8aa3b, v49
	v_exp_f32_e32 v18, v18
	v_fmamk_f32 v24, v26, 0xbfb8aa3b, v48
	v_fmamk_f32 v26, v27, 0xbfb8aa3b, v48
	v_add_f32_e32 v20, 1.0, v20
	v_add_f32_e32 v18, 1.0, v18
	v_rcp_f32_e32 v18, v18
	v_fma_f32 v23, -v40, v40, 1.0
	v_fma_f32 v22, -v39, v39, 1.0
	v_mul_f32_e32 v18, v18, v50
	v_exp_f32_e32 v41, v18
	v_fmamk_f32 v18, v43, 0xbfb8aa3b, v49
	v_exp_f32_e32 v18, v18
	v_rcp_f32_e32 v20, v20
	v_sqrt_f32_e32 v23, v23
	v_exp_f32_e32 v26, v26
	v_add_f32_e32 v18, 1.0, v18
	v_rcp_f32_e32 v18, v18
	v_rcp_f32_e32 v19, v19
	v_sqrt_f32_e32 v22, v22
	v_add_f32_e32 v26, 1.0, v26
	v_mul_f32_e32 v18, v18, v50
	v_exp_f32_e32 v18, v18
	v_mul_f32_e32 v43, v20, v23
	v_fmamk_f32 v20, v44, 0xbfb8aa3b, v49
	v_rcp_f32_e32 v26, v26
	v_fma_f32 v27, -v18, v18, 1.0
	v_sqrt_f32_e32 v27, v27
	v_mul_f32_e32 v42, v19, v22
	v_fmamk_f32 v22, v28, 0xbfb8aa3b, v48
	v_exp_f32_e32 v20, v20
	v_exp_f32_e32 v22, v22
	v_mul_f32_e32 v19, v26, v27
	v_mul_f32_e32 v11, v11, v19
	v_add_f32_e32 v19, 1.0, v20
	v_rcp_f32_e32 v19, v19
	v_add_f32_e32 v20, 1.0, v22
	v_fmamk_f32 v22, v45, 0xbfb8aa3b, v49
	v_exp_f32_e32 v22, v22
	v_mul_f32_e32 v19, v19, v50
	v_exp_f32_e32 v44, v19
	v_add_f32_e32 v19, 1.0, v22
	v_rcp_f32_e32 v19, v19
	v_exp_f32_e32 v24, v24
	v_fmamk_f32 v22, v29, 0xbfb8aa3b, v48
	v_mul_f32_e32 v19, v19, v50
	v_exp_f32_e32 v45, v19
	v_fmamk_f32 v19, v46, 0xbfb8aa3b, v49
	v_exp_f32_e32 v19, v19
	v_add_f32_e32 v24, 1.0, v24
	v_fma_f32 v25, -v41, v41, 1.0
	v_add_f32_e32 v19, 1.0, v19
	v_rcp_f32_e32 v19, v19
	v_exp_f32_e32 v22, v22
	v_rcp_f32_e32 v24, v24
	v_sqrt_f32_e32 v25, v25
	v_mul_f32_e32 v19, v19, v50
	v_exp_f32_e32 v46, v19
	v_fmamk_f32 v19, v47, 0xbfb8aa3b, v49
	v_add_f32_e32 v22, 1.0, v22
	v_exp_f32_e32 v19, v19
	v_mul_f32_e32 v52, v24, v25
	v_rcp_f32_e32 v24, v22
	v_fma_f32 v22, -v45, v45, 1.0
	v_sqrt_f32_e32 v25, v22
	v_fmamk_f32 v22, v30, 0xbfb8aa3b, v48
	v_exp_f32_e32 v22, v22
	v_add_f32_e32 v19, 1.0, v19
	v_rcp_f32_e32 v19, v19
	v_fma_f32 v27, -v46, v46, 1.0
	v_add_f32_e32 v22, 1.0, v22
	v_rcp_f32_e32 v26, v22
	v_fmamk_f32 v22, v31, 0xbfb8aa3b, v48
	v_mul_f32_e32 v19, v19, v50
	v_exp_f32_e32 v28, v22
	v_exp_f32_e32 v22, v19
	v_sqrt_f32_e32 v19, v27
	v_fma_f32 v23, -v44, v44, 1.0
	v_add_f32_e32 v27, 1.0, v28
	v_fma_f32 v28, -v22, v22, 1.0
	v_rcp_f32_e32 v27, v27
	v_sqrt_f32_e32 v28, v28
	v_rcp_f32_e32 v20, v20
	v_sqrt_f32_e32 v23, v23
	v_mul_f32_e32 v49, v26, v19
	v_mul_f32_e32 v19, v27, v28
	v_fmac_f32_e32 v7, 0, v17
	v_mul_f32_e32 v15, v15, v19
	v_mul_f32_e32 v19, v38, v7
	v_fmac_f32_e32 v19, v6, v21
	v_fmac_f32_e32 v3, 0, v16
	v_mul_f32_e32 v21, v37, v19
	v_mul_f32_e32 v47, v20, v23
	v_mul_f32_e32 v20, v53, v3
	v_fmac_f32_e32 v21, v5, v55
	v_fmac_f32_e32 v15, 0, v22
	v_mul_f32_e32 v48, v24, v25
	v_fmac_f32_e32 v20, v2, v35
	v_mul_f32_e32 v24, v36, v21
	v_fmac_f32_e32 v11, 0, v18
	v_mul_f32_e32 v2, v46, v15
	v_fmac_f32_e32 v24, v4, v54
	v_mul_f32_e32 v4, v41, v11
	v_fmac_f32_e32 v2, v14, v49
	v_fmac_f32_e32 v4, v10, v52
	v_mul_f32_e32 v5, v45, v2
	v_mul_f32_e32 v23, v51, v20
	v_mul_f32_e32 v6, v40, v4
	v_fmac_f32_e32 v5, v13, v48
	v_fmac_f32_e32 v23, v1, v34
	v_fmac_f32_e32 v6, v9, v43
	v_mul_f32_e32 v14, v22, v46
	v_mul_f32_e32 v9, v44, v5
	v_mul_f32_e32 v25, v33, v23
	v_mul_f32_e32 v13, v45, v14
	v_fmac_f32_e32 v9, v12, v47
	v_fmac_f32_e32 v25, v0, v32
	v_mul_f32_e32 v12, v44, v13
	ds_bpermute_b32 v0, v137, v9
	ds_bpermute_b32 v35, v137, v12
	v_mul_f32_e32 v28, v18, v41
	v_mul_f32_e32 v26, v16, v53
	v_mul_f32_e32 v27, v17, v38
	v_mul_f32_e32 v31, v40, v28
	v_mul_f32_e32 v10, v39, v6
	v_mul_f32_e32 v29, v51, v26
	v_mul_f32_e32 v30, v37, v27
	v_fmac_f32_e32 v10, v8, v42
	v_mul_f32_e32 v34, v39, v31
	v_mul_f32_e32 v32, v33, v29
	v_mul_f32_e32 v33, v36, v30
	s_waitcnt lgkmcnt(1)
	v_cndmask_b32_e64 v36, v0, v9, s[4:5]
	v_cndmask_b32_e64 v37, v9, v0, s[4:5]
	ds_bpermute_b32 v0, v137, v34
	ds_bpermute_b32 v40, v137, v10
	s_waitcnt lgkmcnt(2)
	v_cndmask_b32_e64 v8, v12, v35, s[4:5]
	v_fmac_f32_e32 v37, 0, v8
	ds_bpermute_b32 v8, v137, v33
	v_cndmask_b32_e64 v1, v35, v12, s[4:5]
	v_mul_f32_e32 v38, v12, v35
	v_fmac_f32_e32 v36, v1, v37
	s_waitcnt lgkmcnt(2)
	v_cndmask_b32_e64 v1, v0, v34, s[4:5]
	s_waitcnt lgkmcnt(1)
	v_cndmask_b32_e64 v39, v40, v10, s[4:5]
	v_cndmask_b32_e64 v0, v34, v0, s[4:5]
	v_cndmask_b32_e64 v40, v10, v40, s[4:5]
	ds_bpermute_b32 v44, v137, v24
	v_mul_f32_e32 v41, v38, v0
	v_fmac_f32_e32 v40, v0, v36
	v_mul_f32_e32 v42, v1, v41
	v_fmac_f32_e32 v39, v1, v40
	s_waitcnt lgkmcnt(1)
	v_cndmask_b32_e64 v0, v8, v33, s[4:5]
	v_cndmask_b32_e64 v1, v33, v8, s[4:5]
	ds_bpermute_b32 v8, v137, v32
	ds_bpermute_b32 v47, v137, v25
	s_waitcnt lgkmcnt(2)
	v_cndmask_b32_e64 v43, v44, v24, s[4:5]
	v_cndmask_b32_e64 v44, v24, v44, s[4:5]
	v_mul_f32_e32 v45, v1, v42
	v_fmac_f32_e32 v44, v1, v39
	v_mul_f32_e32 v46, v0, v45
	v_fmac_f32_e32 v43, v0, v44
	s_waitcnt lgkmcnt(1)
	v_cndmask_b32_e64 v0, v32, v8, s[4:5]
	s_waitcnt lgkmcnt(0)
	v_cndmask_b32_e64 v47, v25, v47, s[4:5]
	v_mul_f32_e32 v48, v0, v46
	v_fmac_f32_e32 v47, v0, v43
	s_and_saveexec_b64 s[12:13], s[4:5]
	v_mul_f32_e32 v0, v32, v48
	v_fma_f32 v1, v32, v47, v25
	ds_write_b64 v136, v[0:1] offset:6144
	s_or_b64 exec, exec, s[12:13]
	s_and_b64 vcc, exec, s[8:9]
	s_waitcnt lgkmcnt(0)
	s_barrier
	s_cbranch_vccnz .LBB0_293
	v_add3_u32 v49, v140, v91, s95
	v_mov_b32_e32 v8, 1.0
	v_mov_b32_e32 v1, 0
	s_mov_b32 s8, 7

.LBB0_320:
	s_and_b32 s63, s57, 63
	s_ashr_i32 s62, s89, 6
	s_lshl_b32 s0, s63, 8
	s_lshl_b32 s1, s62, 5
	v_and_b32_e32 v94, 31, v92
	s_add_i32 s8, s1, s0
	v_or_b32_e32 v9, s8, v94
	v_add_u32_e32 v0, -2, v9
	v_cmp_gt_u32_e32 vcc, s80, v0
	v_bfe_u32 v93, v92, 5, 1
	s_lshl_b32 s14, s70, 1
	v_cndmask_b32_e32 v2, v9, v0, vcc
	v_mov_b64_e32 v[0:1], s[52:53]
	v_mad_i64_i32 v[2:3], s[0:1], v2, s81, v[0:1]
	v_lshl_add_u64 v[2:3], v[2:3], 0, s[14:15]
	v_lshlrev_b32_e32 v88, 4, v93
	v_lshl_add_u64 v[4:5], v[2:3], 0, v[88:89]
	v_add_co_u32_e64 v2, s[0:1], s82, v4
	s_waitcnt lgkmcnt(0)
	s_nop 0
	v_addc_co_u32_e64 v3, s[0:1], 0, v5, s[0:1]
	s_barrier
	global_load_dwordx4 v[10:13], v[2:3], off offset:1024
	global_load_dwordx4 v[178:181], v[2:3], off offset:1056
	global_load_dwordx4 v[194:197], v[2:3], off offset:1088
	global_load_dwordx4 v[210:213], v[2:3], off offset:1120
	global_load_dwordx4 v[226:229], v[2:3], off offset:1152
	global_load_dwordx4 v[242:245], v[2:3], off offset:1184
	v_add_u32_e32 v2, -1, v9
	v_cmp_gt_u32_e64 s[0:1], s80, v2
	v_add_u32_e32 v18, 1, v9
	s_cmpk_lt_u32 s8, 0x4000
	v_cndmask_b32_e64 v2, v9, v2, s[0:1]
	v_mad_i64_i32 v[2:3], s[4:5], v2, s81, v[0:1]
	v_lshl_add_u64 v[2:3], v[2:3], 0, s[14:15]
	v_lshl_add_u64 v[2:3], v[2:3], 0, v[88:89]
	v_add_co_u32_e64 v6, s[4:5], s82, v2
	v_lshlrev_b32_e32 v138, 8, v94
	s_nop 0
	v_addc_co_u32_e64 v7, s[4:5], 0, v3, s[4:5]
	global_load_dwordx4 v[14:17], v[6:7], off offset:1024
	global_load_dwordx4 v[182:185], v[6:7], off offset:1056
	global_load_dwordx4 v[198:201], v[6:7], off offset:1088
	global_load_dwordx4 v[214:217], v[6:7], off offset:1120
	global_load_dwordx4 v[230:233], v[6:7], off offset:1152
	global_load_dwordx4 v[246:249], v[6:7], off offset:1184
	v_mad_i64_i32 v[6:7], s[4:5], v9, s81, v[0:1]
	v_cmp_gt_u32_e64 s[4:5], s80, v18
	v_lshl_add_u64 v[6:7], v[6:7], 0, s[14:15]
	v_lshl_add_u64 v[52:53], v[6:7], 0, v[88:89]
	v_cndmask_b32_e64 v9, v9, v18, s[4:5]
	v_mad_i64_i32 v[0:1], s[6:7], v9, s81, v[0:1]
	v_add_co_u32_e64 v6, s[6:7], s82, v52
	v_lshl_add_u64 v[0:1], v[0:1], 0, s[14:15]
	s_nop 0
	v_addc_co_u32_e64 v7, s[6:7], 0, v53, s[6:7]
	global_load_dwordx4 v[18:21], v[6:7], off offset:1024
	global_load_dwordx4 v[186:189], v[6:7], off offset:1056
	global_load_dwordx4 v[202:205], v[6:7], off offset:1088
	global_load_dwordx4 v[218:221], v[6:7], off offset:1120
	global_load_dwordx4 v[234:237], v[6:7], off offset:1152
	global_load_dwordx4 v[252:255], v[6:7], off offset:1184
	v_lshl_add_u64 v[6:7], v[0:1], 0, v[88:89]
	v_add_co_u32_e64 v0, s[6:7], s82, v6
	v_lshl_add_u32 v9, v93, 5, 16
	s_nop 0
	v_addc_co_u32_e64 v1, s[6:7], 0, v7, s[6:7]
	global_load_dwordx4 v[22:25], v[0:1], off offset:1024
	global_load_dwordx4 v[190:193], v[0:1], off offset:1056
	global_load_dwordx4 v[206:209], v[0:1], off offset:1088
	global_load_dwordx4 v[222:225], v[0:1], off offset:1120
	global_load_dwordx4 v[238:241], v[0:1], off offset:1152
	global_load_dwordx4 v[168:171], v[0:1], off offset:1184
	ds_read_b128 v[26:29], v9 offset:8192
	s_waitcnt vmcnt(26)
	ds_read_b128 v[30:33], v9 offset:8704
	ds_read_b128 v[34:37], v9 offset:10240
	ds_read_b128 v[38:41], v9 offset:10256
	ds_read_b128 v[42:45], v9 offset:8208
	ds_read_b128 v[46:49], v9 offset:8720
	s_waitcnt lgkmcnt(4)
	v_mov_b32_e32 v51, v30
	v_mov_b32_e32 v30, v27
	v_mov_b32_e32 v27, v32
	v_mov_b32_e32 v50, v26
	v_lshl_add_u64 v[0:1], v[4:5], 0, s[30:31]
	v_mov_b32_e32 v26, v28
	s_cselect_b64 s[6:7], -1, 0
	v_lshl_add_u64 v[6:7], v[6:7], 0, s[30:31]
	v_and_b32_e32 v8, 0x70, v8
	v_add_u32_e32 v95, 16, v138
	v_or_b32_e32 v91, s70, v94
	s_waitcnt vmcnt(23)
	v_cndmask_b32_e32 v32, 0, v11, vcc
	v_cndmask_b32_e32 v10, 0, v10, vcc
	v_lshlrev_b32_e32 v4, 16, v10
	v_and_b32_e32 v10, 0xffff0000, v10
	v_cndmask_b32_e32 v54, 0, v12, vcc
	v_lshlrev_b32_e32 v12, 16, v32
	v_cndmask_b32_e32 v28, 0, v13, vcc
	s_waitcnt vmcnt(17)
	v_cndmask_b32_e64 v11, 0, v14, s[0:1]
	v_lshlrev_b32_e32 v5, 16, v11
	v_pk_mul_f32 v[4:5], v[50:51], v[4:5]
	v_cndmask_b32_e64 v15, 0, v15, s[0:1]
	v_and_b32_e32 v11, 0xffff0000, v11
	s_waitcnt lgkmcnt(3)
	v_add_f32_e32 v4, v34, v4
	v_pk_mul_f32 v[10:11], v[30:31], v[10:11]
	v_add_f32_e32 v30, v4, v5
	v_and_b32_e32 v5, 0xffff0000, v15
	v_and_b32_e32 v4, 0xffff0000, v32
	v_mov_b32_e32 v32, v29
	v_pk_mul_f32 v[4:5], v[32:33], v[4:5]
	v_cndmask_b32_e64 v16, 0, v16, s[0:1]
	v_add_f32_e32 v10, v35, v10
	v_add_f32_e32 v4, v37, v4
	v_add_f32_e32 v31, v10, v11
	v_add_f32_e32 v29, v4, v5
	v_lshlrev_b32_e32 v5, 16, v16
	v_lshlrev_b32_e32 v4, 16, v54
	s_waitcnt lgkmcnt(1)
	v_mov_b32_e32 v10, v42
	s_waitcnt lgkmcnt(0)
	v_mov_b32_e32 v11, v46
	v_pk_mul_f32 v[4:5], v[10:11], v[4:5]
	v_mov_b32_e32 v46, v43
	v_add_f32_e32 v4, v38, v4
	v_add_f32_e32 v32, v4, v5
	v_and_b32_e32 v5, 0xffff0000, v16
	v_and_b32_e32 v4, 0xffff0000, v54
	v_pk_mul_f32 v[4:5], v[46:47], v[4:5]
	v_cndmask_b32_e64 v17, 0, v17, s[0:1]
	v_add_f32_e32 v4, v39, v4
	v_add_f32_e32 v33, v4, v5
	v_lshlrev_b32_e32 v5, 16, v17
	v_lshlrev_b32_e32 v4, 16, v28
	v_mov_b32_e32 v10, v44
	v_mov_b32_e32 v11, v48
	v_pk_mul_f32 v[4:5], v[10:11], v[4:5]
	v_lshlrev_b32_e32 v13, 16, v15
	v_add_f32_e32 v4, v40, v4
	v_pk_mul_f32 v[12:13], v[26:27], v[12:13]
	v_add_f32_e32 v35, v4, v5
	v_and_b32_e32 v5, 0xffff0000, v17
	v_and_b32_e32 v4, 0xffff0000, v28
	v_mov_b32_e32 v48, v45
	v_add_f32_e32 v12, v36, v12
	v_pk_mul_f32 v[4:5], v[48:49], v[4:5]
	v_add_f32_e32 v34, v12, v13
	v_add_f32_e32 v4, v41, v4
	s_waitcnt vmcnt(11)
	v_cndmask_b32_e64 v36, 0, v21, s[6:7]
	v_cndmask_b32_e64 v37, 0, v20, s[6:7]
	v_cndmask_b32_e64 v38, 0, v19, s[6:7]
	v_cndmask_b32_e64 v39, 0, v18, s[6:7]
	ds_read_b128 v[10:13], v9 offset:9216
	ds_read_b128 v[14:17], v9 offset:9232
	s_waitcnt vmcnt(5)
	v_cndmask_b32_e64 v40, 0, v25, s[4:5]
	v_cndmask_b32_e64 v41, 0, v24, s[4:5]
	v_cndmask_b32_e64 v42, 0, v23, s[4:5]
	v_cndmask_b32_e64 v43, 0, v22, s[4:5]
	ds_read_b128 v[18:21], v9 offset:9728
	ds_read_b128 v[22:25], v9 offset:9744
	v_add_f32_e32 v28, v4, v5
	v_lshlrev_b32_e32 v5, 16, v43
	v_lshlrev_b32_e32 v4, 16, v39
	s_waitcnt lgkmcnt(3)
	v_mov_b32_e32 v26, v10
	s_waitcnt lgkmcnt(1)
	v_mov_b32_e32 v27, v18
	v_pk_mul_f32 v[4:5], v[26:27], v[4:5]
	v_mov_b32_e32 v18, v11
	v_add_f32_e32 v4, v30, v4
	v_add_f32_e32 v26, v4, v5
	v_and_b32_e32 v5, 0xffff0000, v43
	v_and_b32_e32 v4, 0xffff0000, v39
	v_pk_mul_f32 v[4:5], v[18:19], v[4:5]
	v_mov_b32_e32 v10, v12
	v_add_f32_e32 v4, v31, v4
	v_add_f32_e32 v18, v4, v5
	v_lshlrev_b32_e32 v5, 16, v42
	v_lshlrev_b32_e32 v4, 16, v38
	v_mov_b32_e32 v11, v20
	v_pk_mul_f32 v[4:5], v[10:11], v[4:5]
	v_mov_b32_e32 v20, v13
	v_add_f32_e32 v4, v34, v4
	v_add_f32_e32 v12, v4, v5
	v_and_b32_e32 v5, 0xffff0000, v42
	v_and_b32_e32 v4, 0xffff0000, v38
	v_pk_mul_f32 v[4:5], v[20:21], v[4:5]
	v_mov_b32_e32 v10, v14
	v_add_f32_e32 v4, v29, v4
	v_add_f32_e32 v13, v4, v5
	v_lshlrev_b32_e32 v5, 16, v41
	v_lshlrev_b32_e32 v4, 16, v37
	s_waitcnt lgkmcnt(0)
	v_mov_b32_e32 v11, v22
	v_pk_mul_f32 v[4:5], v[10:11], v[4:5]
	v_mov_b32_e32 v22, v15
	v_add_f32_e32 v4, v32, v4
	v_add_f32_e32 v14, v4, v5
	v_and_b32_e32 v5, 0xffff0000, v41
	v_and_b32_e32 v4, 0xffff0000, v37
	v_pk_mul_f32 v[4:5], v[22:23], v[4:5]
	v_mov_b32_e32 v10, v16
	v_add_f32_e32 v4, v33, v4
	v_add_f32_e32 v15, v4, v5
	v_lshlrev_b32_e32 v5, 16, v40
	v_lshlrev_b32_e32 v4, 16, v36
	v_mov_b32_e32 v11, v24
	v_pk_mul_f32 v[4:5], v[10:11], v[4:5]
	v_mov_b32_e32 v24, v17
	v_add_f32_e32 v4, v35, v4
	v_add_f32_e32 v10, v4, v5
	v_and_b32_e32 v5, 0xffff0000, v40
	v_and_b32_e32 v4, 0xffff0000, v36
	v_pk_mul_f32 v[4:5], v[24:25], v[4:5]
	v_cvt_pk_bf16_f32 v48, v26, v18
	v_cvt_pk_bf16_f32 v49, v12, v13
	v_cvt_pk_bf16_f32 v50, v14, v15
	s_nop 0
	v_add_f32_e32 v4, v28, v4
	v_add_f32_e32 v4, v4, v5
	v_cvt_pk_bf16_f32 v51, v10, v4
	v_lshl_add_u64 v[4:5], v[2:3], 0, s[30:31]
	v_lshl_add_u64 v[2:3], v[52:53], 0, s[30:31]
	ds_read_b128 v[26:29], v9 offset:10304
	ds_read_b128 v[30:33], v9 offset:10320
	s_waitcnt vmcnt(4)
	v_cndmask_b32_e32 v46, 0, v181, vcc
	v_cndmask_b32_e32 v47, 0, v180, vcc
	v_cndmask_b32_e32 v52, 0, v179, vcc
	v_cndmask_b32_e32 v53, 0, v178, vcc
	ds_read_b128 v[10:13], v9 offset:8256
	ds_read_b128 v[34:37], v9 offset:8272
	s_waitcnt vmcnt(4)
	v_cndmask_b32_e64 v54, 0, v185, s[0:1]
	v_cndmask_b32_e64 v55, 0, v184, s[0:1]
	v_cndmask_b32_e64 v56, 0, v183, s[0:1]
	v_cndmask_b32_e64 v57, 0, v182, s[0:1]
	ds_read_b128 v[14:17], v9 offset:8768
	ds_read_b128 v[38:41], v9 offset:8784
	v_lshlrev_b32_e32 v43, 16, v57
	v_lshlrev_b32_e32 v42, 16, v53
	s_waitcnt lgkmcnt(3)
	v_mov_b32_e32 v44, v10
	s_waitcnt lgkmcnt(1)
	v_mov_b32_e32 v45, v14
	v_pk_mul_f32 v[42:43], v[44:45], v[42:43]
	v_mov_b32_e32 v14, v11
	v_add_f32_e32 v10, v26, v42
	v_add_f32_e32 v44, v10, v43
	v_and_b32_e32 v43, 0xffff0000, v57
	v_and_b32_e32 v42, 0xffff0000, v53
	v_pk_mul_f32 v[10:11], v[14:15], v[42:43]
	v_mov_b32_e32 v14, v12
	v_add_f32_e32 v10, v27, v10
	v_add_f32_e32 v42, v10, v11
	v_lshlrev_b32_e32 v11, 16, v56
	v_lshlrev_b32_e32 v10, 16, v52
	v_mov_b32_e32 v15, v16
	v_pk_mul_f32 v[10:11], v[14:15], v[10:11]
	v_mov_b32_e32 v16, v13
	v_add_f32_e32 v10, v28, v10
	v_add_f32_e32 v43, v10, v11
	v_and_b32_e32 v11, 0xffff0000, v56
	v_and_b32_e32 v10, 0xffff0000, v52
	v_pk_mul_f32 v[10:11], v[16:17], v[10:11]
	v_mov_b32_e32 v12, v34
	v_add_f32_e32 v10, v29, v10
	v_add_f32_e32 v45, v10, v11
	v_lshlrev_b32_e32 v11, 16, v55
	v_lshlrev_b32_e32 v10, 16, v47
	s_waitcnt lgkmcnt(0)
	v_mov_b32_e32 v13, v38
	v_pk_mul_f32 v[10:11], v[12:13], v[10:11]
	v_mov_b32_e32 v38, v35
	v_add_f32_e32 v10, v30, v10
	v_add_f32_e32 v30, v10, v11
	v_and_b32_e32 v11, 0xffff0000, v55
	v_and_b32_e32 v10, 0xffff0000, v47
	v_pk_mul_f32 v[10:11], v[38:39], v[10:11]
	v_mov_b32_e32 v12, v36
	v_add_f32_e32 v10, v31, v10
	v_add_f32_e32 v31, v10, v11
	v_lshlrev_b32_e32 v11, 16, v54
	v_lshlrev_b32_e32 v10, 16, v46
	v_mov_b32_e32 v13, v40
	v_pk_mul_f32 v[10:11], v[12:13], v[10:11]
	v_mov_b32_e32 v40, v37
	v_add_f32_e32 v10, v32, v10
	v_add_f32_e32 v32, v10, v11
	v_and_b32_e32 v11, 0xffff0000, v54
	v_and_b32_e32 v10, 0xffff0000, v46
	v_pk_mul_f32 v[10:11], v[40:41], v[10:11]
	s_waitcnt vmcnt(4)
	v_cndmask_b32_e64 v34, 0, v189, s[6:7]
	v_add_f32_e32 v10, v33, v10
	v_add_f32_e32 v33, v10, v11
	v_cndmask_b32_e64 v35, 0, v188, s[6:7]
	v_cndmask_b32_e64 v36, 0, v187, s[6:7]
	v_cndmask_b32_e64 v37, 0, v186, s[6:7]
	ds_read_b128 v[10:13], v9 offset:9280
	ds_read_b128 v[14:17], v9 offset:9296
	v_cndmask_b32_e64 v38, 0, v193, s[4:5]
	v_cndmask_b32_e64 v39, 0, v192, s[4:5]
	v_cndmask_b32_e64 v40, 0, v191, s[4:5]
	v_cndmask_b32_e64 v41, 0, v190, s[4:5]
	ds_read_b128 v[18:21], v9 offset:9792
	ds_read_b128 v[22:25], v9 offset:9808
	v_lshlrev_b32_e32 v27, 16, v41
	v_lshlrev_b32_e32 v26, 16, v37
	s_waitcnt lgkmcnt(3)
	v_mov_b32_e32 v28, v10
	s_waitcnt lgkmcnt(1)
	v_mov_b32_e32 v29, v18
	v_pk_mul_f32 v[26:27], v[28:29], v[26:27]
	v_mov_b32_e32 v18, v11
	v_add_f32_e32 v10, v44, v26
	v_add_f32_e32 v28, v10, v27
	v_and_b32_e32 v27, 0xffff0000, v41
	v_and_b32_e32 v26, 0xffff0000, v37
	v_pk_mul_f32 v[10:11], v[18:19], v[26:27]
	v_mov_b32_e32 v18, v12
	v_add_f32_e32 v10, v42, v10
	v_add_f32_e32 v26, v10, v11
	v_lshlrev_b32_e32 v11, 16, v40
	v_lshlrev_b32_e32 v10, 16, v36
	v_mov_b32_e32 v19, v20
	v_pk_mul_f32 v[10:11], v[18:19], v[10:11]
	v_mov_b32_e32 v20, v13
	v_add_f32_e32 v10, v43, v10
	v_add_f32_e32 v18, v10, v11
	v_and_b32_e32 v11, 0xffff0000, v40
	v_and_b32_e32 v10, 0xffff0000, v36
	v_pk_mul_f32 v[10:11], v[20:21], v[10:11]
	v_mov_b32_e32 v12, v14
	v_add_f32_e32 v10, v45, v10
	v_add_f32_e32 v19, v10, v11
	v_lshlrev_b32_e32 v11, 16, v39
	v_lshlrev_b32_e32 v10, 16, v35
	s_waitcnt lgkmcnt(0)
	v_mov_b32_e32 v13, v22
	v_pk_mul_f32 v[10:11], v[12:13], v[10:11]
	v_mov_b32_e32 v22, v15
	v_add_f32_e32 v10, v30, v10
	v_add_f32_e32 v14, v10, v11
	v_and_b32_e32 v11, 0xffff0000, v39
	v_and_b32_e32 v10, 0xffff0000, v35
	v_pk_mul_f32 v[10:11], v[22:23], v[10:11]
	v_mov_b32_e32 v12, v16
	v_add_f32_e32 v10, v31, v10
	v_add_f32_e32 v15, v10, v11
	v_lshlrev_b32_e32 v11, 16, v38
	v_lshlrev_b32_e32 v10, 16, v34
	v_mov_b32_e32 v13, v24
	v_pk_mul_f32 v[10:11], v[12:13], v[10:11]
	v_mov_b32_e32 v24, v17
	v_add_f32_e32 v10, v32, v10
	v_add_f32_e32 v12, v10, v11
	v_and_b32_e32 v11, 0xffff0000, v38
	v_and_b32_e32 v10, 0xffff0000, v34
	v_pk_mul_f32 v[10:11], v[24:25], v[10:11]
	v_cvt_pk_bf16_f32 v52, v28, v26
	v_cvt_pk_bf16_f32 v53, v18, v19
	v_cvt_pk_bf16_f32 v54, v14, v15
	s_nop 0
	v_add_f32_e32 v10, v33, v10
	v_add_f32_e32 v10, v10, v11
	v_cvt_pk_bf16_f32 v55, v12, v10
	global_load_dwordx4 v[178:181], v[0:1], off offset:192
	global_load_dwordx4 v[182:185], v[4:5], off offset:192
	global_load_dwordx4 v[186:189], v[2:3], off offset:192
	global_load_dwordx4 v[190:193], v[6:7], off offset:192
	ds_read_b128 v[26:29], v9 offset:10368
	ds_read_b128 v[30:33], v9 offset:10384
	s_waitcnt vmcnt(7)
	v_cndmask_b32_e32 v46, 0, v197, vcc
	v_cndmask_b32_e32 v47, 0, v196, vcc
	v_cndmask_b32_e32 v56, 0, v195, vcc
	v_cndmask_b32_e32 v57, 0, v194, vcc
	ds_read_b128 v[10:13], v9 offset:8320
	ds_read_b128 v[34:37], v9 offset:8336
	s_waitcnt vmcnt(7)
	v_cndmask_b32_e64 v58, 0, v201, s[0:1]
	v_cndmask_b32_e64 v59, 0, v200, s[0:1]
	v_cndmask_b32_e64 v60, 0, v199, s[0:1]
	v_cndmask_b32_e64 v61, 0, v198, s[0:1]
	ds_read_b128 v[14:17], v9 offset:8832
	ds_read_b128 v[38:41], v9 offset:8848
	v_lshlrev_b32_e32 v43, 16, v61
	v_lshlrev_b32_e32 v42, 16, v57
	s_waitcnt lgkmcnt(3)
	v_mov_b32_e32 v44, v10
	s_waitcnt lgkmcnt(1)
	v_mov_b32_e32 v45, v14
	v_pk_mul_f32 v[42:43], v[44:45], v[42:43]
	v_mov_b32_e32 v14, v11
	v_add_f32_e32 v10, v26, v42
	v_add_f32_e32 v44, v10, v43
	v_and_b32_e32 v43, 0xffff0000, v61
	v_and_b32_e32 v42, 0xffff0000, v57
	v_pk_mul_f32 v[10:11], v[14:15], v[42:43]
	v_mov_b32_e32 v14, v12
	v_add_f32_e32 v10, v27, v10
	v_add_f32_e32 v42, v10, v11
	v_lshlrev_b32_e32 v11, 16, v60
	v_lshlrev_b32_e32 v10, 16, v56
	v_mov_b32_e32 v15, v16
	v_pk_mul_f32 v[10:11], v[14:15], v[10:11]
	v_mov_b32_e32 v16, v13
	v_add_f32_e32 v10, v28, v10
	v_add_f32_e32 v43, v10, v11
	v_and_b32_e32 v11, 0xffff0000, v60
	v_and_b32_e32 v10, 0xffff0000, v56
	v_pk_mul_f32 v[10:11], v[16:17], v[10:11]
	v_mov_b32_e32 v12, v34
	v_add_f32_e32 v10, v29, v10
	v_add_f32_e32 v45, v10, v11
	v_lshlrev_b32_e32 v11, 16, v59
	v_lshlrev_b32_e32 v10, 16, v47
	s_waitcnt lgkmcnt(0)
	v_mov_b32_e32 v13, v38
	v_pk_mul_f32 v[10:11], v[12:13], v[10:11]
	v_mov_b32_e32 v38, v35
	v_add_f32_e32 v10, v30, v10
	v_add_f32_e32 v30, v10, v11
	v_and_b32_e32 v11, 0xffff0000, v59
	v_and_b32_e32 v10, 0xffff0000, v47
	v_pk_mul_f32 v[10:11], v[38:39], v[10:11]
	v_mov_b32_e32 v12, v36
	v_add_f32_e32 v10, v31, v10
	v_add_f32_e32 v31, v10, v11
	v_lshlrev_b32_e32 v11, 16, v58
	v_lshlrev_b32_e32 v10, 16, v46
	v_mov_b32_e32 v13, v40
	v_pk_mul_f32 v[10:11], v[12:13], v[10:11]
	v_mov_b32_e32 v40, v37
	v_add_f32_e32 v10, v32, v10
	v_add_f32_e32 v32, v10, v11
	v_and_b32_e32 v11, 0xffff0000, v58
	v_and_b32_e32 v10, 0xffff0000, v46
	v_pk_mul_f32 v[10:11], v[40:41], v[10:11]
	s_waitcnt vmcnt(7)
	v_cndmask_b32_e64 v34, 0, v205, s[6:7]
	v_add_f32_e32 v10, v33, v10
	v_add_f32_e32 v33, v10, v11
	v_cndmask_b32_e64 v35, 0, v204, s[6:7]
	v_cndmask_b32_e64 v36, 0, v203, s[6:7]
	v_cndmask_b32_e64 v37, 0, v202, s[6:7]
	ds_read_b128 v[10:13], v9 offset:9344
	ds_read_b128 v[14:17], v9 offset:9360
	s_waitcnt vmcnt(7)
	v_cndmask_b32_e64 v38, 0, v209, s[4:5]
	v_cndmask_b32_e64 v39, 0, v208, s[4:5]
	v_cndmask_b32_e64 v40, 0, v207, s[4:5]
	v_cndmask_b32_e64 v41, 0, v206, s[4:5]
	ds_read_b128 v[18:21], v9 offset:9856
	ds_read_b128 v[22:25], v9 offset:9872
	v_lshlrev_b32_e32 v27, 16, v41
	v_lshlrev_b32_e32 v26, 16, v37
	s_waitcnt lgkmcnt(3)
	v_mov_b32_e32 v28, v10
	s_waitcnt lgkmcnt(1)
	v_mov_b32_e32 v29, v18
	v_pk_mul_f32 v[26:27], v[28:29], v[26:27]
	v_mov_b32_e32 v18, v11
	v_add_f32_e32 v10, v44, v26
	v_add_f32_e32 v28, v10, v27
	v_and_b32_e32 v27, 0xffff0000, v41
	v_and_b32_e32 v26, 0xffff0000, v37
	v_pk_mul_f32 v[10:11], v[18:19], v[26:27]
	v_mov_b32_e32 v18, v12
	v_add_f32_e32 v10, v42, v10
	v_add_f32_e32 v26, v10, v11
	v_lshlrev_b32_e32 v11, 16, v40
	v_lshlrev_b32_e32 v10, 16, v36
	v_mov_b32_e32 v19, v20
	v_pk_mul_f32 v[10:11], v[18:19], v[10:11]
	v_mov_b32_e32 v20, v13
	v_add_f32_e32 v10, v43, v10
	v_add_f32_e32 v18, v10, v11
	v_and_b32_e32 v11, 0xffff0000, v40
	v_and_b32_e32 v10, 0xffff0000, v36
	v_pk_mul_f32 v[10:11], v[20:21], v[10:11]
	v_mov_b32_e32 v12, v14
	v_add_f32_e32 v10, v45, v10
	v_add_f32_e32 v19, v10, v11
	v_lshlrev_b32_e32 v11, 16, v39
	v_lshlrev_b32_e32 v10, 16, v35
	s_waitcnt lgkmcnt(0)
	v_mov_b32_e32 v13, v22
	v_pk_mul_f32 v[10:11], v[12:13], v[10:11]
	v_mov_b32_e32 v22, v15
	v_add_f32_e32 v10, v30, v10
	v_add_f32_e32 v14, v10, v11
	v_and_b32_e32 v11, 0xffff0000, v39
	v_and_b32_e32 v10, 0xffff0000, v35
	v_pk_mul_f32 v[10:11], v[22:23], v[10:11]
	v_mov_b32_e32 v12, v16
	v_add_f32_e32 v10, v31, v10
	v_add_f32_e32 v15, v10, v11
	v_lshlrev_b32_e32 v11, 16, v38
	v_lshlrev_b32_e32 v10, 16, v34
	v_mov_b32_e32 v13, v24
	v_pk_mul_f32 v[10:11], v[12:13], v[10:11]
	v_mov_b32_e32 v24, v17
	v_add_f32_e32 v10, v32, v10
	v_add_f32_e32 v12, v10, v11
	v_and_b32_e32 v11, 0xffff0000, v38
	v_and_b32_e32 v10, 0xffff0000, v34
	v_pk_mul_f32 v[10:11], v[24:25], v[10:11]
	v_cvt_pk_bf16_f32 v56, v28, v26
	v_cvt_pk_bf16_f32 v57, v18, v19
	v_cvt_pk_bf16_f32 v58, v14, v15
	s_nop 0
	v_add_f32_e32 v10, v33, v10
	v_add_f32_e32 v10, v10, v11
	v_cvt_pk_bf16_f32 v59, v12, v10
	global_load_dwordx4 v[194:197], v[0:1], off offset:224
	global_load_dwordx4 v[198:201], v[4:5], off offset:224
	global_load_dwordx4 v[202:205], v[2:3], off offset:224
	global_load_dwordx4 v[206:209], v[6:7], off offset:224
	ds_read_b128 v[26:29], v9 offset:10432
	ds_read_b128 v[30:33], v9 offset:10448
	s_waitcnt vmcnt(10)
	v_cndmask_b32_e32 v46, 0, v213, vcc
	v_cndmask_b32_e32 v47, 0, v212, vcc
	v_cndmask_b32_e32 v60, 0, v211, vcc
	v_cndmask_b32_e32 v61, 0, v210, vcc
	ds_read_b128 v[10:13], v9 offset:8384
	ds_read_b128 v[34:37], v9 offset:8400
	s_waitcnt vmcnt(10)
	v_cndmask_b32_e64 v62, 0, v217, s[0:1]
	v_cndmask_b32_e64 v63, 0, v216, s[0:1]
	v_cndmask_b32_e64 v64, 0, v215, s[0:1]
	v_cndmask_b32_e64 v65, 0, v214, s[0:1]
	ds_read_b128 v[14:17], v9 offset:8896
	ds_read_b128 v[38:41], v9 offset:8912
	v_lshlrev_b32_e32 v43, 16, v65
	v_lshlrev_b32_e32 v42, 16, v61
	s_waitcnt lgkmcnt(3)
	v_mov_b32_e32 v44, v10
	s_waitcnt lgkmcnt(1)
	v_mov_b32_e32 v45, v14
	v_pk_mul_f32 v[42:43], v[44:45], v[42:43]
	v_mov_b32_e32 v14, v11
	v_add_f32_e32 v10, v26, v42
	v_add_f32_e32 v44, v10, v43
	v_and_b32_e32 v43, 0xffff0000, v65
	v_and_b32_e32 v42, 0xffff0000, v61
	v_pk_mul_f32 v[10:11], v[14:15], v[42:43]
	v_mov_b32_e32 v14, v12
	v_add_f32_e32 v10, v27, v10
	v_add_f32_e32 v42, v10, v11
	v_lshlrev_b32_e32 v11, 16, v64
	v_lshlrev_b32_e32 v10, 16, v60
	v_mov_b32_e32 v15, v16
	v_pk_mul_f32 v[10:11], v[14:15], v[10:11]
	v_mov_b32_e32 v16, v13
	v_add_f32_e32 v10, v28, v10
	v_add_f32_e32 v43, v10, v11
	v_and_b32_e32 v11, 0xffff0000, v64
	v_and_b32_e32 v10, 0xffff0000, v60
	v_pk_mul_f32 v[10:11], v[16:17], v[10:11]
	v_mov_b32_e32 v12, v34
	v_add_f32_e32 v10, v29, v10
	v_add_f32_e32 v45, v10, v11
	v_lshlrev_b32_e32 v11, 16, v63
	v_lshlrev_b32_e32 v10, 16, v47
	s_waitcnt lgkmcnt(0)
	v_mov_b32_e32 v13, v38
	v_pk_mul_f32 v[10:11], v[12:13], v[10:11]
	v_mov_b32_e32 v38, v35
	v_add_f32_e32 v10, v30, v10
	v_add_f32_e32 v30, v10, v11
	v_and_b32_e32 v11, 0xffff0000, v63
	v_and_b32_e32 v10, 0xffff0000, v47
	v_pk_mul_f32 v[10:11], v[38:39], v[10:11]
	v_mov_b32_e32 v12, v36
	v_add_f32_e32 v10, v31, v10
	v_add_f32_e32 v31, v10, v11
	v_lshlrev_b32_e32 v11, 16, v62
	v_lshlrev_b32_e32 v10, 16, v46
	v_mov_b32_e32 v13, v40
	v_pk_mul_f32 v[10:11], v[12:13], v[10:11]
	v_mov_b32_e32 v40, v37
	v_add_f32_e32 v10, v32, v10
	v_add_f32_e32 v32, v10, v11
	v_and_b32_e32 v11, 0xffff0000, v62
	v_and_b32_e32 v10, 0xffff0000, v46
	v_pk_mul_f32 v[10:11], v[40:41], v[10:11]
	s_waitcnt vmcnt(10)
	v_cndmask_b32_e64 v34, 0, v221, s[6:7]
	v_add_f32_e32 v10, v33, v10
	v_add_f32_e32 v33, v10, v11
	v_cndmask_b32_e64 v35, 0, v220, s[6:7]
	v_cndmask_b32_e64 v36, 0, v219, s[6:7]
	v_cndmask_b32_e64 v37, 0, v218, s[6:7]
	ds_read_b128 v[10:13], v9 offset:9408
	ds_read_b128 v[14:17], v9 offset:9424
	s_waitcnt vmcnt(10)
	v_cndmask_b32_e64 v38, 0, v225, s[4:5]
	v_cndmask_b32_e64 v39, 0, v224, s[4:5]
	v_cndmask_b32_e64 v40, 0, v223, s[4:5]
	v_cndmask_b32_e64 v41, 0, v222, s[4:5]
	ds_read_b128 v[18:21], v9 offset:9920
	ds_read_b128 v[22:25], v9 offset:9936
	v_lshlrev_b32_e32 v27, 16, v41
	v_lshlrev_b32_e32 v26, 16, v37
	s_waitcnt lgkmcnt(3)
	v_mov_b32_e32 v28, v10
	s_waitcnt lgkmcnt(1)
	v_mov_b32_e32 v29, v18
	v_pk_mul_f32 v[26:27], v[28:29], v[26:27]
	v_mov_b32_e32 v18, v11
	v_add_f32_e32 v10, v44, v26
	v_add_f32_e32 v28, v10, v27
	v_and_b32_e32 v27, 0xffff0000, v41
	v_and_b32_e32 v26, 0xffff0000, v37
	v_pk_mul_f32 v[10:11], v[18:19], v[26:27]
	v_mov_b32_e32 v18, v12
	v_add_f32_e32 v10, v42, v10
	v_add_f32_e32 v26, v10, v11
	v_lshlrev_b32_e32 v11, 16, v40
	v_lshlrev_b32_e32 v10, 16, v36
	v_mov_b32_e32 v19, v20
	v_pk_mul_f32 v[10:11], v[18:19], v[10:11]
	v_mov_b32_e32 v20, v13
	v_add_f32_e32 v10, v43, v10
	v_add_f32_e32 v18, v10, v11
	v_and_b32_e32 v11, 0xffff0000, v40
	v_and_b32_e32 v10, 0xffff0000, v36
	v_pk_mul_f32 v[10:11], v[20:21], v[10:11]
	v_mov_b32_e32 v12, v14
	v_add_f32_e32 v10, v45, v10
	v_add_f32_e32 v19, v10, v11
	v_lshlrev_b32_e32 v11, 16, v39
	v_lshlrev_b32_e32 v10, 16, v35
	s_waitcnt lgkmcnt(0)
	v_mov_b32_e32 v13, v22
	v_pk_mul_f32 v[10:11], v[12:13], v[10:11]
	v_mov_b32_e32 v22, v15
	v_add_f32_e32 v10, v30, v10
	v_add_f32_e32 v14, v10, v11
	v_and_b32_e32 v11, 0xffff0000, v39
	v_and_b32_e32 v10, 0xffff0000, v35
	v_pk_mul_f32 v[10:11], v[22:23], v[10:11]
	v_mov_b32_e32 v12, v16
	v_add_f32_e32 v10, v31, v10
	v_add_f32_e32 v15, v10, v11
	v_lshlrev_b32_e32 v11, 16, v38
	v_lshlrev_b32_e32 v10, 16, v34
	v_mov_b32_e32 v13, v24
	v_pk_mul_f32 v[10:11], v[12:13], v[10:11]
	v_mov_b32_e32 v24, v17
	v_add_f32_e32 v10, v32, v10
	v_add_f32_e32 v12, v10, v11
	v_and_b32_e32 v11, 0xffff0000, v38
	v_and_b32_e32 v10, 0xffff0000, v34
	v_pk_mul_f32 v[10:11], v[24:25], v[10:11]
	v_cvt_pk_bf16_f32 v60, v28, v26
	v_cvt_pk_bf16_f32 v61, v18, v19
	v_cvt_pk_bf16_f32 v62, v14, v15
	s_nop 0
	v_add_f32_e32 v10, v33, v10
	v_add_f32_e32 v10, v10, v11
	v_cvt_pk_bf16_f32 v63, v12, v10
	ds_read_b128 v[26:29], v9 offset:10496
	ds_read_b128 v[30:33], v9 offset:10512
	s_waitcnt vmcnt(9)
	v_cndmask_b32_e32 v46, 0, v229, vcc
	v_cndmask_b32_e32 v47, 0, v228, vcc
	v_cndmask_b32_e32 v64, 0, v227, vcc
	v_cndmask_b32_e32 v65, 0, v226, vcc
	ds_read_b128 v[10:13], v9 offset:8448
	ds_read_b128 v[34:37], v9 offset:8464
	s_waitcnt vmcnt(9)
	v_cndmask_b32_e64 v66, 0, v233, s[0:1]
	v_cndmask_b32_e64 v67, 0, v232, s[0:1]
	v_cndmask_b32_e64 v68, 0, v231, s[0:1]
	v_cndmask_b32_e64 v69, 0, v230, s[0:1]
	ds_read_b128 v[14:17], v9 offset:8960
	ds_read_b128 v[38:41], v9 offset:8976
	v_lshlrev_b32_e32 v43, 16, v69
	v_lshlrev_b32_e32 v42, 16, v65
	s_waitcnt lgkmcnt(3)
	v_mov_b32_e32 v44, v10
	s_waitcnt lgkmcnt(1)
	v_mov_b32_e32 v45, v14
	v_pk_mul_f32 v[42:43], v[44:45], v[42:43]
	v_mov_b32_e32 v14, v11
	v_add_f32_e32 v10, v26, v42
	v_add_f32_e32 v44, v10, v43
	v_and_b32_e32 v43, 0xffff0000, v69
	v_and_b32_e32 v42, 0xffff0000, v65
	v_pk_mul_f32 v[10:11], v[14:15], v[42:43]
	v_mov_b32_e32 v14, v12
	v_add_f32_e32 v10, v27, v10
	v_add_f32_e32 v42, v10, v11
	v_lshlrev_b32_e32 v11, 16, v68
	v_lshlrev_b32_e32 v10, 16, v64
	v_mov_b32_e32 v15, v16
	v_pk_mul_f32 v[10:11], v[14:15], v[10:11]
	v_mov_b32_e32 v16, v13
	v_add_f32_e32 v10, v28, v10
	v_add_f32_e32 v43, v10, v11
	v_and_b32_e32 v11, 0xffff0000, v68
	v_and_b32_e32 v10, 0xffff0000, v64
	v_pk_mul_f32 v[10:11], v[16:17], v[10:11]
	v_mov_b32_e32 v12, v34
	v_add_f32_e32 v10, v29, v10
	v_add_f32_e32 v45, v10, v11
	v_lshlrev_b32_e32 v11, 16, v67
	v_lshlrev_b32_e32 v10, 16, v47
	s_waitcnt lgkmcnt(0)
	v_mov_b32_e32 v13, v38
	v_pk_mul_f32 v[10:11], v[12:13], v[10:11]
	v_mov_b32_e32 v38, v35
	v_add_f32_e32 v10, v30, v10
	v_add_f32_e32 v30, v10, v11
	v_and_b32_e32 v11, 0xffff0000, v67
	v_and_b32_e32 v10, 0xffff0000, v47
	v_pk_mul_f32 v[10:11], v[38:39], v[10:11]
	v_mov_b32_e32 v12, v36
	v_add_f32_e32 v10, v31, v10
	v_add_f32_e32 v31, v10, v11
	v_lshlrev_b32_e32 v11, 16, v66
	v_lshlrev_b32_e32 v10, 16, v46
	v_mov_b32_e32 v13, v40
	v_pk_mul_f32 v[10:11], v[12:13], v[10:11]
	v_mov_b32_e32 v40, v37
	v_add_f32_e32 v10, v32, v10
	v_add_f32_e32 v32, v10, v11
	v_and_b32_e32 v11, 0xffff0000, v66
	v_and_b32_e32 v10, 0xffff0000, v46
	v_pk_mul_f32 v[10:11], v[40:41], v[10:11]
	s_waitcnt vmcnt(9)
	v_cndmask_b32_e64 v34, 0, v237, s[6:7]
	v_add_f32_e32 v10, v33, v10
	v_add_f32_e32 v33, v10, v11
	v_cndmask_b32_e64 v35, 0, v236, s[6:7]
	v_cndmask_b32_e64 v36, 0, v235, s[6:7]
	v_cndmask_b32_e64 v37, 0, v234, s[6:7]
	ds_read_b128 v[10:13], v9 offset:9472
	ds_read_b128 v[14:17], v9 offset:9488
	s_waitcnt vmcnt(9)
	v_cndmask_b32_e64 v38, 0, v241, s[4:5]
	v_cndmask_b32_e64 v39, 0, v240, s[4:5]
	v_cndmask_b32_e64 v40, 0, v239, s[4:5]
	v_cndmask_b32_e64 v41, 0, v238, s[4:5]
	ds_read_b128 v[18:21], v9 offset:9984
	ds_read_b128 v[22:25], v9 offset:10000
	v_lshlrev_b32_e32 v27, 16, v41
	v_lshlrev_b32_e32 v26, 16, v37
	s_waitcnt lgkmcnt(3)
	v_mov_b32_e32 v28, v10
	s_waitcnt lgkmcnt(1)
	v_mov_b32_e32 v29, v18
	v_pk_mul_f32 v[26:27], v[28:29], v[26:27]
	v_mov_b32_e32 v18, v11
	v_add_f32_e32 v10, v44, v26
	v_add_f32_e32 v28, v10, v27
	v_and_b32_e32 v27, 0xffff0000, v41
	v_and_b32_e32 v26, 0xffff0000, v37
	v_pk_mul_f32 v[10:11], v[18:19], v[26:27]
	v_mov_b32_e32 v18, v12
	v_add_f32_e32 v10, v42, v10
	v_add_f32_e32 v26, v10, v11
	v_lshlrev_b32_e32 v11, 16, v40
	v_lshlrev_b32_e32 v10, 16, v36
	v_mov_b32_e32 v19, v20
	v_pk_mul_f32 v[10:11], v[18:19], v[10:11]
	v_mov_b32_e32 v20, v13
	v_add_f32_e32 v10, v43, v10
	v_add_f32_e32 v18, v10, v11
	v_and_b32_e32 v11, 0xffff0000, v40
	v_and_b32_e32 v10, 0xffff0000, v36
	v_pk_mul_f32 v[10:11], v[20:21], v[10:11]
	v_mov_b32_e32 v12, v14
	v_add_f32_e32 v10, v45, v10
	v_add_f32_e32 v19, v10, v11
	v_lshlrev_b32_e32 v11, 16, v39
	v_lshlrev_b32_e32 v10, 16, v35
	s_waitcnt lgkmcnt(0)
	v_mov_b32_e32 v13, v22
	v_pk_mul_f32 v[10:11], v[12:13], v[10:11]
	v_mov_b32_e32 v22, v15
	v_add_f32_e32 v10, v30, v10
	v_add_f32_e32 v14, v10, v11
	v_and_b32_e32 v11, 0xffff0000, v39
	v_and_b32_e32 v10, 0xffff0000, v35
	v_pk_mul_f32 v[10:11], v[22:23], v[10:11]
	v_mov_b32_e32 v12, v16
	v_add_f32_e32 v10, v31, v10
	v_add_f32_e32 v15, v10, v11
	v_lshlrev_b32_e32 v11, 16, v38
	v_lshlrev_b32_e32 v10, 16, v34
	v_mov_b32_e32 v13, v24
	v_pk_mul_f32 v[10:11], v[12:13], v[10:11]
	v_mov_b32_e32 v24, v17
	v_add_f32_e32 v10, v32, v10
	v_add_f32_e32 v12, v10, v11
	v_and_b32_e32 v11, 0xffff0000, v38
	v_and_b32_e32 v10, 0xffff0000, v34
	v_pk_mul_f32 v[10:11], v[24:25], v[10:11]
	v_cvt_pk_bf16_f32 v64, v28, v26
	v_cvt_pk_bf16_f32 v65, v18, v19
	v_cvt_pk_bf16_f32 v66, v14, v15
	s_nop 0
	v_add_f32_e32 v10, v33, v10
	v_add_f32_e32 v10, v10, v11
	v_cvt_pk_bf16_f32 v67, v12, v10
	ds_read_b128 v[26:29], v9 offset:10560
	ds_read_b128 v[30:33], v9 offset:10576
	s_waitcnt vmcnt(8)
	v_cndmask_b32_e32 v46, 0, v245, vcc
	v_cndmask_b32_e32 v47, 0, v244, vcc
	v_cndmask_b32_e32 v68, 0, v243, vcc
	v_cndmask_b32_e32 v69, 0, v242, vcc
	ds_read_b128 v[10:13], v9 offset:8512
	ds_read_b128 v[34:37], v9 offset:8528
	s_waitcnt vmcnt(8)
	v_cndmask_b32_e64 v70, 0, v249, s[0:1]
	v_cndmask_b32_e64 v71, 0, v248, s[0:1]
	v_cndmask_b32_e64 v72, 0, v247, s[0:1]
	v_cndmask_b32_e64 v73, 0, v246, s[0:1]
	ds_read_b128 v[14:17], v9 offset:9024
	ds_read_b128 v[38:41], v9 offset:9040
	v_lshlrev_b32_e32 v43, 16, v73
	v_lshlrev_b32_e32 v42, 16, v69
	s_waitcnt lgkmcnt(3)
	v_mov_b32_e32 v44, v10
	s_waitcnt lgkmcnt(1)
	v_mov_b32_e32 v45, v14
	v_pk_mul_f32 v[42:43], v[44:45], v[42:43]
	v_mov_b32_e32 v14, v11
	v_add_f32_e32 v10, v26, v42
	v_add_f32_e32 v44, v10, v43
	v_and_b32_e32 v43, 0xffff0000, v73
	v_and_b32_e32 v42, 0xffff0000, v69
	v_pk_mul_f32 v[10:11], v[14:15], v[42:43]
	v_mov_b32_e32 v14, v12
	v_add_f32_e32 v10, v27, v10
	v_add_f32_e32 v42, v10, v11
	v_lshlrev_b32_e32 v11, 16, v72
	v_lshlrev_b32_e32 v10, 16, v68
	v_mov_b32_e32 v15, v16
	v_pk_mul_f32 v[10:11], v[14:15], v[10:11]
	v_mov_b32_e32 v16, v13
	v_add_f32_e32 v10, v28, v10
	v_add_f32_e32 v43, v10, v11
	v_and_b32_e32 v11, 0xffff0000, v72
	v_and_b32_e32 v10, 0xffff0000, v68
	v_pk_mul_f32 v[10:11], v[16:17], v[10:11]
	v_mov_b32_e32 v12, v34
	v_add_f32_e32 v10, v29, v10
	v_add_f32_e32 v45, v10, v11
	v_lshlrev_b32_e32 v11, 16, v71
	v_lshlrev_b32_e32 v10, 16, v47
	s_waitcnt lgkmcnt(0)
	v_mov_b32_e32 v13, v38
	v_pk_mul_f32 v[10:11], v[12:13], v[10:11]
	v_mov_b32_e32 v38, v35
	v_add_f32_e32 v10, v30, v10
	v_add_f32_e32 v30, v10, v11
	v_and_b32_e32 v11, 0xffff0000, v71
	v_and_b32_e32 v10, 0xffff0000, v47
	v_pk_mul_f32 v[10:11], v[38:39], v[10:11]
	v_mov_b32_e32 v12, v36
	v_add_f32_e32 v10, v31, v10
	v_add_f32_e32 v31, v10, v11
	v_lshlrev_b32_e32 v11, 16, v70
	v_lshlrev_b32_e32 v10, 16, v46
	v_mov_b32_e32 v13, v40
	v_pk_mul_f32 v[10:11], v[12:13], v[10:11]
	v_mov_b32_e32 v40, v37
	v_add_f32_e32 v10, v32, v10
	v_add_f32_e32 v32, v10, v11
	v_and_b32_e32 v11, 0xffff0000, v70
	v_and_b32_e32 v10, 0xffff0000, v46
	v_pk_mul_f32 v[10:11], v[40:41], v[10:11]
	s_waitcnt vmcnt(8)
	v_cndmask_b32_e64 v34, 0, v255, s[6:7]
	v_add_f32_e32 v10, v33, v10
	v_add_f32_e32 v33, v10, v11
	v_cndmask_b32_e64 v35, 0, v254, s[6:7]
	v_cndmask_b32_e64 v36, 0, v253, s[6:7]
	v_cndmask_b32_e64 v37, 0, v252, s[6:7]
	ds_read_b128 v[10:13], v9 offset:9536
	ds_read_b128 v[14:17], v9 offset:9552
	s_waitcnt vmcnt(8)
	v_cndmask_b32_e64 v38, 0, v171, s[4:5]
	v_cndmask_b32_e64 v39, 0, v170, s[4:5]
	v_cndmask_b32_e64 v40, 0, v169, s[4:5]
	v_cndmask_b32_e64 v41, 0, v168, s[4:5]
	ds_read_b128 v[18:21], v9 offset:10048
	ds_read_b128 v[22:25], v9 offset:10064
	v_lshlrev_b32_e32 v27, 16, v41
	v_lshlrev_b32_e32 v26, 16, v37
	s_waitcnt lgkmcnt(3)
	v_mov_b32_e32 v28, v10
	s_waitcnt lgkmcnt(1)
	v_mov_b32_e32 v29, v18
	v_pk_mul_f32 v[26:27], v[28:29], v[26:27]
	v_mov_b32_e32 v18, v11
	v_add_f32_e32 v10, v44, v26
	v_add_f32_e32 v28, v10, v27
	v_and_b32_e32 v27, 0xffff0000, v41
	v_and_b32_e32 v26, 0xffff0000, v37
	v_pk_mul_f32 v[10:11], v[18:19], v[26:27]
	v_mov_b32_e32 v18, v12
	v_add_f32_e32 v10, v42, v10
	v_add_f32_e32 v26, v10, v11
	v_lshlrev_b32_e32 v11, 16, v40
	v_lshlrev_b32_e32 v10, 16, v36
	v_mov_b32_e32 v19, v20
	v_pk_mul_f32 v[10:11], v[18:19], v[10:11]
	v_mov_b32_e32 v20, v13
	v_add_f32_e32 v10, v43, v10
	v_add_f32_e32 v18, v10, v11
	v_and_b32_e32 v11, 0xffff0000, v40
	v_and_b32_e32 v10, 0xffff0000, v36
	v_pk_mul_f32 v[10:11], v[20:21], v[10:11]
	v_mov_b32_e32 v12, v14
	v_add_f32_e32 v10, v45, v10
	v_add_f32_e32 v19, v10, v11
	v_lshlrev_b32_e32 v11, 16, v39
	v_lshlrev_b32_e32 v10, 16, v35
	s_waitcnt lgkmcnt(0)
	v_mov_b32_e32 v13, v22
	v_pk_mul_f32 v[10:11], v[12:13], v[10:11]
	v_mov_b32_e32 v22, v15
	v_add_f32_e32 v10, v30, v10
	v_add_f32_e32 v14, v10, v11
	v_and_b32_e32 v11, 0xffff0000, v39
	v_and_b32_e32 v10, 0xffff0000, v35
	v_pk_mul_f32 v[10:11], v[22:23], v[10:11]
	v_mov_b32_e32 v12, v16
	v_add_f32_e32 v10, v31, v10
	v_add_f32_e32 v15, v10, v11
	v_lshlrev_b32_e32 v11, 16, v38
	v_lshlrev_b32_e32 v10, 16, v34
	v_mov_b32_e32 v13, v24
	v_pk_mul_f32 v[10:11], v[12:13], v[10:11]
	v_mov_b32_e32 v24, v17
	v_add_f32_e32 v10, v32, v10
	v_add_f32_e32 v12, v10, v11
	v_and_b32_e32 v11, 0xffff0000, v38
	v_and_b32_e32 v10, 0xffff0000, v34
	v_pk_mul_f32 v[10:11], v[24:25], v[10:11]
	v_cvt_pk_bf16_f32 v68, v28, v26
	v_cvt_pk_bf16_f32 v69, v18, v19
	v_cvt_pk_bf16_f32 v70, v14, v15
	s_nop 0
	v_add_f32_e32 v10, v33, v10
	v_add_f32_e32 v10, v10, v11
	v_cvt_pk_bf16_f32 v71, v12, v10
	ds_read_b128 v[26:29], v9 offset:10624
	ds_read_b128 v[30:33], v9 offset:10640
	s_waitcnt vmcnt(4)
	v_cndmask_b32_e32 v46, 0, v181, vcc
	v_cndmask_b32_e32 v47, 0, v180, vcc
	v_cndmask_b32_e32 v72, 0, v179, vcc
	v_cndmask_b32_e32 v73, 0, v178, vcc
	ds_read_b128 v[10:13], v9 offset:8576
	ds_read_b128 v[34:37], v9 offset:8592
	s_waitcnt vmcnt(4)
	v_cndmask_b32_e64 v74, 0, v185, s[0:1]
	v_cndmask_b32_e64 v75, 0, v184, s[0:1]
	v_cndmask_b32_e64 v76, 0, v183, s[0:1]
	v_cndmask_b32_e64 v77, 0, v182, s[0:1]
	ds_read_b128 v[14:17], v9 offset:9088
	ds_read_b128 v[38:41], v9 offset:9104
	v_lshlrev_b32_e32 v43, 16, v77
	v_lshlrev_b32_e32 v42, 16, v73
	s_waitcnt lgkmcnt(3)
	v_mov_b32_e32 v44, v10
	s_waitcnt lgkmcnt(1)
	v_mov_b32_e32 v45, v14
	v_pk_mul_f32 v[42:43], v[44:45], v[42:43]
	v_mov_b32_e32 v14, v11
	v_add_f32_e32 v10, v26, v42
	v_add_f32_e32 v44, v10, v43
	v_and_b32_e32 v43, 0xffff0000, v77
	v_and_b32_e32 v42, 0xffff0000, v73
	v_pk_mul_f32 v[10:11], v[14:15], v[42:43]
	v_mov_b32_e32 v14, v12
	v_add_f32_e32 v10, v27, v10
	v_add_f32_e32 v42, v10, v11
	v_lshlrev_b32_e32 v11, 16, v76
	v_lshlrev_b32_e32 v10, 16, v72
	v_mov_b32_e32 v15, v16
	v_pk_mul_f32 v[10:11], v[14:15], v[10:11]
	v_mov_b32_e32 v16, v13
	v_add_f32_e32 v10, v28, v10
	v_add_f32_e32 v43, v10, v11
	v_and_b32_e32 v11, 0xffff0000, v76
	v_and_b32_e32 v10, 0xffff0000, v72
	v_pk_mul_f32 v[10:11], v[16:17], v[10:11]
	v_mov_b32_e32 v12, v34
	v_add_f32_e32 v10, v29, v10
	v_add_f32_e32 v45, v10, v11
	v_lshlrev_b32_e32 v11, 16, v75
	v_lshlrev_b32_e32 v10, 16, v47
	s_waitcnt lgkmcnt(0)
	v_mov_b32_e32 v13, v38
	v_pk_mul_f32 v[10:11], v[12:13], v[10:11]
	v_mov_b32_e32 v38, v35
	v_add_f32_e32 v10, v30, v10
	v_add_f32_e32 v30, v10, v11
	v_and_b32_e32 v11, 0xffff0000, v75
	v_and_b32_e32 v10, 0xffff0000, v47
	v_pk_mul_f32 v[10:11], v[38:39], v[10:11]
	v_mov_b32_e32 v12, v36
	v_add_f32_e32 v10, v31, v10
	v_add_f32_e32 v31, v10, v11
	v_lshlrev_b32_e32 v11, 16, v74
	v_lshlrev_b32_e32 v10, 16, v46
	v_mov_b32_e32 v13, v40
	v_pk_mul_f32 v[10:11], v[12:13], v[10:11]
	v_mov_b32_e32 v40, v37
	v_add_f32_e32 v10, v32, v10
	v_add_f32_e32 v32, v10, v11
	v_and_b32_e32 v11, 0xffff0000, v74
	v_and_b32_e32 v10, 0xffff0000, v46
	v_pk_mul_f32 v[10:11], v[40:41], v[10:11]
	s_waitcnt vmcnt(4)
	v_cndmask_b32_e64 v34, 0, v189, s[6:7]
	v_add_f32_e32 v10, v33, v10
	v_add_f32_e32 v33, v10, v11
	v_cndmask_b32_e64 v35, 0, v188, s[6:7]
	v_cndmask_b32_e64 v36, 0, v187, s[6:7]
	v_cndmask_b32_e64 v37, 0, v186, s[6:7]
	ds_read_b128 v[10:13], v9 offset:9600
	ds_read_b128 v[14:17], v9 offset:9616
	s_waitcnt vmcnt(4)
	v_cndmask_b32_e64 v38, 0, v193, s[4:5]
	v_cndmask_b32_e64 v39, 0, v192, s[4:5]
	v_cndmask_b32_e64 v40, 0, v191, s[4:5]
	v_cndmask_b32_e64 v41, 0, v190, s[4:5]
	ds_read_b128 v[18:21], v9 offset:10112
	ds_read_b128 v[22:25], v9 offset:10128
	v_lshlrev_b32_e32 v27, 16, v41
	v_lshlrev_b32_e32 v26, 16, v37
	s_waitcnt lgkmcnt(3)
	v_mov_b32_e32 v28, v10
	s_waitcnt lgkmcnt(1)
	v_mov_b32_e32 v29, v18
	v_pk_mul_f32 v[26:27], v[28:29], v[26:27]
	v_mov_b32_e32 v18, v11
	v_add_f32_e32 v10, v44, v26
	v_add_f32_e32 v28, v10, v27
	v_and_b32_e32 v27, 0xffff0000, v41
	v_and_b32_e32 v26, 0xffff0000, v37
	v_pk_mul_f32 v[10:11], v[18:19], v[26:27]
	v_mov_b32_e32 v18, v12
	v_add_f32_e32 v10, v42, v10
	v_add_f32_e32 v26, v10, v11
	v_lshlrev_b32_e32 v11, 16, v40
	v_lshlrev_b32_e32 v10, 16, v36
	v_mov_b32_e32 v19, v20
	v_pk_mul_f32 v[10:11], v[18:19], v[10:11]
	v_mov_b32_e32 v20, v13
	v_add_f32_e32 v10, v43, v10
	v_add_f32_e32 v18, v10, v11
	v_and_b32_e32 v11, 0xffff0000, v40
	v_and_b32_e32 v10, 0xffff0000, v36
	v_pk_mul_f32 v[10:11], v[20:21], v[10:11]
	v_mov_b32_e32 v12, v14
	v_add_f32_e32 v10, v45, v10
	v_add_f32_e32 v19, v10, v11
	v_lshlrev_b32_e32 v11, 16, v39
	v_lshlrev_b32_e32 v10, 16, v35
	s_waitcnt lgkmcnt(0)
	v_mov_b32_e32 v13, v22
	v_pk_mul_f32 v[10:11], v[12:13], v[10:11]
	v_mov_b32_e32 v22, v15
	v_add_f32_e32 v10, v30, v10
	v_add_f32_e32 v14, v10, v11
	v_and_b32_e32 v11, 0xffff0000, v39
	v_and_b32_e32 v10, 0xffff0000, v35
	v_pk_mul_f32 v[10:11], v[22:23], v[10:11]
	v_mov_b32_e32 v12, v16
	v_add_f32_e32 v10, v31, v10
	v_add_f32_e32 v15, v10, v11
	v_lshlrev_b32_e32 v11, 16, v38
	v_lshlrev_b32_e32 v10, 16, v34
	v_mov_b32_e32 v13, v24
	v_pk_mul_f32 v[10:11], v[12:13], v[10:11]
	v_mov_b32_e32 v24, v17
	v_add_f32_e32 v10, v32, v10
	v_add_f32_e32 v12, v10, v11
	v_and_b32_e32 v11, 0xffff0000, v38
	v_and_b32_e32 v10, 0xffff0000, v34
	v_pk_mul_f32 v[10:11], v[24:25], v[10:11]
	v_cvt_pk_bf16_f32 v72, v28, v26
	v_cvt_pk_bf16_f32 v73, v18, v19
	v_cvt_pk_bf16_f32 v74, v14, v15
	v_lshlrev_b32_e32 v38, 3, v93
	v_add_f32_e32 v10, v33, v10
	v_add_f32_e32 v10, v10, v11
	v_cvt_pk_bf16_f32 v75, v12, v10
	s_nop 0
	s_nop 0
	ds_read_b128 v[18:21], v9 offset:10688
	ds_read_b128 v[22:25], v9 offset:10704
	v_or_b32_e32 v39, 16, v38
	s_waitcnt vmcnt(0)
	v_cndmask_b32_e32 v40, 0, v197, vcc
	v_cndmask_b32_e32 v41, 0, v196, vcc
	v_cndmask_b32_e32 v42, 0, v195, vcc
	v_cndmask_b32_e32 v43, 0, v194, vcc
	ds_read_b128 v[10:13], v9 offset:8640
	ds_read_b128 v[26:29], v9 offset:8656
	s_waitcnt vmcnt(0)
	v_cndmask_b32_e64 v44, 0, v201, s[0:1]
	v_cndmask_b32_e64 v45, 0, v200, s[0:1]
	v_cndmask_b32_e64 v46, 0, v199, s[0:1]
	v_cndmask_b32_e64 v47, 0, v198, s[0:1]
	ds_read_b128 v[14:17], v9 offset:9152
	ds_read_b128 v[30:33], v9 offset:9168
	v_lshlrev_b32_e32 v35, 16, v47
	v_lshlrev_b32_e32 v34, 16, v43
	s_waitcnt lgkmcnt(3)
	v_mov_b32_e32 v36, v10
	s_waitcnt lgkmcnt(1)
	v_mov_b32_e32 v37, v14
	v_pk_mul_f32 v[34:35], v[36:37], v[34:35]
	v_mov_b32_e32 v14, v11
	v_add_f32_e32 v10, v18, v34
	v_add_f32_e32 v36, v10, v35
	v_and_b32_e32 v35, 0xffff0000, v47
	v_and_b32_e32 v34, 0xffff0000, v43
	v_pk_mul_f32 v[10:11], v[14:15], v[34:35]
	v_mov_b32_e32 v14, v12
	v_add_f32_e32 v10, v19, v10
	v_add_f32_e32 v34, v10, v11
	v_lshlrev_b32_e32 v11, 16, v46
	v_lshlrev_b32_e32 v10, 16, v42
	v_mov_b32_e32 v15, v16
	v_pk_mul_f32 v[10:11], v[14:15], v[10:11]
	v_mov_b32_e32 v16, v13
	v_add_f32_e32 v10, v20, v10
	v_add_f32_e32 v35, v10, v11
	v_and_b32_e32 v11, 0xffff0000, v46
	v_and_b32_e32 v10, 0xffff0000, v42
	v_pk_mul_f32 v[10:11], v[16:17], v[10:11]
	v_mov_b32_e32 v12, v26
	v_add_f32_e32 v10, v21, v10
	v_add_f32_e32 v37, v10, v11
	v_lshlrev_b32_e32 v11, 16, v45
	v_lshlrev_b32_e32 v10, 16, v41
	s_waitcnt lgkmcnt(0)
	v_mov_b32_e32 v13, v30
	v_pk_mul_f32 v[10:11], v[12:13], v[10:11]
	v_mov_b32_e32 v30, v27
	v_add_f32_e32 v10, v22, v10
	v_add_f32_e32 v22, v10, v11
	v_and_b32_e32 v11, 0xffff0000, v45
	v_and_b32_e32 v10, 0xffff0000, v41
	v_pk_mul_f32 v[10:11], v[30:31], v[10:11]
	v_mov_b32_e32 v12, v28
	v_add_f32_e32 v10, v23, v10
	v_add_f32_e32 v23, v10, v11
	v_lshlrev_b32_e32 v11, 16, v44
	v_lshlrev_b32_e32 v10, 16, v40
	v_mov_b32_e32 v13, v32
	v_pk_mul_f32 v[10:11], v[12:13], v[10:11]
	v_mov_b32_e32 v32, v29
	v_add_f32_e32 v10, v24, v10
	v_add_f32_e32 v24, v10, v11
	v_and_b32_e32 v11, 0xffff0000, v44
	v_and_b32_e32 v10, 0xffff0000, v40
	v_pk_mul_f32 v[10:11], v[32:33], v[10:11]
	s_waitcnt vmcnt(0)
	v_cndmask_b32_e64 v26, 0, v205, s[6:7]
	v_add_f32_e32 v10, v25, v10
	v_add_f32_e32 v25, v10, v11
	v_cndmask_b32_e64 v27, 0, v204, s[6:7]
	v_cndmask_b32_e64 v28, 0, v203, s[6:7]
	v_cndmask_b32_e64 v29, 0, v202, s[6:7]
	ds_read_b128 v[0:3], v9 offset:9664
	ds_read_b128 v[10:13], v9 offset:9680
	s_waitcnt vmcnt(0)
	v_cndmask_b32_e64 v30, 0, v209, s[4:5]
	v_cndmask_b32_e64 v31, 0, v208, s[4:5]
	v_cndmask_b32_e64 v32, 0, v207, s[4:5]
	v_cndmask_b32_e64 v33, 0, v206, s[4:5]
	ds_read_b128 v[4:7], v9 offset:10176
	ds_read_b128 v[14:17], v9 offset:10192
	v_lshlrev_b32_e32 v19, 16, v33
	v_lshlrev_b32_e32 v18, 16, v29
	s_waitcnt lgkmcnt(3)
	v_mov_b32_e32 v20, v0
	s_waitcnt lgkmcnt(1)
	v_mov_b32_e32 v21, v4
	v_pk_mul_f32 v[18:19], v[20:21], v[18:19]
	v_mov_b32_e32 v4, v1
	v_add_f32_e32 v0, v36, v18
	v_add_f32_e32 v9, v0, v19
	v_and_b32_e32 v19, 0xffff0000, v33
	v_and_b32_e32 v18, 0xffff0000, v29
	v_pk_mul_f32 v[0:1], v[4:5], v[18:19]
	v_mov_b32_e32 v4, v2
	v_add_f32_e32 v0, v34, v0
	v_add_f32_e32 v18, v0, v1
	v_lshlrev_b32_e32 v1, 16, v32
	v_lshlrev_b32_e32 v0, 16, v28
	v_mov_b32_e32 v5, v6
	v_pk_mul_f32 v[0:1], v[4:5], v[0:1]
	v_mov_b32_e32 v6, v3
	v_add_f32_e32 v0, v35, v0
	v_add_f32_e32 v4, v0, v1
	v_and_b32_e32 v1, 0xffff0000, v32
	v_and_b32_e32 v0, 0xffff0000, v28
	v_pk_mul_f32 v[0:1], v[6:7], v[0:1]
	v_mov_b32_e32 v2, v10
	v_add_f32_e32 v0, v37, v0
	v_add_f32_e32 v5, v0, v1
	v_lshlrev_b32_e32 v1, 16, v31
	v_lshlrev_b32_e32 v0, 16, v27
	s_waitcnt lgkmcnt(0)
	v_mov_b32_e32 v3, v14
	v_pk_mul_f32 v[0:1], v[2:3], v[0:1]
	v_mov_b32_e32 v14, v11
	v_add_f32_e32 v0, v22, v0
	v_add_f32_e32 v6, v0, v1
	v_and_b32_e32 v1, 0xffff0000, v31
	v_and_b32_e32 v0, 0xffff0000, v27
	v_pk_mul_f32 v[0:1], v[14:15], v[0:1]
	v_mov_b32_e32 v2, v12
	v_add_f32_e32 v0, v23, v0
	v_add_f32_e32 v7, v0, v1
	v_lshlrev_b32_e32 v1, 16, v30
	v_lshlrev_b32_e32 v0, 16, v26
	v_mov_b32_e32 v3, v16
	v_pk_mul_f32 v[0:1], v[2:3], v[0:1]
	v_mov_b32_e32 v16, v13
	v_add_f32_e32 v0, v24, v0
	v_add_f32_e32 v2, v0, v1
	v_and_b32_e32 v1, 0xffff0000, v30
	v_and_b32_e32 v0, 0xffff0000, v26
	v_pk_mul_f32 v[0:1], v[16:17], v[0:1]
	v_cvt_pk_bf16_f32 v76, v9, v18
	v_cvt_pk_bf16_f32 v77, v4, v5
	v_cvt_pk_bf16_f32 v78, v6, v7
	v_cmp_eq_u32_e32 vcc, v38, v94
	v_add_f32_e32 v0, v25, v0
	v_add_f32_e32 v0, v0, v1
	v_cvt_pk_bf16_f32 v79, v2, v0
	v_or_b32_e32 v2, 1, v38
	v_cndmask_b32_e32 v0, 0, v134, vcc
	v_or_b32_e32 v1, 2, v38
	v_cmp_eq_u32_e32 vcc, v2, v94
	v_or_b32_e32 v4, 3, v38
	v_or_b32_e32 v3, 4, v38
	v_cndmask_b32_e32 v2, 0, v134, vcc
	v_cmp_eq_u32_e32 vcc, v1, v94
	v_or_b32_e32 v5, 6, v38
	v_or_b32_e32 v6, 5, v38
	v_cndmask_b32_e32 v1, 0, v134, vcc
	v_cmp_eq_u32_e32 vcc, v4, v94
	v_or_b32_e32 v7, 7, v38
	v_or_b32_e32 v11, 17, v38
	v_cndmask_b32_e32 v4, 0, v134, vcc
	v_cmp_eq_u32_e32 vcc, v3, v94
	v_or_b32_e32 v10, 18, v38
	v_or_b32_e32 v13, 19, v38
	v_cndmask_b32_e32 v3, 0, v134, vcc
	v_cmp_eq_u32_e32 vcc, v5, v94
	v_or_b32_e32 v12, 20, v38
	v_or_b32_e32 v14, 22, v38
	v_cndmask_b32_e32 v5, 0, v134, vcc
	v_cmp_eq_u32_e32 vcc, v6, v94
	v_or_b32_e32 v15, 21, v38
	v_or_b32_e32 v16, 23, v38
	v_cndmask_b32_e32 v6, 0, v134, vcc
	v_cmp_eq_u32_e32 vcc, v7, v94
	v_and_b32_e32 v18, 64, v132
	v_xor_b32_e32 v17, 32, v132
	v_cndmask_b32_e32 v7, 0, v134, vcc
	v_cmp_eq_u32_e32 vcc, v39, v94
	v_add_u32_e32 v18, 64, v18
	s_lshl_b32 s4, s62, 8
	v_cndmask_b32_e32 v9, 0, v134, vcc
	v_cmp_eq_u32_e32 vcc, v11, v94
	s_add_i32 s4, s4, 16
	v_cmp_eq_u32_e64 s[0:1], 0, v93
	v_cndmask_b32_e32 v11, 0, v134, vcc
	v_cmp_eq_u32_e32 vcc, v10, v94
	v_lshl_add_u32 v139, v94, 3, s4
	v_perm_b32 v82, v6, v3, s83
	v_cndmask_b32_e32 v10, 0, v134, vcc
	v_cmp_eq_u32_e32 vcc, v13, v94
	v_perm_b32 v81, v4, v1, s83
	v_perm_b32 v83, v7, v5, s83
	v_cndmask_b32_e32 v13, 0, v134, vcc
	v_cmp_eq_u32_e32 vcc, v12, v94
	v_perm_b32 v80, v2, v0, s83
	v_perm_b32 v85, v13, v10, s83
	v_cndmask_b32_e32 v12, 0, v134, vcc
	v_cmp_eq_u32_e32 vcc, v14, v94
	v_perm_b32 v84, v11, v9, s83
	s_nop 0
	v_cndmask_b32_e32 v14, 0, v134, vcc
	v_cmp_eq_u32_e32 vcc, v15, v94
	s_nop 1
	v_cndmask_b32_e32 v15, 0, v134, vcc
	v_cmp_eq_u32_e32 vcc, v16, v94
	v_perm_b32 v86, v15, v12, s83
	s_nop 0
	v_cndmask_b32_e32 v16, 0, v134, vcc
	v_cmp_lt_i32_e32 vcc, v17, v18
	v_perm_b32 v87, v16, v14, s83
	s_nop 0
	v_cndmask_b32_e32 v17, v132, v17, vcc
	v_lshlrev_b32_e32 v140, 2, v17
	v_lshlrev_b32_e32 v175, 2, v91
	global_load_dword v172, v175, s[42:43]
	global_load_dword v173, v175, s[36:37]
	global_load_dword v174, v175, s[40:41]
	s_setprio 1
	v_xad_u32 v148, v88, v8, v95
	ds_read_b128 v[0:3], v148 offset:16384
	ds_read_b128 v[4:7], v148 offset:49152
	s_waitcnt lgkmcnt(1)
	v_mfma_f32_32x32x16_bf16 v[32:47], v[48:51], v[0:3], 0
	v_or_b32_e32 v0, 32, v88
	v_xad_u32 v150, v0, v8, v95
	s_waitcnt lgkmcnt(0)
	v_mfma_f32_32x32x16_bf16 v[16:31], v[48:51], v[4:7], 0
	ds_read_b128 v[0:3], v150 offset:16384
	ds_read_b128 v[4:7], v150 offset:49152
	s_waitcnt lgkmcnt(1)
	v_mfma_f32_32x32x16_bf16 v[32:47], v[52:55], v[0:3], v[32:47]
	v_or_b32_e32 v0, 64, v88
	v_xad_u32 v145, v0, v8, v95
	s_waitcnt lgkmcnt(0)
	v_mfma_f32_32x32x16_bf16 v[16:31], v[52:55], v[4:7], v[16:31]
	ds_read_b128 v[0:3], v145 offset:16384
	ds_read_b128 v[4:7], v145 offset:49152
	s_waitcnt lgkmcnt(1)
	v_mfma_f32_32x32x16_bf16 v[32:47], v[56:59], v[0:3], v[32:47]
	v_or_b32_e32 v0, 0x60, v88
	v_xad_u32 v149, v0, v8, v95
	s_waitcnt lgkmcnt(0)
	v_mfma_f32_32x32x16_bf16 v[16:31], v[56:59], v[4:7], v[16:31]
	ds_read_b128 v[0:3], v149 offset:16384
	ds_read_b128 v[4:7], v149 offset:49152
	s_waitcnt lgkmcnt(1)
	v_mfma_f32_32x32x16_bf16 v[32:47], v[60:63], v[0:3], v[32:47]
	v_or_b32_e32 v0, 0x80, v88
	v_xad_u32 v144, v0, v8, v95
	s_waitcnt lgkmcnt(0)
	v_mfma_f32_32x32x16_bf16 v[16:31], v[60:63], v[4:7], v[16:31]
	ds_read_b128 v[0:3], v144 offset:16384
	ds_read_b128 v[4:7], v144 offset:49152
	s_waitcnt lgkmcnt(1)
	v_mfma_f32_32x32x16_bf16 v[32:47], v[64:67], v[0:3], v[32:47]
	v_or_b32_e32 v0, 0xa0, v88
	v_xad_u32 v147, v0, v8, v95
	s_waitcnt lgkmcnt(0)
	v_mfma_f32_32x32x16_bf16 v[16:31], v[64:67], v[4:7], v[16:31]
	ds_read_b128 v[0:3], v147 offset:16384
	ds_read_b128 v[4:7], v147 offset:49152
	s_waitcnt lgkmcnt(1)
	v_mfma_f32_32x32x16_bf16 v[32:47], v[68:71], v[0:3], v[32:47]
	v_or_b32_e32 v0, 0xc0, v88
	v_xad_u32 v143, v0, v8, v95
	s_waitcnt lgkmcnt(0)
	v_mfma_f32_32x32x16_bf16 v[16:31], v[68:71], v[4:7], v[16:31]
	ds_read_b128 v[0:3], v143 offset:16384
	ds_read_b128 v[4:7], v143 offset:49152
	s_waitcnt lgkmcnt(1)
	v_mfma_f32_32x32x16_bf16 v[32:47], v[72:75], v[0:3], v[32:47]
	v_or_b32_e32 v0, 0xe0, v88
	v_xad_u32 v146, v0, v8, v95
	s_waitcnt lgkmcnt(0)
	v_mfma_f32_32x32x16_bf16 v[16:31], v[72:75], v[4:7], v[16:31]
	ds_read_b128 v[0:3], v146 offset:16384
	ds_read_b128 v[4:7], v146 offset:49152
	s_waitcnt lgkmcnt(1)
	v_mfma_f32_32x32x16_bf16 v[32:47], v[76:79], v[0:3], v[32:47]
	s_waitcnt lgkmcnt(0)
	v_mfma_f32_32x32x16_bf16 v[16:31], v[76:79], v[4:7], v[16:31]
	v_mfma_f32_32x32x16_bf16 v[0:15], v[48:51], v[80:83], 0
	v_mfma_f32_32x32x16_bf16 v[0:15], v[52:55], v[84:87], v[0:15]
	s_setprio 0
	v_lshlrev_b32_e32 v88, 2, v91
	s_waitcnt vmcnt(0)
	ds_read_b32 v251, v167
	v_mul_f32_e32 v97, 0xbfb8aa3b, v173
	v_mul_f32_e32 v96, 0xbfb8aa3b, v174
	v_fmamk_f32 v32, v32, 0xbfb8aa3b, v97
	v_fmamk_f32 v34, v34, 0xbfb8aa3b, v97
	v_fmamk_f32 v33, v33, 0xbfb8aa3b, v97
	v_fmamk_f32 v35, v35, 0xbfb8aa3b, v97
	v_fmamk_f32 v16, v16, 0xbfb8aa3b, v96
	v_fmamk_f32 v17, v17, 0xbfb8aa3b, v96
	v_exp_f32_e32 v32, v32
	v_exp_f32_e32 v34, v34
	v_exp_f32_e32 v33, v33
	v_exp_f32_e32 v107, v35
	v_exp_f32_e32 v91, v16
	v_exp_f32_e32 v98, v17
	v_add_f32_e32 v32, 1.0, v32
	v_add_f32_e32 v108, 1.0, v34
	v_add_f32_e32 v33, 1.0, v33
	v_rcp_f32_e32 v109, v32
	v_rcp_f32_e32 v111, v33
	v_add_f32_e32 v91, 1.0, v91
	v_rcp_f32_e32 v110, v91
	v_add_f32_e32 v98, 1.0, v98
	v_rcp_f32_e32 v112, v98
	v_fmamk_f32 v18, v18, 0xbfb8aa3b, v96
	v_exp_f32_e32 v18, v18
	v_fmamk_f32 v20, v20, 0xbfb8aa3b, v96
	v_add_f32_e32 v18, 1.0, v18
	v_exp_f32_e32 v20, v20
	v_fmamk_f32 v19, v19, 0xbfb8aa3b, v96
	v_exp_f32_e32 v19, v19
	v_fmamk_f32 v21, v21, 0xbfb8aa3b, v96
	s_waitcnt lgkmcnt(0)
	v_mul_f32_e32 v33, 0x3fb8aa3b, v251
	v_mul_f32_e32 v16, v109, v33
	v_exp_f32_e32 v32, v16
	v_mul_f32_e32 v17, v111, v33
	v_exp_f32_e32 v34, v17
	v_rcp_f32_e32 v16, v108
	v_rcp_f32_e32 v17, v18
	v_fma_f32 v18, -v32, v32, 1.0
	v_sqrt_f32_e32 v18, v18
	v_mul_f32_e32 v16, v16, v33
	v_add_f32_e32 v19, 1.0, v19
	v_mul_f32_e32 v18, v110, v18
	v_mul_f32_e32 v18, v0, v18
	v_exp_f32_e32 v0, v16
	v_add_f32_e32 v16, 1.0, v107
	v_rcp_f32_e32 v16, v16
	v_rcp_f32_e32 v19, v19
	v_fma_f32 v91, -v0, v0, 1.0
	v_sqrt_f32_e32 v91, v91
	v_mul_f32_e32 v16, v16, v33
	v_exp_f32_e32 v98, v16
	v_fmamk_f32 v16, v36, 0xbfb8aa3b, v97
	v_exp_f32_e32 v16, v16
	v_mul_f32_e32 v91, v17, v91
	v_add_f32_e32 v17, 1.0, v20
	v_fma_f32 v36, -v98, v98, 1.0
	v_add_f32_e32 v16, 1.0, v16
	v_rcp_f32_e32 v16, v16
	v_sqrt_f32_e32 v36, v36
	v_rcp_f32_e32 v17, v17
	v_mul_f32_e32 v16, v16, v33
	v_exp_f32_e32 v20, v16
	v_fmamk_f32 v16, v37, 0xbfb8aa3b, v97
	v_exp_f32_e32 v16, v16
	v_mul_f32_e32 v36, v19, v36
	v_fma_f32 v19, -v20, v20, 1.0
	v_sqrt_f32_e32 v19, v19
	v_add_f32_e32 v16, 1.0, v16
	v_rcp_f32_e32 v16, v16
	v_exp_f32_e32 v21, v21
	v_mul_f32_e32 v17, v17, v19
	v_mul_f32_e32 v19, v4, v17
	v_mul_f32_e32 v16, v16, v33
	v_exp_f32_e32 v37, v16
	v_fmamk_f32 v16, v38, 0xbfb8aa3b, v97
	v_exp_f32_e32 v16, v16
	v_add_f32_e32 v4, 1.0, v21
	v_fmamk_f32 v21, v22, 0xbfb8aa3b, v96
	v_add_f32_e32 v16, 1.0, v16
	v_rcp_f32_e32 v16, v16
	v_fma_f32 v17, -v37, v37, 1.0
	v_exp_f32_e32 v21, v21
	v_rcp_f32_e32 v4, v4
	v_mul_f32_e32 v16, v16, v33
	v_sqrt_f32_e32 v17, v17
	v_exp_f32_e32 v38, v16
	v_add_f32_e32 v16, 1.0, v21
	v_fmamk_f32 v21, v39, 0xbfb8aa3b, v97
	v_mul_f32_e32 v4, v4, v17
	v_fma_f32 v17, -v38, v38, 1.0
	v_rcp_f32_e32 v16, v16
	v_sqrt_f32_e32 v17, v17
	v_exp_f32_e32 v21, v21
	v_fmamk_f32 v22, v23, 0xbfb8aa3b, v96
	v_mul_f32_e32 v23, v16, v17
	v_add_f32_e32 v16, 1.0, v21
	v_rcp_f32_e32 v16, v16
	v_fmamk_f32 v21, v40, 0xbfb8aa3b, v97
	v_exp_f32_e32 v21, v21
	v_mul_f32_e32 v16, v16, v33
	v_exp_f32_e32 v39, v16
	v_add_f32_e32 v16, 1.0, v21
	v_rcp_f32_e32 v16, v16
	v_exp_f32_e32 v22, v22
	v_fmamk_f32 v21, v24, 0xbfb8aa3b, v96
	v_mul_f32_e32 v16, v16, v33
	v_add_f32_e32 v17, 1.0, v22
	v_fma_f32 v22, -v39, v39, 1.0
	v_sqrt_f32_e32 v24, v22
	v_exp_f32_e32 v22, v16
	v_fmamk_f32 v16, v41, 0xbfb8aa3b, v97
	v_exp_f32_e32 v16, v16
	v_exp_f32_e32 v21, v21
	v_fma_f32 v40, -v22, v22, 1.0
	v_rcp_f32_e32 v17, v17
	v_add_f32_e32 v16, 1.0, v16
	v_rcp_f32_e32 v16, v16
	v_add_f32_e32 v21, 1.0, v21
	v_rcp_f32_e32 v21, v21
	v_sqrt_f32_e32 v40, v40
	v_mul_f32_e32 v16, v16, v33
	v_mul_f32_e32 v24, v17, v24
	v_mul_f32_e32 v17, v21, v40
	v_exp_f32_e32 v40, v16
	v_fmamk_f32 v16, v42, 0xbfb8aa3b, v97
	v_fmamk_f32 v25, v25, 0xbfb8aa3b, v96
	v_exp_f32_e32 v16, v16
	v_exp_f32_e32 v25, v25
	v_fma_f32 v35, -v34, v34, 1.0
	v_sqrt_f32_e32 v35, v35
	v_add_f32_e32 v16, 1.0, v16
	v_add_f32_e32 v21, 1.0, v25
	v_rcp_f32_e32 v16, v16
	v_rcp_f32_e32 v25, v21
	v_fma_f32 v21, -v40, v40, 1.0
	v_sqrt_f32_e32 v41, v21
	v_fmamk_f32 v21, v26, 0xbfb8aa3b, v96
	v_mul_f32_e32 v16, v16, v33
	v_exp_f32_e32 v26, v21
	v_mul_f32_e32 v21, v8, v17
	v_mul_f32_e32 v8, v25, v41
	v_exp_f32_e32 v41, v16
	v_fmamk_f32 v16, v43, 0xbfb8aa3b, v97
	v_exp_f32_e32 v16, v16
	v_add_f32_e32 v17, 1.0, v26
	v_fma_f32 v25, -v41, v41, 1.0
	v_fmamk_f32 v26, v27, 0xbfb8aa3b, v96
	v_add_f32_e32 v16, 1.0, v16
	v_rcp_f32_e32 v16, v16
	v_rcp_f32_e32 v17, v17
	v_sqrt_f32_e32 v25, v25
	v_mul_f32_e32 v16, v16, v33
	v_exp_f32_e32 v26, v26
	v_exp_f32_e32 v99, v16
	v_mul_f32_e32 v100, v17, v25
	v_fmamk_f32 v25, v44, 0xbfb8aa3b, v97
	v_add_f32_e32 v16, 1.0, v26
	v_fmamk_f32 v26, v28, 0xbfb8aa3b, v96
	v_fma_f32 v17, -v99, v99, 1.0
	v_exp_f32_e32 v25, v25
	v_rcp_f32_e32 v16, v16
	v_sqrt_f32_e32 v17, v17
	v_exp_f32_e32 v26, v26
	v_add_f32_e32 v25, 1.0, v25
	v_rcp_f32_e32 v25, v25
	v_mul_f32_e32 v101, v16, v17
	v_add_f32_e32 v16, 1.0, v26
	v_fmamk_f32 v26, v29, 0xbfb8aa3b, v96
	v_exp_f32_e32 v26, v26
	v_rcp_f32_e32 v17, v16
	v_mul_f32_e32 v16, v25, v33
	v_fmamk_f32 v25, v45, 0xbfb8aa3b, v97
	v_exp_f32_e32 v25, v25
	v_add_f32_e32 v26, 1.0, v26
	v_rcp_f32_e32 v42, v26
	v_fmamk_f32 v26, v46, 0xbfb8aa3b, v97
	v_exp_f32_e32 v26, v26
	v_add_f32_e32 v25, 1.0, v25
	v_rcp_f32_e32 v25, v25
	v_fmamk_f32 v27, v30, 0xbfb8aa3b, v96
	v_exp_f32_e32 v27, v27
	v_add_f32_e32 v26, 1.0, v26
	v_rcp_f32_e32 v26, v26
	v_mul_f32_e32 v25, v25, v33
	v_exp_f32_e32 v43, v25
	v_add_f32_e32 v25, 1.0, v27
	v_rcp_f32_e32 v44, v25
	v_mul_f32_e32 v25, v26, v33
	v_fmamk_f32 v26, v47, 0xbfb8aa3b, v97
	v_exp_f32_e32 v26, v26
	v_fmamk_f32 v27, v31, 0xbfb8aa3b, v96
	v_exp_f32_e32 v27, v27
	v_add_f32_e32 v26, 1.0, v26
	v_rcp_f32_e32 v26, v26
	v_exp_f32_e32 v16, v16
	v_fmac_f32_e32 v18, 0, v32
	v_mul_f32_e32 v35, v112, v35
	v_exp_f32_e32 v45, v25
	v_add_f32_e32 v25, 1.0, v27
	v_mul_f32_e32 v31, v34, v18
	v_rcp_f32_e32 v46, v25
	v_mul_f32_e32 v25, v26, v33
	v_fmac_f32_e32 v31, v1, v35
	v_mul_f32_e32 v33, v32, v34
	v_mul_f32_e32 v30, v0, v31
	v_mul_f32_e32 v34, v0, v33
	v_fma_f32 v0, -v16, v16, 1.0
	v_sqrt_f32_e32 v1, v0
	v_fmac_f32_e32 v30, v2, v91
	v_fmac_f32_e32 v21, 0, v22
	v_fma_f32 v2, -v43, v43, 1.0
	v_exp_f32_e32 v47, v25
	v_mul_f32_e32 v25, v40, v21
	v_mov_b32_e32 v0, v89
	v_sqrt_f32_e32 v2, v2
	v_fmac_f32_e32 v25, v9, v8
	v_pk_mul_f32 v[8:9], v[16:17], v[0:1]
	v_mul_f32_e32 v29, v98, v30
	v_fmac_f32_e32 v19, 0, v20
	v_fmac_f32_e32 v8, v12, v9
	v_fmac_f32_e32 v29, v3, v36
	v_mul_f32_e32 v28, v37, v19
	v_mov_b32_e32 v3, v8
	v_fmac_f32_e32 v28, v5, v4
	v_pk_mul_f32 v[4:5], v[42:43], v[2:3]
	v_fma_f32 v0, -v45, v45, 1.0
	v_fmac_f32_e32 v5, v13, v4
	v_sqrt_f32_e32 v4, v0
	v_mul_f32_e32 v27, v38, v28
	v_fmac_f32_e32 v27, v6, v23
	v_mul_f32_e32 v26, v39, v27
	v_fmac_f32_e32 v26, v7, v24
	v_pk_mul_f32 v[6:7], v[44:45], v[4:5]
	v_fma_f32 v0, -v47, v47, 1.0
	v_fmac_f32_e32 v7, v14, v6
	v_sqrt_f32_e32 v6, v0
	ds_bpermute_b32 v0, v140, v29
	v_mul_f32_e32 v24, v41, v25
	v_mul_f32_e32 v35, v98, v34
	v_mul_f32_e32 v36, v20, v37
	v_fmac_f32_e32 v24, v10, v100
	v_mul_f32_e32 v37, v38, v36
	v_mul_f32_e32 v23, v99, v24
	ds_bpermute_b32 v13, v140, v35
	v_mul_f32_e32 v38, v39, v37
	v_fmac_f32_e32 v23, v11, v101
	v_pk_mul_f32 v[10:11], v[46:47], v[6:7]
	s_waitcnt lgkmcnt(1)
	v_cndmask_b32_e64 v14, v29, v0, s[0:1]
	v_fmac_f32_e32 v11, v15, v10
	v_cndmask_b32_e64 v10, v0, v29, s[0:1]
	ds_bpermute_b32 v0, v140, v38
	ds_bpermute_b32 v3, v140, v26
	v_mul_f32_e32 v39, v22, v40
	v_mul_f32_e32 v40, v41, v39
	s_waitcnt lgkmcnt(2)
	v_cndmask_b32_e64 v1, v13, v35, s[0:1]
	v_mul_f32_e32 v12, v99, v40
	v_mul_f32_e32 v9, v16, v43
	v_cndmask_b32_e64 v2, v35, v13, s[0:1]
	v_fmac_f32_e32 v10, 0, v1
	v_mul_f32_e32 v4, v45, v9
	v_mul_f32_e32 v15, v35, v13
	v_fmac_f32_e32 v14, v2, v10
	s_waitcnt lgkmcnt(1)
	v_cndmask_b32_e64 v1, v0, v38, s[0:1]
	s_waitcnt lgkmcnt(0)
	v_cndmask_b32_e64 v17, v3, v26, s[0:1]
	v_cndmask_b32_e64 v41, v26, v3, s[0:1]
	ds_bpermute_b32 v2, v140, v12
	ds_bpermute_b32 v3, v140, v23
	v_mul_f32_e32 v6, v47, v4
	v_cndmask_b32_e64 v0, v38, v0, s[0:1]
	v_mul_f32_e32 v42, v15, v1
	v_fmac_f32_e32 v17, v1, v14
	v_mul_f32_e32 v43, v0, v42
	v_fmac_f32_e32 v41, v0, v17
	ds_bpermute_b32 v1, v140, v6
	ds_bpermute_b32 v0, v140, v11
	s_waitcnt lgkmcnt(3)
	v_cndmask_b32_e64 v47, v2, v12, s[0:1]
	s_waitcnt lgkmcnt(2)
	v_cndmask_b32_e64 v44, v3, v23, s[0:1]
	v_cndmask_b32_e64 v2, v12, v2, s[0:1]
	v_cndmask_b32_e64 v45, v23, v3, s[0:1]
	v_mul_f32_e32 v46, v47, v43
	v_fmac_f32_e32 v44, v47, v41
	v_mul_f32_e32 v47, v2, v46
	v_fmac_f32_e32 v45, v2, v44
	s_waitcnt lgkmcnt(1)
	v_cndmask_b32_e64 v2, v1, v6, s[0:1]
	s_waitcnt lgkmcnt(0)
	v_cndmask_b32_e64 v91, v0, v11, s[0:1]
	v_mul_f32_e32 v96, v2, v47
	v_fmac_f32_e32 v91, v2, v45
	s_and_saveexec_b64 s[4:5], s[0:1]
	v_mul_f32_e32 v3, v91, v1
	v_mul_f32_e32 v2, v96, v1
	v_add_f32_e32 v3, v3, v0
	ds_write_b64 v139, v[2:3]
	s_or_b64 exec, exec, s[4:5]
	s_cmp_gt_i32 s62, 0
	s_cselect_b64 s[12:13], -1, 0
	s_cmp_lt_i32 s62, 1
	v_mul_i32_i24_e32 v141, 0xffffff08, v94
	s_waitcnt lgkmcnt(0)
	s_barrier
	s_cbranch_scc1 .LBB0_327
	s_cmp_lt_u32 s62, 8
	s_cbranch_scc1 .LBB0_328
	v_add_u32_e32 v95, v95, v141
	s_and_b32 s4, s62, 0x7ffffff8
	v_mov_b32_e32 v0, 1.0
	v_mov_b32_e32 v3, 0
	s_mov_b32 s5, 0

.LBB0_333:
	s_or_b64 exec, exec, s[6:7]
	s_setprio 1
	ds_read_b128 v[0:3], v148 offset:24576
	ds_read_b128 v[4:7], v148 offset:57344
	s_waitcnt lgkmcnt(1)
	v_mfma_f32_32x32x16_bf16 v[32:47], v[48:51], v[0:3], 0
	s_waitcnt lgkmcnt(0)
	v_mfma_f32_32x32x16_bf16 v[16:31], v[48:51], v[4:7], 0
	ds_read_b128 v[0:3], v150 offset:24576
	ds_read_b128 v[4:7], v150 offset:57344
	s_waitcnt lgkmcnt(1)
	v_mfma_f32_32x32x16_bf16 v[32:47], v[52:55], v[0:3], v[32:47]
	s_waitcnt lgkmcnt(0)
	v_mfma_f32_32x32x16_bf16 v[16:31], v[52:55], v[4:7], v[16:31]
	ds_read_b128 v[0:3], v145 offset:24576
	ds_read_b128 v[4:7], v145 offset:57344
	s_waitcnt lgkmcnt(1)
	v_mfma_f32_32x32x16_bf16 v[32:47], v[56:59], v[0:3], v[32:47]
	s_waitcnt lgkmcnt(0)
	v_mfma_f32_32x32x16_bf16 v[16:31], v[56:59], v[4:7], v[16:31]
	ds_read_b128 v[0:3], v149 offset:24576
	ds_read_b128 v[4:7], v149 offset:57344
	s_waitcnt lgkmcnt(1)
	v_mfma_f32_32x32x16_bf16 v[32:47], v[60:63], v[0:3], v[32:47]
	s_waitcnt lgkmcnt(0)
	v_mfma_f32_32x32x16_bf16 v[16:31], v[60:63], v[4:7], v[16:31]
	ds_read_b128 v[0:3], v144 offset:24576
	ds_read_b128 v[4:7], v144 offset:57344
	s_waitcnt lgkmcnt(1)
	v_mfma_f32_32x32x16_bf16 v[32:47], v[64:67], v[0:3], v[32:47]
	s_waitcnt lgkmcnt(0)
	v_mfma_f32_32x32x16_bf16 v[16:31], v[64:67], v[4:7], v[16:31]
	ds_read_b128 v[0:3], v147 offset:24576
	ds_read_b128 v[4:7], v147 offset:57344
	s_waitcnt lgkmcnt(1)
	v_mfma_f32_32x32x16_bf16 v[32:47], v[68:71], v[0:3], v[32:47]
	s_waitcnt lgkmcnt(0)
	v_mfma_f32_32x32x16_bf16 v[16:31], v[68:71], v[4:7], v[16:31]
	ds_read_b128 v[0:3], v143 offset:24576
	ds_read_b128 v[4:7], v143 offset:57344
	s_waitcnt lgkmcnt(1)
	v_mfma_f32_32x32x16_bf16 v[32:47], v[72:75], v[0:3], v[32:47]
	s_waitcnt lgkmcnt(0)
	v_mfma_f32_32x32x16_bf16 v[16:31], v[72:75], v[4:7], v[16:31]
	ds_read_b128 v[0:3], v146 offset:24576
	ds_read_b128 v[4:7], v146 offset:57344
	s_waitcnt lgkmcnt(1)
	v_mfma_f32_32x32x16_bf16 v[32:47], v[76:79], v[0:3], v[32:47]
	s_waitcnt lgkmcnt(0)
	v_mfma_f32_32x32x16_bf16 v[16:31], v[76:79], v[4:7], v[16:31]
	v_mfma_f32_32x32x16_bf16 v[0:15], v[56:59], v[80:83], 0
	v_mfma_f32_32x32x16_bf16 v[0:15], v[60:63], v[84:87], v[0:15]
	s_setprio 0
	s_waitcnt vmcnt(16)
	ds_read_b32 v251, v167 offset:128
	v_mul_f32_e32 v151, 0xbfb8aa3b, v173
	v_mul_f32_e32 v93, 0xbfb8aa3b, v174
	v_fmamk_f32 v32, v32, 0xbfb8aa3b, v151
	v_fmamk_f32 v34, v34, 0xbfb8aa3b, v151
	v_fmamk_f32 v33, v33, 0xbfb8aa3b, v151
	v_fmamk_f32 v35, v35, 0xbfb8aa3b, v151
	v_fmamk_f32 v16, v16, 0xbfb8aa3b, v93
	v_fmamk_f32 v17, v17, 0xbfb8aa3b, v93
	v_exp_f32_e32 v32, v32
	v_exp_f32_e32 v34, v34
	v_exp_f32_e32 v33, v33
	v_exp_f32_e32 v161, v35
	v_exp_f32_e32 v91, v16
	v_exp_f32_e32 v152, v17
	v_add_f32_e32 v32, 1.0, v32
	v_add_f32_e32 v162, 1.0, v34
	v_add_f32_e32 v33, 1.0, v33
	v_rcp_f32_e32 v163, v32
	v_rcp_f32_e32 v165, v33
	v_add_f32_e32 v91, 1.0, v91
	v_rcp_f32_e32 v164, v91
	v_add_f32_e32 v152, 1.0, v152
	v_rcp_f32_e32 v166, v152
	v_fmamk_f32 v18, v18, 0xbfb8aa3b, v93
	v_exp_f32_e32 v18, v18
	v_fmamk_f32 v20, v20, 0xbfb8aa3b, v93
	v_add_f32_e32 v18, 1.0, v18
	v_exp_f32_e32 v20, v20
	v_fmamk_f32 v19, v19, 0xbfb8aa3b, v93
	v_exp_f32_e32 v19, v19
	v_fmamk_f32 v21, v21, 0xbfb8aa3b, v93
	s_waitcnt lgkmcnt(0)
	v_mul_f32_e32 v33, 0x3fb8aa3b, v251
	v_mul_f32_e32 v16, v163, v33
	v_exp_f32_e32 v32, v16
	v_mul_f32_e32 v17, v165, v33
	v_exp_f32_e32 v34, v17
	v_rcp_f32_e32 v16, v162
	v_rcp_f32_e32 v17, v18
	v_fma_f32 v18, -v32, v32, 1.0
	v_sqrt_f32_e32 v18, v18
	v_mul_f32_e32 v16, v16, v33
	v_add_f32_e32 v19, 1.0, v19
	v_mul_f32_e32 v18, v164, v18
	v_mul_f32_e32 v18, v0, v18
	v_exp_f32_e32 v0, v16
	v_add_f32_e32 v16, 1.0, v161
	v_rcp_f32_e32 v16, v16
	v_rcp_f32_e32 v19, v19
	v_fma_f32 v91, -v0, v0, 1.0
	v_sqrt_f32_e32 v91, v91
	v_mul_f32_e32 v16, v16, v33
	v_exp_f32_e32 v152, v16
	v_fmamk_f32 v16, v36, 0xbfb8aa3b, v151
	v_exp_f32_e32 v16, v16
	v_mul_f32_e32 v91, v17, v91
	v_add_f32_e32 v17, 1.0, v20
	v_fma_f32 v36, -v152, v152, 1.0
	v_add_f32_e32 v16, 1.0, v16
	v_rcp_f32_e32 v16, v16
	v_sqrt_f32_e32 v36, v36
	v_rcp_f32_e32 v17, v17
	v_mul_f32_e32 v16, v16, v33
	v_exp_f32_e32 v20, v16
	v_fmamk_f32 v16, v37, 0xbfb8aa3b, v151
	v_exp_f32_e32 v16, v16
	v_mul_f32_e32 v36, v19, v36
	v_fma_f32 v19, -v20, v20, 1.0
	v_sqrt_f32_e32 v19, v19
	v_add_f32_e32 v16, 1.0, v16
	v_rcp_f32_e32 v16, v16
	v_exp_f32_e32 v21, v21
	v_mul_f32_e32 v17, v17, v19
	v_mul_f32_e32 v19, v4, v17
	v_mul_f32_e32 v16, v16, v33
	v_exp_f32_e32 v37, v16
	v_fmamk_f32 v16, v38, 0xbfb8aa3b, v151
	v_exp_f32_e32 v16, v16
	v_add_f32_e32 v4, 1.0, v21
	v_fmamk_f32 v21, v22, 0xbfb8aa3b, v93
	v_add_f32_e32 v16, 1.0, v16
	v_rcp_f32_e32 v16, v16
	v_fma_f32 v17, -v37, v37, 1.0
	v_exp_f32_e32 v21, v21
	v_rcp_f32_e32 v4, v4
	v_mul_f32_e32 v16, v16, v33
	v_sqrt_f32_e32 v17, v17
	v_exp_f32_e32 v38, v16
	v_add_f32_e32 v16, 1.0, v21
	v_fmamk_f32 v21, v39, 0xbfb8aa3b, v151
	v_mul_f32_e32 v4, v4, v17
	v_fma_f32 v17, -v38, v38, 1.0
	v_rcp_f32_e32 v16, v16
	v_sqrt_f32_e32 v17, v17
	v_exp_f32_e32 v21, v21
	v_fmamk_f32 v22, v23, 0xbfb8aa3b, v93
	v_mul_f32_e32 v23, v16, v17
	v_add_f32_e32 v16, 1.0, v21
	v_rcp_f32_e32 v16, v16
	v_fmamk_f32 v21, v40, 0xbfb8aa3b, v151
	v_exp_f32_e32 v21, v21
	v_mul_f32_e32 v16, v16, v33
	v_exp_f32_e32 v39, v16
	v_add_f32_e32 v16, 1.0, v21
	v_rcp_f32_e32 v16, v16
	v_exp_f32_e32 v22, v22
	v_fmamk_f32 v21, v24, 0xbfb8aa3b, v93
	v_mul_f32_e32 v16, v16, v33
	v_add_f32_e32 v17, 1.0, v22
	v_fma_f32 v22, -v39, v39, 1.0
	v_sqrt_f32_e32 v24, v22
	v_exp_f32_e32 v22, v16
	v_fmamk_f32 v16, v41, 0xbfb8aa3b, v151
	v_exp_f32_e32 v16, v16
	v_exp_f32_e32 v21, v21
	v_fma_f32 v40, -v22, v22, 1.0
	v_rcp_f32_e32 v17, v17
	v_add_f32_e32 v16, 1.0, v16
	v_rcp_f32_e32 v16, v16
	v_add_f32_e32 v21, 1.0, v21
	v_rcp_f32_e32 v21, v21
	v_sqrt_f32_e32 v40, v40
	v_mul_f32_e32 v16, v16, v33
	v_mul_f32_e32 v24, v17, v24
	v_mul_f32_e32 v17, v21, v40
	v_exp_f32_e32 v40, v16
	v_fmamk_f32 v16, v42, 0xbfb8aa3b, v151
	v_fmamk_f32 v25, v25, 0xbfb8aa3b, v93
	v_exp_f32_e32 v16, v16
	v_exp_f32_e32 v25, v25
	v_fma_f32 v35, -v34, v34, 1.0
	v_sqrt_f32_e32 v35, v35
	v_add_f32_e32 v16, 1.0, v16
	v_add_f32_e32 v21, 1.0, v25
	v_rcp_f32_e32 v16, v16
	v_rcp_f32_e32 v25, v21
	v_fma_f32 v21, -v40, v40, 1.0
	v_sqrt_f32_e32 v41, v21
	v_fmamk_f32 v21, v26, 0xbfb8aa3b, v93
	v_mul_f32_e32 v16, v16, v33
	v_exp_f32_e32 v26, v21
	v_mul_f32_e32 v21, v8, v17
	v_mul_f32_e32 v8, v25, v41
	v_exp_f32_e32 v41, v16
	v_fmamk_f32 v16, v43, 0xbfb8aa3b, v151
	v_exp_f32_e32 v16, v16
	v_add_f32_e32 v17, 1.0, v26
	v_fma_f32 v25, -v41, v41, 1.0
	v_fmamk_f32 v26, v27, 0xbfb8aa3b, v93
	v_add_f32_e32 v16, 1.0, v16
	v_rcp_f32_e32 v16, v16
	v_rcp_f32_e32 v17, v17
	v_sqrt_f32_e32 v25, v25
	v_mul_f32_e32 v16, v16, v33
	v_exp_f32_e32 v26, v26
	v_exp_f32_e32 v153, v16
	v_mul_f32_e32 v154, v17, v25
	v_fmamk_f32 v25, v44, 0xbfb8aa3b, v151
	v_add_f32_e32 v16, 1.0, v26
	v_fmamk_f32 v26, v28, 0xbfb8aa3b, v93
	v_fma_f32 v17, -v153, v153, 1.0
	v_exp_f32_e32 v25, v25
	v_rcp_f32_e32 v16, v16
	v_sqrt_f32_e32 v17, v17
	v_exp_f32_e32 v26, v26
	v_add_f32_e32 v25, 1.0, v25
	v_rcp_f32_e32 v25, v25
	v_mul_f32_e32 v155, v16, v17
	v_add_f32_e32 v16, 1.0, v26
	v_fmamk_f32 v26, v29, 0xbfb8aa3b, v93
	v_exp_f32_e32 v26, v26
	v_rcp_f32_e32 v17, v16
	v_mul_f32_e32 v16, v25, v33
	v_fmamk_f32 v25, v45, 0xbfb8aa3b, v151
	v_exp_f32_e32 v25, v25
	v_add_f32_e32 v26, 1.0, v26
	v_rcp_f32_e32 v42, v26
	v_fmamk_f32 v26, v46, 0xbfb8aa3b, v151
	v_exp_f32_e32 v26, v26
	v_add_f32_e32 v25, 1.0, v25
	v_rcp_f32_e32 v25, v25
	v_fmamk_f32 v27, v30, 0xbfb8aa3b, v93
	v_exp_f32_e32 v27, v27
	v_add_f32_e32 v26, 1.0, v26
	v_rcp_f32_e32 v26, v26
	v_mul_f32_e32 v25, v25, v33
	v_exp_f32_e32 v43, v25
	v_add_f32_e32 v25, 1.0, v27
	v_rcp_f32_e32 v44, v25
	v_mul_f32_e32 v25, v26, v33
	v_fmamk_f32 v26, v47, 0xbfb8aa3b, v151
	v_exp_f32_e32 v26, v26
	v_fmamk_f32 v27, v31, 0xbfb8aa3b, v93
	v_exp_f32_e32 v27, v27
	v_add_f32_e32 v26, 1.0, v26
	v_rcp_f32_e32 v26, v26
	v_exp_f32_e32 v16, v16
	v_fmac_f32_e32 v18, 0, v32
	v_mul_f32_e32 v35, v166, v35
	v_exp_f32_e32 v45, v25
	v_add_f32_e32 v25, 1.0, v27
	v_mul_f32_e32 v31, v34, v18
	v_rcp_f32_e32 v46, v25
	v_mul_f32_e32 v25, v26, v33
	v_fmac_f32_e32 v31, v1, v35
	v_mul_f32_e32 v33, v32, v34
	v_fmac_f32_e32 v19, 0, v20
	v_mul_f32_e32 v30, v0, v31
	v_mul_f32_e32 v34, v0, v33
	v_mul_f32_e32 v28, v37, v19
	v_fma_f32 v0, -v16, v16, 1.0
	v_fmac_f32_e32 v28, v5, v4
	v_sqrt_f32_e32 v1, v0
	v_mul_f32_e32 v27, v38, v28
	v_fmac_f32_e32 v30, v2, v91
	v_fmac_f32_e32 v27, v6, v23
	v_fma_f32 v2, -v43, v43, 1.0
	v_mul_f32_e32 v26, v39, v27
	v_mov_b32_e32 v0, v89
	v_sqrt_f32_e32 v2, v2
	v_fmac_f32_e32 v26, v7, v24
	v_pk_mul_f32 v[6:7], v[16:17], v[0:1]
	v_mul_f32_e32 v29, v152, v30
	v_fmac_f32_e32 v6, v12, v7
	v_fmac_f32_e32 v29, v3, v36
	v_mov_b32_e32 v3, v6
	v_pk_mul_f32 v[4:5], v[42:43], v[2:3]
	v_fma_f32 v0, -v45, v45, 1.0
	v_exp_f32_e32 v47, v25
	v_fmac_f32_e32 v5, v13, v4
	v_sqrt_f32_e32 v4, v0
	v_fmac_f32_e32 v21, 0, v22
	v_mul_f32_e32 v25, v40, v21
	v_fmac_f32_e32 v25, v9, v8
	v_pk_mul_f32 v[8:9], v[44:45], v[4:5]
	v_fma_f32 v0, -v47, v47, 1.0
	v_fmac_f32_e32 v9, v14, v8
	v_sqrt_f32_e32 v8, v0
	ds_bpermute_b32 v0, v140, v29
	v_mul_f32_e32 v24, v41, v25
	v_mul_f32_e32 v35, v152, v34
	v_mul_f32_e32 v36, v20, v37
	v_fmac_f32_e32 v24, v10, v154
	v_mul_f32_e32 v37, v38, v36
	v_mul_f32_e32 v23, v153, v24
	ds_bpermute_b32 v13, v140, v35
	v_mul_f32_e32 v38, v39, v37
	v_fmac_f32_e32 v23, v11, v155
	v_pk_mul_f32 v[10:11], v[46:47], v[8:9]
	s_waitcnt lgkmcnt(1)
	v_cndmask_b32_e64 v14, v29, v0, s[0:1]
	v_fmac_f32_e32 v11, v15, v10
	v_cndmask_b32_e64 v10, v0, v29, s[0:1]
	ds_bpermute_b32 v0, v140, v38
	ds_bpermute_b32 v3, v140, v26
	v_mul_f32_e32 v39, v22, v40
	v_mul_f32_e32 v40, v41, v39
	s_waitcnt lgkmcnt(2)
	v_cndmask_b32_e64 v1, v13, v35, s[0:1]
	v_mul_f32_e32 v12, v153, v40
	v_mul_f32_e32 v7, v16, v43
	v_cndmask_b32_e64 v2, v35, v13, s[0:1]
	v_fmac_f32_e32 v10, 0, v1
	v_mul_f32_e32 v4, v45, v7
	v_mul_f32_e32 v15, v35, v13
	v_fmac_f32_e32 v14, v2, v10
	s_waitcnt lgkmcnt(1)
	v_cndmask_b32_e64 v1, v0, v38, s[0:1]
	s_waitcnt lgkmcnt(0)
	v_cndmask_b32_e64 v17, v3, v26, s[0:1]
	v_cndmask_b32_e64 v41, v26, v3, s[0:1]
	ds_bpermute_b32 v2, v140, v12
	ds_bpermute_b32 v3, v140, v23
	v_mul_f32_e32 v8, v47, v4
	v_cndmask_b32_e64 v0, v38, v0, s[0:1]
	v_mul_f32_e32 v42, v15, v1
	v_fmac_f32_e32 v17, v1, v14
	v_mul_f32_e32 v43, v0, v42
	v_fmac_f32_e32 v41, v0, v17
	ds_bpermute_b32 v1, v140, v8
	ds_bpermute_b32 v0, v140, v11
	s_waitcnt lgkmcnt(3)
	v_cndmask_b32_e64 v47, v2, v12, s[0:1]
	s_waitcnt lgkmcnt(2)
	v_cndmask_b32_e64 v44, v3, v23, s[0:1]
	v_cndmask_b32_e64 v2, v12, v2, s[0:1]
	v_cndmask_b32_e64 v45, v23, v3, s[0:1]
	v_mul_f32_e32 v46, v47, v43
	v_fmac_f32_e32 v44, v47, v41
	v_mul_f32_e32 v47, v2, v46
	v_fmac_f32_e32 v45, v2, v44
	s_waitcnt lgkmcnt(1)
	v_cndmask_b32_e64 v2, v1, v8, s[0:1]
	s_waitcnt lgkmcnt(0)
	v_cndmask_b32_e64 v91, v0, v11, s[0:1]
	v_mul_f32_e32 v93, v2, v47
	v_fmac_f32_e32 v91, v2, v45
	s_and_saveexec_b64 s[6:7], s[0:1]
	v_mul_f32_e32 v3, v91, v1
	v_mul_f32_e32 v2, v93, v1
	v_add_f32_e32 v3, v3, v0
	ds_write_b64 v139, v[2:3] offset:2048
	s_or_b64 exec, exec, s[6:7]
	v_cndmask_b32_e64 v0, 0, 1, s[12:13]
	v_cmp_ne_u32_e64 s[6:7], 1, v0
	s_andn2_b64 vcc, exec, s[12:13]
	s_waitcnt lgkmcnt(0)
	s_barrier
	s_cbranch_vccnz .LBB0_340
	s_cmp_lt_u32 s62, 8
	s_cbranch_scc1 .LBB0_341
	s_add_i32 s9, 16, 0x800
	s_and_b32 s8, s62, 0x7ffffff8
	v_add3_u32 v151, v141, v138, s9
	v_mov_b32_e32 v0, 1.0
	v_mov_b32_e32 v3, 0
	s_mov_b32 s9, 0

.LBB0_346:
	s_or_b64 exec, exec, s[8:9]
	s_setprio 1
	ds_read_b128 v[0:3], v148 offset:32768
	ds_read_b128 v[4:7], v150 offset:32768
	v_add_u32_e32 v8, 0x8000, v150
	s_waitcnt lgkmcnt(1)
	v_mfma_f32_32x32x16_bf16 v[16:31], v[48:51], v[0:3], 0
	v_add_u32_e32 v0, 0x8000, v148
	ds_read_b128 v[0:3], v0 offset:32768
	ds_read_b128 v[8:11], v8 offset:32768
	s_waitcnt lgkmcnt(1)
	v_mfma_f32_32x32x16_bf16 v[32:47], v[48:51], v[0:3], 0
	v_mfma_f32_32x32x16_bf16 v[16:31], v[52:55], v[4:7], v[16:31]
	ds_read_b128 v[0:3], v145 offset:32768
	ds_read_b128 v[4:7], v149 offset:32768
	s_waitcnt lgkmcnt(2)
	v_mfma_f32_32x32x16_bf16 v[32:47], v[52:55], v[8:11], v[32:47]
	v_add_u32_e32 v8, 0x8000, v149
	ds_read_b128 v[8:11], v8 offset:32768
	s_waitcnt lgkmcnt(2)
	v_mfma_f32_32x32x16_bf16 v[16:31], v[56:59], v[0:3], v[16:31]
	v_add_u32_e32 v0, 0x8000, v145
	ds_read_b128 v[0:3], v0 offset:32768
	s_waitcnt lgkmcnt(0)
	v_mfma_f32_32x32x16_bf16 v[32:47], v[56:59], v[0:3], v[32:47]
	v_mfma_f32_32x32x16_bf16 v[16:31], v[60:63], v[4:7], v[16:31]
	ds_read_b128 v[0:3], v144 offset:32768
	ds_read_b128 v[4:7], v147 offset:32768
	v_mfma_f32_32x32x16_bf16 v[32:47], v[60:63], v[8:11], v[32:47]
	v_add_u32_e32 v8, 0x8000, v147
	ds_read_b128 v[8:11], v8 offset:32768
	s_waitcnt lgkmcnt(2)
	v_mfma_f32_32x32x16_bf16 v[16:31], v[64:67], v[0:3], v[16:31]
	v_add_u32_e32 v0, 0x8000, v144
	ds_read_b128 v[0:3], v0 offset:32768
	s_waitcnt lgkmcnt(0)
	v_mfma_f32_32x32x16_bf16 v[32:47], v[64:67], v[0:3], v[32:47]
	v_mfma_f32_32x32x16_bf16 v[16:31], v[68:71], v[4:7], v[16:31]
	ds_read_b128 v[0:3], v143 offset:32768
	ds_read_b128 v[4:7], v146 offset:32768
	v_mfma_f32_32x32x16_bf16 v[32:47], v[68:71], v[8:11], v[32:47]
	v_add_u32_e32 v8, 0x8000, v146
	ds_read_b128 v[8:11], v8 offset:32768
	s_waitcnt lgkmcnt(2)
	v_mfma_f32_32x32x16_bf16 v[16:31], v[72:75], v[0:3], v[16:31]
	v_add_u32_e32 v0, 0x8000, v143
	ds_read_b128 v[0:3], v0 offset:32768
	s_waitcnt lgkmcnt(0)
	v_mfma_f32_32x32x16_bf16 v[32:47], v[72:75], v[0:3], v[32:47]
	v_mfma_f32_32x32x16_bf16 v[16:31], v[76:79], v[4:7], v[16:31]
	v_mfma_f32_32x32x16_bf16 v[32:47], v[76:79], v[8:11], v[32:47]
	v_mfma_f32_32x32x16_bf16 v[0:15], v[64:67], v[80:83], 0
	v_mfma_f32_32x32x16_bf16 v[0:15], v[68:71], v[84:87], v[0:15]
	s_setprio 0
	s_waitcnt vmcnt(16)
	ds_read_b32 v251, v167 offset:256
	v_mul_f32_e32 v151, 0xbfb8aa3b, v173
	v_mul_f32_e32 v93, 0xbfb8aa3b, v174
	s_nop 0
	v_fmamk_f32 v18, v18, 0xbfb8aa3b, v151
	v_fmamk_f32 v19, v19, 0xbfb8aa3b, v151
	v_fmamk_f32 v16, v16, 0xbfb8aa3b, v151
	v_fmamk_f32 v32, v32, 0xbfb8aa3b, v93
	v_fmamk_f32 v17, v17, 0xbfb8aa3b, v151
	v_exp_f32_e32 v18, v18
	v_fmamk_f32 v33, v33, 0xbfb8aa3b, v93
	v_exp_f32_e32 v161, v19
	v_exp_f32_e32 v91, v16
	v_exp_f32_e32 v32, v32
	v_exp_f32_e32 v152, v17
	v_exp_f32_e32 v33, v33
	v_add_f32_e32 v162, 1.0, v18
	v_add_f32_e32 v32, 1.0, v32
	v_add_f32_e32 v91, 1.0, v91
	v_add_f32_e32 v33, 1.0, v33
	v_rcp_f32_e32 v164, v32
	v_rcp_f32_e32 v163, v91
	v_rcp_f32_e32 v166, v33
	v_add_f32_e32 v152, 1.0, v152
	v_rcp_f32_e32 v165, v152
	v_fmamk_f32 v34, v34, 0xbfb8aa3b, v93
	v_exp_f32_e32 v34, v34
	v_fmamk_f32 v36, v36, 0xbfb8aa3b, v93
	v_add_f32_e32 v34, 1.0, v34
	v_exp_f32_e32 v36, v36
	s_nop 1
	s_nop 1
	s_waitcnt lgkmcnt(0)
	v_mul_f32_e32 v33, 0x3fb8aa3b, v251
	v_mul_f32_e32 v16, v163, v33
	v_exp_f32_e32 v32, v16
	v_rcp_f32_e32 v16, v162
	v_mul_f32_e32 v17, v165, v33
	v_fma_f32 v18, -v32, v32, 1.0
	v_sqrt_f32_e32 v18, v18
	v_mul_f32_e32 v16, v16, v33
	v_exp_f32_e32 v91, v17
	v_mul_f32_e32 v18, v164, v18
	v_mul_f32_e32 v18, v0, v18
	v_exp_f32_e32 v0, v16
	v_add_f32_e32 v16, 1.0, v161
	v_rcp_f32_e32 v16, v16
	v_fma_f32 v19, -v91, v91, 1.0
	v_sqrt_f32_e32 v19, v19
	v_rcp_f32_e32 v17, v34
	v_mul_f32_e32 v16, v16, v33
	v_exp_f32_e32 v152, v16
	v_fmamk_f32 v16, v20, 0xbfb8aa3b, v151
	v_mul_f32_e32 v34, v166, v19
	v_fmamk_f32 v19, v35, 0xbfb8aa3b, v93
	v_exp_f32_e32 v16, v16
	v_exp_f32_e32 v19, v19
	v_fma_f32 v20, -v152, v152, 1.0
	v_add_f32_e32 v16, 1.0, v16
	v_rcp_f32_e32 v16, v16
	v_add_f32_e32 v19, 1.0, v19
	v_rcp_f32_e32 v19, v19
	v_sqrt_f32_e32 v20, v20
	v_mul_f32_e32 v16, v16, v33
	v_fma_f32 v35, -v0, v0, 1.0
	v_mul_f32_e32 v153, v19, v20
	v_exp_f32_e32 v20, v16
	v_fmamk_f32 v16, v21, 0xbfb8aa3b, v151
	v_exp_f32_e32 v16, v16
	v_sqrt_f32_e32 v35, v35
	v_fma_f32 v19, -v20, v20, 1.0
	v_fmamk_f32 v21, v37, 0xbfb8aa3b, v93
	v_add_f32_e32 v16, 1.0, v16
	v_rcp_f32_e32 v16, v16
	v_mul_f32_e32 v35, v17, v35
	v_add_f32_e32 v17, 1.0, v36
	v_rcp_f32_e32 v17, v17
	v_mul_f32_e32 v16, v16, v33
	v_exp_f32_e32 v36, v16
	v_fmamk_f32 v16, v22, 0xbfb8aa3b, v151
	v_exp_f32_e32 v16, v16
	v_sqrt_f32_e32 v19, v19
	v_exp_f32_e32 v21, v21
	v_add_f32_e32 v16, 1.0, v16
	v_rcp_f32_e32 v16, v16
	v_mul_f32_e32 v17, v17, v19
	v_mul_f32_e32 v19, v4, v17
	v_add_f32_e32 v4, 1.0, v21
	v_fmamk_f32 v21, v38, 0xbfb8aa3b, v93
	v_mul_f32_e32 v16, v16, v33
	v_fma_f32 v17, -v36, v36, 1.0
	v_exp_f32_e32 v21, v21
	v_rcp_f32_e32 v4, v4
	v_sqrt_f32_e32 v17, v17
	v_exp_f32_e32 v37, v16
	v_add_f32_e32 v16, 1.0, v21
	v_fmamk_f32 v21, v23, 0xbfb8aa3b, v151
	v_mul_f32_e32 v4, v4, v17
	v_fma_f32 v17, -v37, v37, 1.0
	v_rcp_f32_e32 v16, v16
	v_sqrt_f32_e32 v17, v17
	v_exp_f32_e32 v21, v21
	v_fmamk_f32 v22, v39, 0xbfb8aa3b, v93
	v_mul_f32_e32 v23, v16, v17
	v_add_f32_e32 v16, 1.0, v21
	v_rcp_f32_e32 v16, v16
	v_fmamk_f32 v21, v24, 0xbfb8aa3b, v151
	v_exp_f32_e32 v21, v21
	v_mul_f32_e32 v16, v16, v33
	v_exp_f32_e32 v24, v16
	v_add_f32_e32 v16, 1.0, v21
	v_rcp_f32_e32 v16, v16
	v_exp_f32_e32 v22, v22
	v_fmamk_f32 v21, v40, 0xbfb8aa3b, v93
	v_mul_f32_e32 v16, v16, v33
	v_add_f32_e32 v17, 1.0, v22
	v_fma_f32 v22, -v24, v24, 1.0
	v_sqrt_f32_e32 v38, v22
	v_exp_f32_e32 v22, v16
	v_fmamk_f32 v16, v25, 0xbfb8aa3b, v151
	v_exp_f32_e32 v16, v16
	v_exp_f32_e32 v21, v21
	v_fmamk_f32 v39, v41, 0xbfb8aa3b, v93
	v_fma_f32 v25, -v22, v22, 1.0
	v_add_f32_e32 v16, 1.0, v16
	v_rcp_f32_e32 v16, v16
	v_add_f32_e32 v21, 1.0, v21
	v_rcp_f32_e32 v17, v17
	v_rcp_f32_e32 v21, v21
	v_sqrt_f32_e32 v25, v25
	v_exp_f32_e32 v39, v39
	v_mul_f32_e32 v16, v16, v33
	v_mul_f32_e32 v38, v17, v38
	v_mul_f32_e32 v17, v21, v25
	v_add_f32_e32 v21, 1.0, v39
	v_exp_f32_e32 v39, v16
	v_fmamk_f32 v16, v26, 0xbfb8aa3b, v151
	v_exp_f32_e32 v16, v16
	v_rcp_f32_e32 v25, v21
	v_fma_f32 v21, -v39, v39, 1.0
	v_sqrt_f32_e32 v26, v21
	v_add_f32_e32 v16, 1.0, v16
	v_fmamk_f32 v21, v42, 0xbfb8aa3b, v93
	v_rcp_f32_e32 v16, v16
	v_exp_f32_e32 v40, v21
	v_mul_f32_e32 v21, v8, v17
	v_mul_f32_e32 v16, v16, v33
	v_add_f32_e32 v17, 1.0, v40
	v_exp_f32_e32 v40, v16
	v_fmamk_f32 v16, v27, 0xbfb8aa3b, v151
	v_exp_f32_e32 v16, v16
	v_mul_f32_e32 v8, v25, v26
	v_fma_f32 v25, -v40, v40, 1.0
	v_fmamk_f32 v26, v43, 0xbfb8aa3b, v93
	v_add_f32_e32 v16, 1.0, v16
	v_rcp_f32_e32 v16, v16
	v_rcp_f32_e32 v17, v17
	v_sqrt_f32_e32 v25, v25
	v_mul_f32_e32 v16, v16, v33
	v_exp_f32_e32 v26, v26
	v_exp_f32_e32 v41, v16
	v_mul_f32_e32 v154, v17, v25
	v_fmamk_f32 v25, v28, 0xbfb8aa3b, v151
	v_add_f32_e32 v16, 1.0, v26
	v_fmamk_f32 v26, v44, 0xbfb8aa3b, v93
	v_fma_f32 v17, -v41, v41, 1.0
	v_exp_f32_e32 v25, v25
	v_rcp_f32_e32 v16, v16
	v_sqrt_f32_e32 v17, v17
	v_exp_f32_e32 v26, v26
	v_add_f32_e32 v25, 1.0, v25
	v_rcp_f32_e32 v25, v25
	v_mul_f32_e32 v155, v16, v17
	v_add_f32_e32 v16, 1.0, v26
	v_fmamk_f32 v26, v45, 0xbfb8aa3b, v93
	v_exp_f32_e32 v26, v26
	v_rcp_f32_e32 v17, v16
	v_mul_f32_e32 v16, v25, v33
	v_fmamk_f32 v25, v29, 0xbfb8aa3b, v151
	v_exp_f32_e32 v25, v25
	v_add_f32_e32 v26, 1.0, v26
	v_rcp_f32_e32 v42, v26
	v_fmamk_f32 v26, v30, 0xbfb8aa3b, v151
	v_exp_f32_e32 v26, v26
	v_add_f32_e32 v25, 1.0, v25
	v_rcp_f32_e32 v25, v25
	v_fmamk_f32 v27, v46, 0xbfb8aa3b, v93
	v_exp_f32_e32 v27, v27
	v_add_f32_e32 v26, 1.0, v26
	v_rcp_f32_e32 v26, v26
	v_mul_f32_e32 v25, v25, v33
	v_exp_f32_e32 v43, v25
	v_add_f32_e32 v25, 1.0, v27
	v_rcp_f32_e32 v44, v25
	v_mul_f32_e32 v25, v26, v33
	v_fmamk_f32 v26, v31, 0xbfb8aa3b, v151
	v_exp_f32_e32 v26, v26
	v_fmamk_f32 v27, v47, 0xbfb8aa3b, v93
	v_exp_f32_e32 v27, v27
	v_add_f32_e32 v26, 1.0, v26
	v_rcp_f32_e32 v26, v26
	v_exp_f32_e32 v16, v16
	v_fmac_f32_e32 v18, 0, v32
	v_exp_f32_e32 v45, v25
	v_add_f32_e32 v25, 1.0, v27
	v_mul_f32_e32 v31, v91, v18
	v_rcp_f32_e32 v46, v25
	v_mul_f32_e32 v25, v26, v33
	v_fmac_f32_e32 v31, v1, v34
	v_mul_f32_e32 v33, v32, v91
	v_fmac_f32_e32 v19, 0, v20
	v_mul_f32_e32 v30, v0, v31
	v_mul_f32_e32 v34, v0, v33
	v_mul_f32_e32 v28, v36, v19
	v_fma_f32 v0, -v16, v16, 1.0
	v_fmac_f32_e32 v28, v5, v4
	v_sqrt_f32_e32 v1, v0
	v_mul_f32_e32 v27, v37, v28
	v_fmac_f32_e32 v30, v2, v35
	v_fmac_f32_e32 v27, v6, v23
	v_fma_f32 v2, -v43, v43, 1.0
	v_mul_f32_e32 v26, v24, v27
	v_mov_b32_e32 v0, v89
	v_sqrt_f32_e32 v2, v2
	v_fmac_f32_e32 v26, v7, v38
	v_pk_mul_f32 v[6:7], v[16:17], v[0:1]
	v_mul_f32_e32 v29, v152, v30
	v_fmac_f32_e32 v6, v12, v7
	v_fmac_f32_e32 v29, v3, v153
	v_mov_b32_e32 v3, v6
	v_pk_mul_f32 v[4:5], v[42:43], v[2:3]
	v_fma_f32 v0, -v45, v45, 1.0
	v_exp_f32_e32 v47, v25
	v_fmac_f32_e32 v5, v13, v4
	v_sqrt_f32_e32 v4, v0
	v_fmac_f32_e32 v21, 0, v22
	v_mul_f32_e32 v25, v39, v21
	v_mul_f32_e32 v36, v20, v36
	v_fmac_f32_e32 v25, v9, v8
	v_pk_mul_f32 v[8:9], v[44:45], v[4:5]
	v_fma_f32 v0, -v47, v47, 1.0
	v_mul_f32_e32 v37, v37, v36
	v_fmac_f32_e32 v9, v14, v8
	v_sqrt_f32_e32 v8, v0
	ds_bpermute_b32 v0, v140, v29
	v_mul_f32_e32 v38, v24, v37
	v_mul_f32_e32 v24, v40, v25
	v_mul_f32_e32 v35, v152, v34
	v_fmac_f32_e32 v24, v10, v154
	v_mul_f32_e32 v23, v41, v24
	ds_bpermute_b32 v13, v140, v35
	v_fmac_f32_e32 v23, v11, v155
	v_pk_mul_f32 v[10:11], v[46:47], v[8:9]
	s_waitcnt lgkmcnt(1)
	v_cndmask_b32_e64 v14, v29, v0, s[0:1]
	v_fmac_f32_e32 v11, v15, v10
	v_cndmask_b32_e64 v10, v0, v29, s[0:1]
	ds_bpermute_b32 v0, v140, v38
	ds_bpermute_b32 v3, v140, v26
	v_mul_f32_e32 v39, v22, v39
	v_mul_f32_e32 v40, v40, v39
	s_waitcnt lgkmcnt(2)
	v_cndmask_b32_e64 v1, v13, v35, s[0:1]
	v_mul_f32_e32 v12, v41, v40
	v_mul_f32_e32 v7, v16, v43
	v_cndmask_b32_e64 v2, v35, v13, s[0:1]
	v_fmac_f32_e32 v10, 0, v1
	v_mul_f32_e32 v4, v45, v7
	v_mul_f32_e32 v15, v35, v13
	v_fmac_f32_e32 v14, v2, v10
	s_waitcnt lgkmcnt(1)
	v_cndmask_b32_e64 v1, v0, v38, s[0:1]
	s_waitcnt lgkmcnt(0)
	v_cndmask_b32_e64 v17, v3, v26, s[0:1]
	v_cndmask_b32_e64 v41, v26, v3, s[0:1]
	ds_bpermute_b32 v2, v140, v12
	ds_bpermute_b32 v3, v140, v23
	v_mul_f32_e32 v8, v47, v4
	v_cndmask_b32_e64 v0, v38, v0, s[0:1]
	v_mul_f32_e32 v42, v15, v1
	v_fmac_f32_e32 v17, v1, v14
	v_mul_f32_e32 v43, v0, v42
	v_fmac_f32_e32 v41, v0, v17
	ds_bpermute_b32 v1, v140, v8
	ds_bpermute_b32 v0, v140, v11
	s_waitcnt lgkmcnt(3)
	v_cndmask_b32_e64 v47, v2, v12, s[0:1]
	s_waitcnt lgkmcnt(2)
	v_cndmask_b32_e64 v44, v3, v23, s[0:1]
	v_cndmask_b32_e64 v2, v12, v2, s[0:1]
	v_cndmask_b32_e64 v45, v23, v3, s[0:1]
	v_mul_f32_e32 v46, v47, v43
	v_fmac_f32_e32 v44, v47, v41
	v_mul_f32_e32 v47, v2, v46
	v_fmac_f32_e32 v45, v2, v44
	s_waitcnt lgkmcnt(1)
	v_cndmask_b32_e64 v2, v1, v8, s[0:1]
	s_waitcnt lgkmcnt(0)
	v_cndmask_b32_e64 v91, v0, v11, s[0:1]
	v_mul_f32_e32 v93, v2, v47
	v_fmac_f32_e32 v91, v2, v45
	s_and_saveexec_b64 s[8:9], s[0:1]
	v_mul_f32_e32 v3, v91, v1
	v_mul_f32_e32 v2, v93, v1
	v_add_f32_e32 v3, v3, v0
	ds_write_b64 v139, v[2:3] offset:4096
	s_or_b64 exec, exec, s[8:9]
	s_and_b64 vcc, exec, s[6:7]
	s_waitcnt lgkmcnt(0)
	s_barrier
	s_cbranch_vccnz .LBB0_353
	s_cmp_lt_u32 s62, 8
	s_cbranch_scc1 .LBB0_354
	s_add_i32 s9, 16, 0x1000
	s_and_b32 s8, s62, 0x7ffffff8
	v_add3_u32 v151, v141, v138, s9
	v_mov_b32_e32 v0, 1.0
	v_mov_b32_e32 v3, 0
	s_mov_b32 s9, 0

.LBB0_359:
	s_or_b64 exec, exec, s[8:9]
	s_setprio 1
	ds_read_b128 v[0:3], v148 offset:40960
	ds_read_b128 v[4:7], v150 offset:40960
	v_add_u32_e32 v8, 0xa000, v150
	s_waitcnt lgkmcnt(1)
	v_mfma_f32_32x32x16_bf16 v[16:31], v[48:51], v[0:3], 0
	v_add_u32_e32 v0, 0xa000, v148
	ds_read_b128 v[0:3], v0 offset:32768
	ds_read_b128 v[8:11], v8 offset:32768
	s_waitcnt lgkmcnt(1)
	v_mfma_f32_32x32x16_bf16 v[32:47], v[48:51], v[0:3], 0
	v_mfma_f32_32x32x16_bf16 v[16:31], v[52:55], v[4:7], v[16:31]
	ds_read_b128 v[0:3], v145 offset:40960
	ds_read_b128 v[4:7], v149 offset:40960
	s_waitcnt lgkmcnt(2)
	v_mfma_f32_32x32x16_bf16 v[32:47], v[52:55], v[8:11], v[32:47]
	v_add_u32_e32 v8, 0xa000, v149
	ds_read_b128 v[8:11], v8 offset:32768
	s_waitcnt lgkmcnt(2)
	v_mfma_f32_32x32x16_bf16 v[16:31], v[56:59], v[0:3], v[16:31]
	v_add_u32_e32 v0, 0xa000, v145
	ds_read_b128 v[0:3], v0 offset:32768
	s_waitcnt lgkmcnt(0)
	v_mfma_f32_32x32x16_bf16 v[32:47], v[56:59], v[0:3], v[32:47]
	v_mfma_f32_32x32x16_bf16 v[16:31], v[60:63], v[4:7], v[16:31]
	ds_read_b128 v[0:3], v144 offset:40960
	ds_read_b128 v[4:7], v147 offset:40960
	v_mfma_f32_32x32x16_bf16 v[32:47], v[60:63], v[8:11], v[32:47]
	v_add_u32_e32 v8, 0xa000, v147
	ds_read_b128 v[8:11], v8 offset:32768
	s_waitcnt lgkmcnt(2)
	v_mfma_f32_32x32x16_bf16 v[16:31], v[64:67], v[0:3], v[16:31]
	v_add_u32_e32 v0, 0xa000, v144
	ds_read_b128 v[0:3], v0 offset:32768
	s_waitcnt lgkmcnt(0)
	v_mfma_f32_32x32x16_bf16 v[32:47], v[64:67], v[0:3], v[32:47]
	v_mfma_f32_32x32x16_bf16 v[16:31], v[68:71], v[4:7], v[16:31]
	ds_read_b128 v[0:3], v143 offset:40960
	ds_read_b128 v[4:7], v146 offset:40960
	v_mfma_f32_32x32x16_bf16 v[32:47], v[68:71], v[8:11], v[32:47]
	v_add_u32_e32 v8, 0xa000, v146
	ds_read_b128 v[8:11], v8 offset:32768
	s_waitcnt lgkmcnt(2)
	v_mfma_f32_32x32x16_bf16 v[16:31], v[72:75], v[0:3], v[16:31]
	v_add_u32_e32 v0, 0xa000, v143
	ds_read_b128 v[0:3], v0 offset:32768
	s_waitcnt lgkmcnt(0)
	v_mfma_f32_32x32x16_bf16 v[32:47], v[72:75], v[0:3], v[32:47]
	v_mfma_f32_32x32x16_bf16 v[16:31], v[76:79], v[4:7], v[16:31]
	v_mfma_f32_32x32x16_bf16 v[32:47], v[76:79], v[8:11], v[32:47]
	v_mfma_f32_32x32x16_bf16 v[0:15], v[72:75], v[80:83], 0
	v_mfma_f32_32x32x16_bf16 v[0:15], v[76:79], v[84:87], v[0:15]
	s_setprio 0
	s_waitcnt vmcnt(16)
	ds_read_b32 v251, v167 offset:384
	v_mul_f32_e32 v49, 0xbfb8aa3b, v173
	v_mul_f32_e32 v48, 0xbfb8aa3b, v174
	s_nop 0
	v_fmamk_f32 v18, v18, 0xbfb8aa3b, v49
	v_fmamk_f32 v19, v19, 0xbfb8aa3b, v49
	v_fmamk_f32 v16, v16, 0xbfb8aa3b, v49
	v_fmamk_f32 v32, v32, 0xbfb8aa3b, v48
	v_fmamk_f32 v17, v17, 0xbfb8aa3b, v49
	v_exp_f32_e32 v18, v18
	v_fmamk_f32 v33, v33, 0xbfb8aa3b, v48
	v_exp_f32_e32 v59, v19
	v_exp_f32_e32 v50, v16
	v_exp_f32_e32 v32, v32
	v_exp_f32_e32 v51, v17
	v_exp_f32_e32 v33, v33
	v_add_f32_e32 v60, 1.0, v18
	v_add_f32_e32 v32, 1.0, v32
	v_add_f32_e32 v50, 1.0, v50
	v_add_f32_e32 v33, 1.0, v33
	v_rcp_f32_e32 v62, v32
	v_rcp_f32_e32 v61, v50
	v_rcp_f32_e32 v64, v33
	v_add_f32_e32 v51, 1.0, v51
	v_rcp_f32_e32 v63, v51
	v_fmamk_f32 v34, v34, 0xbfb8aa3b, v48
	v_exp_f32_e32 v34, v34
	v_fmamk_f32 v36, v36, 0xbfb8aa3b, v48
	v_add_f32_e32 v34, 1.0, v34
	v_exp_f32_e32 v36, v36
	s_nop 1
	s_nop 1
	s_waitcnt lgkmcnt(0)
	v_mul_f32_e32 v33, 0x3fb8aa3b, v251
	v_mul_f32_e32 v16, v61, v33
	v_exp_f32_e32 v32, v16
	v_rcp_f32_e32 v16, v60
	v_mul_f32_e32 v17, v63, v33
	v_fma_f32 v18, -v32, v32, 1.0
	v_sqrt_f32_e32 v18, v18
	v_mul_f32_e32 v16, v16, v33
	v_exp_f32_e32 v50, v17
	v_mul_f32_e32 v18, v62, v18
	v_mul_f32_e32 v18, v0, v18
	v_exp_f32_e32 v0, v16
	v_add_f32_e32 v16, 1.0, v59
	v_rcp_f32_e32 v16, v16
	v_fma_f32 v19, -v50, v50, 1.0
	v_sqrt_f32_e32 v19, v19
	v_rcp_f32_e32 v17, v34
	v_mul_f32_e32 v16, v16, v33
	v_exp_f32_e32 v51, v16
	v_fmamk_f32 v16, v20, 0xbfb8aa3b, v49
	v_mul_f32_e32 v34, v64, v19
	v_fmamk_f32 v19, v35, 0xbfb8aa3b, v48
	v_exp_f32_e32 v16, v16
	v_exp_f32_e32 v19, v19
	v_fma_f32 v20, -v51, v51, 1.0
	v_add_f32_e32 v16, 1.0, v16
	v_rcp_f32_e32 v16, v16
	v_add_f32_e32 v19, 1.0, v19
	v_rcp_f32_e32 v19, v19
	v_sqrt_f32_e32 v20, v20
	v_mul_f32_e32 v16, v16, v33
	v_fma_f32 v35, -v0, v0, 1.0
	v_mul_f32_e32 v52, v19, v20
	v_exp_f32_e32 v20, v16
	v_fmamk_f32 v16, v21, 0xbfb8aa3b, v49
	v_exp_f32_e32 v16, v16
	v_sqrt_f32_e32 v35, v35
	v_fma_f32 v19, -v20, v20, 1.0
	v_fmamk_f32 v21, v37, 0xbfb8aa3b, v48
	v_add_f32_e32 v16, 1.0, v16
	v_rcp_f32_e32 v16, v16
	v_mul_f32_e32 v35, v17, v35
	v_add_f32_e32 v17, 1.0, v36
	v_rcp_f32_e32 v17, v17
	v_mul_f32_e32 v16, v16, v33
	v_exp_f32_e32 v36, v16
	v_fmamk_f32 v16, v22, 0xbfb8aa3b, v49
	v_exp_f32_e32 v16, v16
	v_sqrt_f32_e32 v19, v19
	v_exp_f32_e32 v21, v21
	v_add_f32_e32 v16, 1.0, v16
	v_rcp_f32_e32 v16, v16
	v_mul_f32_e32 v17, v17, v19
	v_mul_f32_e32 v19, v4, v17
	v_add_f32_e32 v4, 1.0, v21
	v_fmamk_f32 v21, v38, 0xbfb8aa3b, v48
	v_mul_f32_e32 v16, v16, v33
	v_fma_f32 v17, -v36, v36, 1.0
	v_exp_f32_e32 v21, v21
	v_rcp_f32_e32 v4, v4
	v_sqrt_f32_e32 v17, v17
	v_exp_f32_e32 v37, v16
	v_add_f32_e32 v16, 1.0, v21
	v_fmamk_f32 v21, v23, 0xbfb8aa3b, v49
	v_mul_f32_e32 v4, v4, v17
	v_fma_f32 v17, -v37, v37, 1.0
	v_rcp_f32_e32 v16, v16
	v_sqrt_f32_e32 v17, v17
	v_exp_f32_e32 v21, v21
	v_fmamk_f32 v22, v39, 0xbfb8aa3b, v48
	v_mul_f32_e32 v23, v16, v17
	v_add_f32_e32 v16, 1.0, v21
	v_rcp_f32_e32 v16, v16
	v_fmamk_f32 v21, v24, 0xbfb8aa3b, v49
	v_exp_f32_e32 v21, v21
	v_mul_f32_e32 v16, v16, v33
	v_exp_f32_e32 v24, v16
	v_add_f32_e32 v16, 1.0, v21
	v_rcp_f32_e32 v16, v16
	v_exp_f32_e32 v22, v22
	v_fmamk_f32 v21, v40, 0xbfb8aa3b, v48
	v_mul_f32_e32 v16, v16, v33
	v_add_f32_e32 v17, 1.0, v22
	v_fma_f32 v22, -v24, v24, 1.0
	v_sqrt_f32_e32 v38, v22
	v_exp_f32_e32 v22, v16
	v_fmamk_f32 v16, v25, 0xbfb8aa3b, v49
	v_exp_f32_e32 v16, v16
	v_exp_f32_e32 v21, v21
	v_fmamk_f32 v39, v41, 0xbfb8aa3b, v48
	v_fma_f32 v25, -v22, v22, 1.0
	v_add_f32_e32 v16, 1.0, v16
	v_rcp_f32_e32 v16, v16
	v_add_f32_e32 v21, 1.0, v21
	v_rcp_f32_e32 v17, v17
	v_rcp_f32_e32 v21, v21
	v_sqrt_f32_e32 v25, v25
	v_exp_f32_e32 v39, v39
	v_mul_f32_e32 v16, v16, v33
	v_mul_f32_e32 v38, v17, v38
	v_mul_f32_e32 v17, v21, v25
	v_add_f32_e32 v21, 1.0, v39
	v_exp_f32_e32 v39, v16
	v_fmamk_f32 v16, v26, 0xbfb8aa3b, v49
	v_exp_f32_e32 v16, v16
	v_rcp_f32_e32 v25, v21
	v_fma_f32 v21, -v39, v39, 1.0
	v_sqrt_f32_e32 v26, v21
	v_add_f32_e32 v16, 1.0, v16
	v_fmamk_f32 v21, v42, 0xbfb8aa3b, v48
	v_rcp_f32_e32 v16, v16
	v_exp_f32_e32 v40, v21
	v_mul_f32_e32 v21, v8, v17
	v_mul_f32_e32 v16, v16, v33
	v_add_f32_e32 v17, 1.0, v40
	v_exp_f32_e32 v40, v16
	v_fmamk_f32 v16, v27, 0xbfb8aa3b, v49
	v_exp_f32_e32 v16, v16
	v_mul_f32_e32 v8, v25, v26
	v_fma_f32 v25, -v40, v40, 1.0
	v_fmamk_f32 v26, v43, 0xbfb8aa3b, v48
	v_add_f32_e32 v16, 1.0, v16
	v_rcp_f32_e32 v16, v16
	v_rcp_f32_e32 v17, v17
	v_sqrt_f32_e32 v25, v25
	v_mul_f32_e32 v16, v16, v33
	v_exp_f32_e32 v26, v26
	v_exp_f32_e32 v41, v16
	v_mul_f32_e32 v53, v17, v25
	v_fmamk_f32 v25, v28, 0xbfb8aa3b, v49
	v_add_f32_e32 v16, 1.0, v26
	v_fmamk_f32 v26, v44, 0xbfb8aa3b, v48
	v_fma_f32 v17, -v41, v41, 1.0
	v_exp_f32_e32 v25, v25
	v_rcp_f32_e32 v16, v16
	v_sqrt_f32_e32 v17, v17
	v_exp_f32_e32 v26, v26
	v_add_f32_e32 v25, 1.0, v25
	v_rcp_f32_e32 v25, v25
	v_mul_f32_e32 v54, v16, v17
	v_add_f32_e32 v16, 1.0, v26
	v_fmamk_f32 v26, v45, 0xbfb8aa3b, v48
	v_exp_f32_e32 v26, v26
	v_rcp_f32_e32 v17, v16
	v_mul_f32_e32 v16, v25, v33
	v_fmamk_f32 v25, v29, 0xbfb8aa3b, v49
	v_exp_f32_e32 v25, v25
	v_add_f32_e32 v26, 1.0, v26
	v_rcp_f32_e32 v42, v26
	v_fmamk_f32 v26, v30, 0xbfb8aa3b, v49
	v_exp_f32_e32 v26, v26
	v_add_f32_e32 v25, 1.0, v25
	v_rcp_f32_e32 v25, v25
	v_fmamk_f32 v27, v46, 0xbfb8aa3b, v48
	v_exp_f32_e32 v27, v27
	v_add_f32_e32 v26, 1.0, v26
	v_rcp_f32_e32 v26, v26
	v_mul_f32_e32 v25, v25, v33
	v_exp_f32_e32 v43, v25
	v_add_f32_e32 v25, 1.0, v27
	v_rcp_f32_e32 v44, v25
	v_mul_f32_e32 v25, v26, v33
	v_fmamk_f32 v26, v31, 0xbfb8aa3b, v49
	v_exp_f32_e32 v26, v26
	v_fmamk_f32 v27, v47, 0xbfb8aa3b, v48
	v_exp_f32_e32 v27, v27
	v_add_f32_e32 v26, 1.0, v26
	v_rcp_f32_e32 v26, v26
	v_exp_f32_e32 v16, v16
	v_fmac_f32_e32 v18, 0, v32
	v_exp_f32_e32 v45, v25
	v_add_f32_e32 v25, 1.0, v27
	v_mul_f32_e32 v31, v50, v18
	v_rcp_f32_e32 v46, v25
	v_mul_f32_e32 v25, v26, v33
	v_fmac_f32_e32 v31, v1, v34
	v_mul_f32_e32 v33, v32, v50
	v_fmac_f32_e32 v19, 0, v20
	v_mul_f32_e32 v30, v0, v31
	v_mul_f32_e32 v34, v0, v33
	v_mul_f32_e32 v28, v36, v19
	v_fma_f32 v0, -v16, v16, 1.0
	v_fmac_f32_e32 v28, v5, v4
	v_sqrt_f32_e32 v1, v0
	v_mul_f32_e32 v27, v37, v28
	v_fmac_f32_e32 v30, v2, v35
	v_fmac_f32_e32 v27, v6, v23
	v_fma_f32 v2, -v43, v43, 1.0
	v_mul_f32_e32 v26, v24, v27
	v_mov_b32_e32 v0, v89
	v_sqrt_f32_e32 v2, v2
	v_fmac_f32_e32 v26, v7, v38
	v_pk_mul_f32 v[6:7], v[16:17], v[0:1]
	v_mul_f32_e32 v29, v51, v30
	v_fmac_f32_e32 v6, v12, v7
	v_fmac_f32_e32 v29, v3, v52
	v_mov_b32_e32 v3, v6
	v_pk_mul_f32 v[4:5], v[42:43], v[2:3]
	v_fma_f32 v0, -v45, v45, 1.0
	v_exp_f32_e32 v47, v25
	v_fmac_f32_e32 v5, v13, v4
	v_sqrt_f32_e32 v4, v0
	v_fmac_f32_e32 v21, 0, v22
	v_mul_f32_e32 v25, v39, v21
	v_mul_f32_e32 v36, v20, v36
	v_fmac_f32_e32 v25, v9, v8
	v_pk_mul_f32 v[8:9], v[44:45], v[4:5]
	v_fma_f32 v0, -v47, v47, 1.0
	v_mul_f32_e32 v37, v37, v36
	v_fmac_f32_e32 v9, v14, v8
	v_sqrt_f32_e32 v8, v0
	ds_bpermute_b32 v0, v140, v29
	v_mul_f32_e32 v38, v24, v37
	v_mul_f32_e32 v24, v40, v25
	v_mul_f32_e32 v35, v51, v34
	v_fmac_f32_e32 v24, v10, v53
	v_mul_f32_e32 v23, v41, v24
	ds_bpermute_b32 v13, v140, v35
	v_fmac_f32_e32 v23, v11, v54
	v_pk_mul_f32 v[10:11], v[46:47], v[8:9]
	s_waitcnt lgkmcnt(1)
	v_cndmask_b32_e64 v14, v29, v0, s[0:1]
	v_fmac_f32_e32 v11, v15, v10
	v_cndmask_b32_e64 v10, v0, v29, s[0:1]
	ds_bpermute_b32 v0, v140, v38
	ds_bpermute_b32 v3, v140, v26
	v_mul_f32_e32 v39, v22, v39
	v_mul_f32_e32 v40, v40, v39
	s_waitcnt lgkmcnt(2)
	v_cndmask_b32_e64 v1, v13, v35, s[0:1]
	v_mul_f32_e32 v12, v41, v40
	v_mul_f32_e32 v7, v16, v43
	v_cndmask_b32_e64 v2, v35, v13, s[0:1]
	v_fmac_f32_e32 v10, 0, v1
	v_mul_f32_e32 v4, v45, v7
	v_mul_f32_e32 v15, v35, v13
	v_fmac_f32_e32 v14, v2, v10
	s_waitcnt lgkmcnt(1)
	v_cndmask_b32_e64 v1, v0, v38, s[0:1]
	s_waitcnt lgkmcnt(0)
	v_cndmask_b32_e64 v17, v3, v26, s[0:1]
	v_cndmask_b32_e64 v41, v26, v3, s[0:1]
	ds_bpermute_b32 v2, v140, v12
	ds_bpermute_b32 v3, v140, v23
	v_mul_f32_e32 v8, v47, v4
	v_cndmask_b32_e64 v0, v38, v0, s[0:1]
	v_mul_f32_e32 v42, v15, v1
	v_fmac_f32_e32 v17, v1, v14
	v_mul_f32_e32 v43, v0, v42
	v_fmac_f32_e32 v41, v0, v17
	ds_bpermute_b32 v1, v140, v8
	ds_bpermute_b32 v0, v140, v11
	s_waitcnt lgkmcnt(3)
	v_cndmask_b32_e64 v47, v2, v12, s[0:1]
	s_waitcnt lgkmcnt(2)
	v_cndmask_b32_e64 v44, v3, v23, s[0:1]
	v_cndmask_b32_e64 v2, v12, v2, s[0:1]
	v_cndmask_b32_e64 v45, v23, v3, s[0:1]
	v_mul_f32_e32 v46, v47, v43
	v_fmac_f32_e32 v44, v47, v41
	v_mul_f32_e32 v47, v2, v46
	v_fmac_f32_e32 v45, v2, v44
	s_waitcnt lgkmcnt(1)
	v_cndmask_b32_e64 v2, v1, v8, s[0:1]
	s_waitcnt lgkmcnt(0)
	v_cndmask_b32_e64 v48, v0, v11, s[0:1]
	v_mul_f32_e32 v49, v2, v47
	v_fmac_f32_e32 v48, v2, v45
	s_and_saveexec_b64 s[8:9], s[0:1]
	v_mul_f32_e32 v3, v48, v1
	v_mul_f32_e32 v2, v49, v1
	v_add_f32_e32 v3, v3, v0
	ds_write_b64 v139, v[2:3] offset:6144
	s_or_b64 exec, exec, s[8:9]
	s_and_b64 vcc, exec, s[6:7]
	s_waitcnt lgkmcnt(0)
	s_barrier
	s_cbranch_vccnz .LBB0_366
	s_cmp_lt_u32 s62, 8
	s_cbranch_scc1 .LBB0_367
	s_and_b32 s6, s62, 0x7ffffff8
	v_add3_u32 v50, v141, v138, s88
	v_mov_b32_e32 v0, 1.0
	v_mov_b32_e32 v3, 0
	s_mov_b32 s7, 0
